# removed redundant back-to-back s_setprio 0/1 pairs between MFMA groups in the 16 GEMM K-loops
# speedup vs baseline: 1.0003x; 1.0003x over previous
.LBB0_42:
	s_add_i32 s53, s2, 2
	s_add_u32 s3, s0, 0xfff00080
	s_addc_u32 s20, s1, -1
	s_add_i32 s50, 0, 0x10000
	s_cmp_eq_u32 s48, s2
	s_cselect_b32 s21, s42, s20
	s_cselect_b32 s20, s43, s3
	s_cselect_b32 s3, s44, s47
	s_cselect_b32 s2, s45, s46
	s_add_i32 s51, 0, 0x14000
	v_add_u32_e32 v146, s50, v215
	v_add_u32_e32 v162, s51, v215
	ds_read_b128 v[128:131], v146
	ds_read_b128 v[132:135], v146 offset:1024
	ds_read_b128 v[136:139], v146 offset:2048
	ds_read_b128 v[146:149], v146 offset:3072
	ds_read_b128 v[150:153], v162
	ds_read_b128 v[154:157], v162 offset:1024
	ds_read_b128 v[158:161], v162 offset:2048
	ds_read_b128 v[162:165], v162 offset:3072
	v_lshl_add_u64 v[166:167], s[0:1], 0, v[142:143]
	s_add_i32 m0, s27, 0xc000
	ds_read_b128 v[186:189], v216
	ds_read_b128 v[190:193], v216 offset:1024
	ds_read_b128 v[194:197], v216 offset:2048
	ds_read_b128 v[198:201], v216 offset:3072
	ds_read_b128 v[202:205], v216 offset:4096
	ds_read_b128 v[206:209], v216 offset:5120
	ds_read_b128 v[210:213], v216 offset:6144
	ds_read_b128 v[218:221], v216 offset:7168
	global_load_lds_dwordx4 v[166:167], off
	v_lshl_add_u64 v[166:167], s[0:1], 0, v[144:145]
	s_add_i32 m0, s27, 0xe000
	s_nop 0
	global_load_lds_dwordx4 v[166:167], off
	s_waitcnt vmcnt(8)
	s_waitcnt lgkmcnt(0)
	s_barrier
	s_setprio 1
	s_waitcnt lgkmcnt(0)
	v_mfma_f32_16x16x32_bf16 v[124:127], v[128:131], v[186:189], v[124:127]
	v_mfma_f32_16x16x32_bf16 v[120:123], v[136:139], v[186:189], v[120:123]
	v_mfma_f32_16x16x32_bf16 v[108:111], v[128:131], v[194:197], v[108:111]
	v_mfma_f32_16x16x32_bf16 v[104:107], v[136:139], v[194:197], v[104:107]
	v_mfma_f32_16x16x32_bf16 v[92:95], v[128:131], v[202:205], v[92:95]
	v_mfma_f32_16x16x32_bf16 v[88:91], v[136:139], v[202:205], v[88:91]
	v_mfma_f32_16x16x32_bf16 v[76:79], v[128:131], v[210:213], v[76:79]
	v_mfma_f32_16x16x32_bf16 v[72:75], v[136:139], v[210:213], v[72:75]
	v_mfma_f32_16x16x32_bf16 v[124:127], v[132:135], v[190:193], v[124:127]
	v_mfma_f32_16x16x32_bf16 v[120:123], v[146:149], v[190:193], v[120:123]
	v_mfma_f32_16x16x32_bf16 v[108:111], v[132:135], v[198:201], v[108:111]
	v_mfma_f32_16x16x32_bf16 v[104:107], v[146:149], v[198:201], v[104:107]
	v_mfma_f32_16x16x32_bf16 v[92:95], v[132:135], v[206:209], v[92:95]
	v_mfma_f32_16x16x32_bf16 v[88:91], v[146:149], v[206:209], v[88:91]
	v_mfma_f32_16x16x32_bf16 v[76:79], v[132:135], v[218:221], v[76:79]
	v_mfma_f32_16x16x32_bf16 v[72:75], v[146:149], v[218:221], v[72:75]
	v_mfma_f32_16x16x32_bf16 v[116:119], v[150:153], v[186:189], v[116:119]
	v_mfma_f32_16x16x32_bf16 v[112:115], v[158:161], v[186:189], v[112:115]
	v_mfma_f32_16x16x32_bf16 v[100:103], v[150:153], v[194:197], v[100:103]
	v_mfma_f32_16x16x32_bf16 v[96:99], v[158:161], v[194:197], v[96:99]
	v_mfma_f32_16x16x32_bf16 v[84:87], v[150:153], v[202:205], v[84:87]
	v_mfma_f32_16x16x32_bf16 v[80:83], v[158:161], v[202:205], v[80:83]
	v_mfma_f32_16x16x32_bf16 v[68:71], v[150:153], v[210:213], v[68:71]
	v_mfma_f32_16x16x32_bf16 v[64:67], v[158:161], v[210:213], v[64:67]
	v_mfma_f32_16x16x32_bf16 v[116:119], v[154:157], v[190:193], v[116:119]
	v_mfma_f32_16x16x32_bf16 v[112:115], v[162:165], v[190:193], v[112:115]
	v_mfma_f32_16x16x32_bf16 v[100:103], v[154:157], v[198:201], v[100:103]
	v_mfma_f32_16x16x32_bf16 v[96:99], v[162:165], v[198:201], v[96:99]
	v_mfma_f32_16x16x32_bf16 v[84:87], v[154:157], v[206:209], v[84:87]
	v_mfma_f32_16x16x32_bf16 v[80:83], v[162:165], v[206:209], v[80:83]
	v_mfma_f32_16x16x32_bf16 v[68:71], v[154:157], v[218:221], v[68:71]
	v_mfma_f32_16x16x32_bf16 v[64:67], v[162:165], v[218:221], v[64:67]
	s_setprio 0
	s_barrier
	s_add_i32 s50, s50, s26
	v_lshl_add_u64 v[166:167], s[2:3], 0, v[168:169]
	s_mov_b32 m0, s50
	ds_read_b128 v[186:189], v216 offset:16384
	ds_read_b128 v[190:193], v216 offset:17408
	ds_read_b128 v[194:197], v216 offset:18432
	ds_read_b128 v[198:201], v216 offset:19456
	ds_read_b128 v[202:205], v216 offset:20480
	ds_read_b128 v[206:209], v216 offset:21504
	ds_read_b128 v[210:213], v216 offset:22528
	ds_read_b128 v[218:221], v216 offset:23552
	global_load_lds_dwordx4 v[166:167], off
	s_add_i32 m0, s50, 0x2000
	s_add_u32 s68, s2, 0x100000
	v_lshl_add_u64 v[222:223], s[2:3], 0, v[140:141]
	s_addc_u32 s69, s3, 0
	s_add_i32 s50, s51, s26
	global_load_lds_dwordx4 v[222:223], off
	v_lshl_add_u64 v[234:235], s[68:69], 0, v[168:169]
	s_mov_b32 m0, s50
	v_lshl_add_u64 v[236:237], s[20:21], 0, v[140:141]
	global_load_lds_dwordx4 v[234:235], off
	v_lshl_add_u64 v[234:235], s[68:69], 0, v[140:141]
	s_add_i32 m0, s50, 0x2000
	s_nop 0
	global_load_lds_dwordx4 v[234:235], off
	v_lshl_add_u64 v[234:235], s[20:21], 0, v[168:169]
	s_mov_b32 m0, s27
	s_nop 0
	global_load_lds_dwordx4 v[234:235], off
	s_mov_b32 m0, s34
	s_nop 0
	global_load_lds_dwordx4 v[236:237], off
	s_waitcnt vmcnt(8)
	s_waitcnt lgkmcnt(0)
	s_barrier
	s_setprio 1
	s_waitcnt lgkmcnt(0)
	v_mfma_f32_16x16x32_bf16 v[60:63], v[128:131], v[186:189], v[60:63]
	v_mfma_f32_16x16x32_bf16 v[56:59], v[136:139], v[186:189], v[56:59]
	v_mfma_f32_16x16x32_bf16 v[44:47], v[128:131], v[194:197], v[44:47]
	v_mfma_f32_16x16x32_bf16 v[40:43], v[136:139], v[194:197], v[40:43]
	v_mfma_f32_16x16x32_bf16 v[28:31], v[128:131], v[202:205], v[28:31]
	v_mfma_f32_16x16x32_bf16 v[24:27], v[136:139], v[202:205], v[24:27]
	v_mfma_f32_16x16x32_bf16 v[12:15], v[128:131], v[210:213], v[12:15]
	v_mfma_f32_16x16x32_bf16 v[8:11], v[136:139], v[210:213], v[8:11]
	v_mfma_f32_16x16x32_bf16 v[60:63], v[132:135], v[190:193], v[60:63]
	v_mfma_f32_16x16x32_bf16 v[56:59], v[146:149], v[190:193], v[56:59]
	v_mfma_f32_16x16x32_bf16 v[44:47], v[132:135], v[198:201], v[44:47]
	v_mfma_f32_16x16x32_bf16 v[40:43], v[146:149], v[198:201], v[40:43]
	v_mfma_f32_16x16x32_bf16 v[28:31], v[132:135], v[206:209], v[28:31]
	v_mfma_f32_16x16x32_bf16 v[24:27], v[146:149], v[206:209], v[24:27]
	v_mfma_f32_16x16x32_bf16 v[12:15], v[132:135], v[218:221], v[12:15]
	v_mfma_f32_16x16x32_bf16 v[8:11], v[146:149], v[218:221], v[8:11]
	v_mfma_f32_16x16x32_bf16 v[52:55], v[150:153], v[186:189], v[52:55]
	v_mfma_f32_16x16x32_bf16 v[48:51], v[158:161], v[186:189], v[48:51]
	v_mfma_f32_16x16x32_bf16 v[36:39], v[150:153], v[194:197], v[36:39]
	v_mfma_f32_16x16x32_bf16 v[32:35], v[158:161], v[194:197], v[32:35]
	v_mfma_f32_16x16x32_bf16 v[20:23], v[150:153], v[202:205], v[20:23]
	v_mfma_f32_16x16x32_bf16 v[16:19], v[158:161], v[202:205], v[16:19]
	v_mfma_f32_16x16x32_bf16 v[4:7], v[150:153], v[210:213], v[4:7]
	v_mfma_f32_16x16x32_bf16 v[0:3], v[158:161], v[210:213], v[0:3]
	v_mfma_f32_16x16x32_bf16 v[52:55], v[154:157], v[190:193], v[52:55]
	v_mfma_f32_16x16x32_bf16 v[48:51], v[162:165], v[190:193], v[48:51]
	v_mfma_f32_16x16x32_bf16 v[36:39], v[154:157], v[198:201], v[36:39]
	v_mfma_f32_16x16x32_bf16 v[32:35], v[162:165], v[198:201], v[32:35]
	v_mfma_f32_16x16x32_bf16 v[20:23], v[154:157], v[206:209], v[20:23]
	v_mfma_f32_16x16x32_bf16 v[16:19], v[162:165], v[206:209], v[16:19]
	v_mfma_f32_16x16x32_bf16 v[4:7], v[154:157], v[218:221], v[4:7]
	v_mfma_f32_16x16x32_bf16 v[0:3], v[162:165], v[218:221], v[0:3]
	s_setprio 0
	s_barrier
	s_add_i32 s50, 0, 0x18000
	s_add_i32 s51, 0, 0x1c000
	v_add_u32_e32 v146, s50, v215
	v_add_u32_e32 v162, s51, v215
	ds_read_b128 v[128:131], v146
	ds_read_b128 v[132:135], v146 offset:1024
	ds_read_b128 v[136:139], v146 offset:2048
	ds_read_b128 v[146:149], v146 offset:3072
	ds_read_b128 v[150:153], v162
	ds_read_b128 v[154:157], v162 offset:1024
	ds_read_b128 v[158:161], v162 offset:2048
	ds_read_b128 v[162:165], v162 offset:3072
	s_add_u32 s20, s20, 0x100000
	s_addc_u32 s21, s21, 0
	s_mov_b32 m0, s41
	v_lshl_add_u64 v[242:243], s[20:21], 0, v[168:169]
	ds_read_b128 v[186:189], v216 offset:32768
	ds_read_b128 v[190:193], v216 offset:33792
	ds_read_b128 v[194:197], v216 offset:34816
	ds_read_b128 v[198:201], v216 offset:35840
	ds_read_b128 v[202:205], v216 offset:36864
	ds_read_b128 v[206:209], v216 offset:37888
	ds_read_b128 v[210:213], v216 offset:38912
	ds_read_b128 v[218:221], v216 offset:39936
	global_load_lds_dwordx4 v[242:243], off
	v_lshl_add_u64 v[242:243], s[20:21], 0, v[140:141]
	s_mov_b32 m0, s70
	s_nop 0
	global_load_lds_dwordx4 v[242:243], off
	s_waitcnt vmcnt(8)
	s_waitcnt lgkmcnt(0)
	s_barrier
	s_setprio 1
	s_waitcnt lgkmcnt(0)
	v_mfma_f32_16x16x32_bf16 v[124:127], v[128:131], v[186:189], v[124:127]
	v_mfma_f32_16x16x32_bf16 v[120:123], v[136:139], v[186:189], v[120:123]
	v_mfma_f32_16x16x32_bf16 v[108:111], v[128:131], v[194:197], v[108:111]
	v_mfma_f32_16x16x32_bf16 v[104:107], v[136:139], v[194:197], v[104:107]
	v_mfma_f32_16x16x32_bf16 v[92:95], v[128:131], v[202:205], v[92:95]
	v_mfma_f32_16x16x32_bf16 v[88:91], v[136:139], v[202:205], v[88:91]
	v_mfma_f32_16x16x32_bf16 v[76:79], v[128:131], v[210:213], v[76:79]
	v_mfma_f32_16x16x32_bf16 v[72:75], v[136:139], v[210:213], v[72:75]
	v_mfma_f32_16x16x32_bf16 v[124:127], v[132:135], v[190:193], v[124:127]
	v_mfma_f32_16x16x32_bf16 v[120:123], v[146:149], v[190:193], v[120:123]
	v_mfma_f32_16x16x32_bf16 v[108:111], v[132:135], v[198:201], v[108:111]
	v_mfma_f32_16x16x32_bf16 v[104:107], v[146:149], v[198:201], v[104:107]
	v_mfma_f32_16x16x32_bf16 v[92:95], v[132:135], v[206:209], v[92:95]
	v_mfma_f32_16x16x32_bf16 v[88:91], v[146:149], v[206:209], v[88:91]
	v_mfma_f32_16x16x32_bf16 v[76:79], v[132:135], v[218:221], v[76:79]
	v_mfma_f32_16x16x32_bf16 v[72:75], v[146:149], v[218:221], v[72:75]
	v_mfma_f32_16x16x32_bf16 v[116:119], v[150:153], v[186:189], v[116:119]
	v_mfma_f32_16x16x32_bf16 v[112:115], v[158:161], v[186:189], v[112:115]
	v_mfma_f32_16x16x32_bf16 v[100:103], v[150:153], v[194:197], v[100:103]
	v_mfma_f32_16x16x32_bf16 v[96:99], v[158:161], v[194:197], v[96:99]
	v_mfma_f32_16x16x32_bf16 v[84:87], v[150:153], v[202:205], v[84:87]
	v_mfma_f32_16x16x32_bf16 v[80:83], v[158:161], v[202:205], v[80:83]
	v_mfma_f32_16x16x32_bf16 v[68:71], v[150:153], v[210:213], v[68:71]
	v_mfma_f32_16x16x32_bf16 v[64:67], v[158:161], v[210:213], v[64:67]
	v_mfma_f32_16x16x32_bf16 v[116:119], v[154:157], v[190:193], v[116:119]
	v_mfma_f32_16x16x32_bf16 v[112:115], v[162:165], v[190:193], v[112:115]
	v_mfma_f32_16x16x32_bf16 v[100:103], v[154:157], v[198:201], v[100:103]
	v_mfma_f32_16x16x32_bf16 v[96:99], v[162:165], v[198:201], v[96:99]
	v_mfma_f32_16x16x32_bf16 v[84:87], v[154:157], v[206:209], v[84:87]
	v_mfma_f32_16x16x32_bf16 v[80:83], v[162:165], v[206:209], v[80:83]
	v_mfma_f32_16x16x32_bf16 v[68:71], v[154:157], v[218:221], v[68:71]
	v_mfma_f32_16x16x32_bf16 v[64:67], v[162:165], v[218:221], v[64:67]
	s_setprio 0
	s_barrier
	s_add_i32 s20, s50, s26
	v_lshl_add_u64 v[166:167], v[166:167], 0, s[28:29]
	s_mov_b32 m0, s20
	ds_read_b128 v[186:189], v216 offset:49152
	ds_read_b128 v[190:193], v216 offset:50176
	ds_read_b128 v[194:197], v216 offset:51200
	ds_read_b128 v[198:201], v216 offset:52224
	ds_read_b128 v[202:205], v216 offset:53248
	ds_read_b128 v[206:209], v216 offset:54272
	ds_read_b128 v[210:213], v216 offset:55296
	ds_read_b128 v[218:221], v216 offset:56320
	global_load_lds_dwordx4 v[166:167], off
	s_add_i32 m0, s20, 0x2000
	s_add_u32 s2, s2, 0x100080
	v_lshl_add_u64 v[166:167], v[222:223], 0, s[28:29]
	s_addc_u32 s3, s3, 0
	s_add_i32 s20, s51, s26
	global_load_lds_dwordx4 v[166:167], off
	v_lshl_add_u64 v[166:167], s[2:3], 0, v[168:169]
	s_mov_b32 m0, s20
	s_nop 0
	global_load_lds_dwordx4 v[166:167], off
	v_lshl_add_u64 v[166:167], s[2:3], 0, v[140:141]
	s_add_i32 m0, s20, 0x2000
	s_nop 0
	global_load_lds_dwordx4 v[166:167], off
	v_lshl_add_u64 v[166:167], v[234:235], 0, s[28:29]
	s_mov_b32 m0, s76
	s_nop 0
	global_load_lds_dwordx4 v[166:167], off
	v_lshl_add_u64 v[166:167], v[236:237], 0, s[28:29]
	s_mov_b32 m0, s77
	s_nop 0
	global_load_lds_dwordx4 v[166:167], off
	s_waitcnt vmcnt(8)
	s_waitcnt lgkmcnt(0)
	s_barrier
	s_setprio 1
	s_waitcnt lgkmcnt(0)
	v_mfma_f32_16x16x32_bf16 v[60:63], v[128:131], v[186:189], v[60:63]
	v_mfma_f32_16x16x32_bf16 v[56:59], v[136:139], v[186:189], v[56:59]
	v_mfma_f32_16x16x32_bf16 v[44:47], v[128:131], v[194:197], v[44:47]
	v_mfma_f32_16x16x32_bf16 v[40:43], v[136:139], v[194:197], v[40:43]
	v_mfma_f32_16x16x32_bf16 v[28:31], v[128:131], v[202:205], v[28:31]
	v_mfma_f32_16x16x32_bf16 v[24:27], v[136:139], v[202:205], v[24:27]
	v_mfma_f32_16x16x32_bf16 v[12:15], v[128:131], v[210:213], v[12:15]
	v_mfma_f32_16x16x32_bf16 v[8:11], v[136:139], v[210:213], v[8:11]
	v_mfma_f32_16x16x32_bf16 v[60:63], v[132:135], v[190:193], v[60:63]
	v_mfma_f32_16x16x32_bf16 v[56:59], v[146:149], v[190:193], v[56:59]
	v_mfma_f32_16x16x32_bf16 v[44:47], v[132:135], v[198:201], v[44:47]
	v_mfma_f32_16x16x32_bf16 v[40:43], v[146:149], v[198:201], v[40:43]
	v_mfma_f32_16x16x32_bf16 v[28:31], v[132:135], v[206:209], v[28:31]
	v_mfma_f32_16x16x32_bf16 v[24:27], v[146:149], v[206:209], v[24:27]
	v_mfma_f32_16x16x32_bf16 v[12:15], v[132:135], v[218:221], v[12:15]
	v_mfma_f32_16x16x32_bf16 v[8:11], v[146:149], v[218:221], v[8:11]
	v_mfma_f32_16x16x32_bf16 v[52:55], v[150:153], v[186:189], v[52:55]
	v_mfma_f32_16x16x32_bf16 v[48:51], v[158:161], v[186:189], v[48:51]
	v_mfma_f32_16x16x32_bf16 v[36:39], v[150:153], v[194:197], v[36:39]
	v_mfma_f32_16x16x32_bf16 v[32:35], v[158:161], v[194:197], v[32:35]
	v_mfma_f32_16x16x32_bf16 v[20:23], v[150:153], v[202:205], v[20:23]
	v_mfma_f32_16x16x32_bf16 v[16:19], v[158:161], v[202:205], v[16:19]
	v_mfma_f32_16x16x32_bf16 v[4:7], v[150:153], v[210:213], v[4:7]
	v_mfma_f32_16x16x32_bf16 v[0:3], v[158:161], v[210:213], v[0:3]
	v_mfma_f32_16x16x32_bf16 v[52:55], v[154:157], v[190:193], v[52:55]
	v_mfma_f32_16x16x32_bf16 v[48:51], v[162:165], v[190:193], v[48:51]
	v_mfma_f32_16x16x32_bf16 v[36:39], v[154:157], v[198:201], v[36:39]
	v_mfma_f32_16x16x32_bf16 v[32:35], v[162:165], v[198:201], v[32:35]
	v_mfma_f32_16x16x32_bf16 v[20:23], v[154:157], v[206:209], v[20:23]
	v_mfma_f32_16x16x32_bf16 v[16:19], v[162:165], v[206:209], v[16:19]
	v_mfma_f32_16x16x32_bf16 v[4:7], v[154:157], v[218:221], v[4:7]
	v_mfma_f32_16x16x32_bf16 v[0:3], v[162:165], v[218:221], v[0:3]
	s_setprio 0
	s_barrier
	s_add_u32 s0, s0, 0x100
	s_addc_u32 s1, s1, 0
	s_add_u32 s46, s46, 0x100
	s_addc_u32 s47, s47, 0
	s_cmp_ge_i32 s53, s73
	s_mov_b32 s2, s53
	s_cbranch_scc0 .LBB0_42

.LBB0_90:
	s_add_i32 s45, s2, 2
	s_add_u32 s3, s0, 0xfff00080
	s_addc_u32 s20, s1, -1
	s_add_i32 s46, 0, 0x10000
	s_cmp_eq_u32 s74, s2
	s_cselect_b32 s21, s22, s20
	s_cselect_b32 s20, s23, s3
	s_cselect_b32 s3, s34, s44
	s_cselect_b32 s2, s42, s43
	s_add_i32 s50, 0, 0x14000
	v_add_u32_e32 v146, s46, v219
	v_add_u32_e32 v162, s50, v219
	ds_read_b128 v[128:131], v146
	ds_read_b128 v[132:135], v146 offset:1024
	ds_read_b128 v[142:145], v146 offset:2048
	ds_read_b128 v[146:149], v146 offset:3072
	ds_read_b128 v[150:153], v162
	ds_read_b128 v[154:157], v162 offset:1024
	ds_read_b128 v[158:161], v162 offset:2048
	ds_read_b128 v[162:165], v162 offset:3072
	v_lshl_add_u64 v[166:167], s[0:1], 0, v[138:139]
	s_add_i32 m0, s27, 0xc000
	ds_read_b128 v[186:189], v220
	ds_read_b128 v[190:193], v220 offset:1024
	ds_read_b128 v[194:197], v220 offset:2048
	ds_read_b128 v[198:201], v220 offset:3072
	ds_read_b128 v[202:205], v220 offset:4096
	ds_read_b128 v[206:209], v220 offset:5120
	ds_read_b128 v[210:213], v220 offset:6144
	ds_read_b128 v[214:217], v220 offset:7168
	global_load_lds_dwordx4 v[166:167], off
	v_lshl_add_u64 v[166:167], s[0:1], 0, v[140:141]
	s_add_i32 m0, s27, 0xe000
	s_nop 0
	global_load_lds_dwordx4 v[166:167], off
	s_waitcnt vmcnt(8)
	s_waitcnt lgkmcnt(0)
	s_barrier
	s_setprio 1
	s_waitcnt lgkmcnt(0)
	v_mfma_f32_16x16x32_bf16 v[124:127], v[128:131], v[186:189], v[124:127]
	v_mfma_f32_16x16x32_bf16 v[120:123], v[142:145], v[186:189], v[120:123]
	v_mfma_f32_16x16x32_bf16 v[108:111], v[128:131], v[194:197], v[108:111]
	v_mfma_f32_16x16x32_bf16 v[104:107], v[142:145], v[194:197], v[104:107]
	v_mfma_f32_16x16x32_bf16 v[92:95], v[128:131], v[202:205], v[92:95]
	v_mfma_f32_16x16x32_bf16 v[88:91], v[142:145], v[202:205], v[88:91]
	v_mfma_f32_16x16x32_bf16 v[76:79], v[128:131], v[210:213], v[76:79]
	v_mfma_f32_16x16x32_bf16 v[72:75], v[142:145], v[210:213], v[72:75]
	v_mfma_f32_16x16x32_bf16 v[124:127], v[132:135], v[190:193], v[124:127]
	v_mfma_f32_16x16x32_bf16 v[120:123], v[146:149], v[190:193], v[120:123]
	v_mfma_f32_16x16x32_bf16 v[108:111], v[132:135], v[198:201], v[108:111]
	v_mfma_f32_16x16x32_bf16 v[104:107], v[146:149], v[198:201], v[104:107]
	v_mfma_f32_16x16x32_bf16 v[92:95], v[132:135], v[206:209], v[92:95]
	v_mfma_f32_16x16x32_bf16 v[88:91], v[146:149], v[206:209], v[88:91]
	v_mfma_f32_16x16x32_bf16 v[76:79], v[132:135], v[214:217], v[76:79]
	v_mfma_f32_16x16x32_bf16 v[72:75], v[146:149], v[214:217], v[72:75]
	v_mfma_f32_16x16x32_bf16 v[116:119], v[150:153], v[186:189], v[116:119]
	v_mfma_f32_16x16x32_bf16 v[112:115], v[158:161], v[186:189], v[112:115]
	v_mfma_f32_16x16x32_bf16 v[100:103], v[150:153], v[194:197], v[100:103]
	v_mfma_f32_16x16x32_bf16 v[96:99], v[158:161], v[194:197], v[96:99]
	v_mfma_f32_16x16x32_bf16 v[84:87], v[150:153], v[202:205], v[84:87]
	v_mfma_f32_16x16x32_bf16 v[80:83], v[158:161], v[202:205], v[80:83]
	v_mfma_f32_16x16x32_bf16 v[68:71], v[150:153], v[210:213], v[68:71]
	v_mfma_f32_16x16x32_bf16 v[64:67], v[158:161], v[210:213], v[64:67]
	v_mfma_f32_16x16x32_bf16 v[116:119], v[154:157], v[190:193], v[116:119]
	v_mfma_f32_16x16x32_bf16 v[112:115], v[162:165], v[190:193], v[112:115]
	v_mfma_f32_16x16x32_bf16 v[100:103], v[154:157], v[198:201], v[100:103]
	v_mfma_f32_16x16x32_bf16 v[96:99], v[162:165], v[198:201], v[96:99]
	v_mfma_f32_16x16x32_bf16 v[84:87], v[154:157], v[206:209], v[84:87]
	v_mfma_f32_16x16x32_bf16 v[80:83], v[162:165], v[206:209], v[80:83]
	v_mfma_f32_16x16x32_bf16 v[68:71], v[154:157], v[214:217], v[68:71]
	v_mfma_f32_16x16x32_bf16 v[64:67], v[162:165], v[214:217], v[64:67]
	s_setprio 0
	s_barrier
	s_add_i32 s46, s46, s26
	v_lshl_add_u64 v[166:167], s[2:3], 0, v[168:169]
	s_mov_b32 m0, s46
	ds_read_b128 v[186:189], v220 offset:16384
	ds_read_b128 v[190:193], v220 offset:17408
	ds_read_b128 v[194:197], v220 offset:18432
	ds_read_b128 v[198:201], v220 offset:19456
	ds_read_b128 v[202:205], v220 offset:20480
	ds_read_b128 v[206:209], v220 offset:21504
	ds_read_b128 v[210:213], v220 offset:22528
	ds_read_b128 v[214:217], v220 offset:23552
	global_load_lds_dwordx4 v[166:167], off
	s_add_i32 m0, s46, 0x2000
	s_add_u32 s46, s2, 0x100000
	v_lshl_add_u64 v[222:223], s[2:3], 0, v[136:137]
	s_addc_u32 s47, s3, 0
	s_add_i32 s50, s50, s26
	global_load_lds_dwordx4 v[222:223], off
	v_lshl_add_u64 v[234:235], s[46:47], 0, v[168:169]
	s_mov_b32 m0, s50
	v_lshl_add_u64 v[236:237], s[20:21], 0, v[136:137]
	global_load_lds_dwordx4 v[234:235], off
	v_lshl_add_u64 v[234:235], s[46:47], 0, v[136:137]
	s_add_i32 m0, s50, 0x2000
	s_nop 0
	global_load_lds_dwordx4 v[234:235], off
	v_lshl_add_u64 v[234:235], s[20:21], 0, v[168:169]
	s_mov_b32 m0, s27
	s_nop 0
	global_load_lds_dwordx4 v[234:235], off
	s_mov_b32 m0, s41
	s_nop 0
	global_load_lds_dwordx4 v[236:237], off
	s_waitcnt vmcnt(8)
	s_waitcnt lgkmcnt(0)
	s_barrier
	s_setprio 1
	s_waitcnt lgkmcnt(0)
	v_mfma_f32_16x16x32_bf16 v[60:63], v[128:131], v[186:189], v[60:63]
	v_mfma_f32_16x16x32_bf16 v[56:59], v[142:145], v[186:189], v[56:59]
	v_mfma_f32_16x16x32_bf16 v[44:47], v[128:131], v[194:197], v[44:47]
	v_mfma_f32_16x16x32_bf16 v[40:43], v[142:145], v[194:197], v[40:43]
	v_mfma_f32_16x16x32_bf16 v[28:31], v[128:131], v[202:205], v[28:31]
	v_mfma_f32_16x16x32_bf16 v[24:27], v[142:145], v[202:205], v[24:27]
	v_mfma_f32_16x16x32_bf16 v[12:15], v[128:131], v[210:213], v[12:15]
	v_mfma_f32_16x16x32_bf16 v[8:11], v[142:145], v[210:213], v[8:11]
	v_mfma_f32_16x16x32_bf16 v[60:63], v[132:135], v[190:193], v[60:63]
	v_mfma_f32_16x16x32_bf16 v[56:59], v[146:149], v[190:193], v[56:59]
	v_mfma_f32_16x16x32_bf16 v[44:47], v[132:135], v[198:201], v[44:47]
	v_mfma_f32_16x16x32_bf16 v[40:43], v[146:149], v[198:201], v[40:43]
	v_mfma_f32_16x16x32_bf16 v[28:31], v[132:135], v[206:209], v[28:31]
	v_mfma_f32_16x16x32_bf16 v[24:27], v[146:149], v[206:209], v[24:27]
	v_mfma_f32_16x16x32_bf16 v[12:15], v[132:135], v[214:217], v[12:15]
	v_mfma_f32_16x16x32_bf16 v[8:11], v[146:149], v[214:217], v[8:11]
	v_mfma_f32_16x16x32_bf16 v[52:55], v[150:153], v[186:189], v[52:55]
	v_mfma_f32_16x16x32_bf16 v[48:51], v[158:161], v[186:189], v[48:51]
	v_mfma_f32_16x16x32_bf16 v[36:39], v[150:153], v[194:197], v[36:39]
	v_mfma_f32_16x16x32_bf16 v[32:35], v[158:161], v[194:197], v[32:35]
	v_mfma_f32_16x16x32_bf16 v[20:23], v[150:153], v[202:205], v[20:23]
	v_mfma_f32_16x16x32_bf16 v[16:19], v[158:161], v[202:205], v[16:19]
	v_mfma_f32_16x16x32_bf16 v[4:7], v[150:153], v[210:213], v[4:7]
	v_mfma_f32_16x16x32_bf16 v[0:3], v[158:161], v[210:213], v[0:3]
	v_mfma_f32_16x16x32_bf16 v[52:55], v[154:157], v[190:193], v[52:55]
	v_mfma_f32_16x16x32_bf16 v[48:51], v[162:165], v[190:193], v[48:51]
	v_mfma_f32_16x16x32_bf16 v[36:39], v[154:157], v[198:201], v[36:39]
	v_mfma_f32_16x16x32_bf16 v[32:35], v[162:165], v[198:201], v[32:35]
	v_mfma_f32_16x16x32_bf16 v[20:23], v[154:157], v[206:209], v[20:23]
	v_mfma_f32_16x16x32_bf16 v[16:19], v[162:165], v[206:209], v[16:19]
	v_mfma_f32_16x16x32_bf16 v[4:7], v[154:157], v[214:217], v[4:7]
	v_mfma_f32_16x16x32_bf16 v[0:3], v[162:165], v[214:217], v[0:3]
	s_setprio 0
	s_barrier
	s_add_i32 s46, 0, 0x18000
	s_add_i32 s47, 0, 0x1c000
	v_add_u32_e32 v146, s46, v219
	v_add_u32_e32 v162, s47, v219
	ds_read_b128 v[128:131], v146
	ds_read_b128 v[132:135], v146 offset:1024
	ds_read_b128 v[142:145], v146 offset:2048
	ds_read_b128 v[146:149], v146 offset:3072
	ds_read_b128 v[150:153], v162
	ds_read_b128 v[154:157], v162 offset:1024
	ds_read_b128 v[158:161], v162 offset:2048
	ds_read_b128 v[162:165], v162 offset:3072
	s_add_u32 s20, s20, 0x100000
	s_addc_u32 s21, s21, 0
	s_mov_b32 m0, s70
	v_lshl_add_u64 v[242:243], s[20:21], 0, v[168:169]
	ds_read_b128 v[186:189], v220 offset:32768
	ds_read_b128 v[190:193], v220 offset:33792
	ds_read_b128 v[194:197], v220 offset:34816
	ds_read_b128 v[198:201], v220 offset:35840
	ds_read_b128 v[202:205], v220 offset:36864
	ds_read_b128 v[206:209], v220 offset:37888
	ds_read_b128 v[210:213], v220 offset:38912
	ds_read_b128 v[214:217], v220 offset:39936
	global_load_lds_dwordx4 v[242:243], off
	v_lshl_add_u64 v[242:243], s[20:21], 0, v[136:137]
	s_mov_b32 m0, s71
	s_nop 0
	global_load_lds_dwordx4 v[242:243], off
	s_waitcnt vmcnt(8)
	s_waitcnt lgkmcnt(0)
	s_barrier
	s_setprio 1
	s_waitcnt lgkmcnt(0)
	v_mfma_f32_16x16x32_bf16 v[124:127], v[128:131], v[186:189], v[124:127]
	v_mfma_f32_16x16x32_bf16 v[120:123], v[142:145], v[186:189], v[120:123]
	v_mfma_f32_16x16x32_bf16 v[108:111], v[128:131], v[194:197], v[108:111]
	v_mfma_f32_16x16x32_bf16 v[104:107], v[142:145], v[194:197], v[104:107]
	v_mfma_f32_16x16x32_bf16 v[92:95], v[128:131], v[202:205], v[92:95]
	v_mfma_f32_16x16x32_bf16 v[88:91], v[142:145], v[202:205], v[88:91]
	v_mfma_f32_16x16x32_bf16 v[76:79], v[128:131], v[210:213], v[76:79]
	v_mfma_f32_16x16x32_bf16 v[72:75], v[142:145], v[210:213], v[72:75]
	v_mfma_f32_16x16x32_bf16 v[124:127], v[132:135], v[190:193], v[124:127]
	v_mfma_f32_16x16x32_bf16 v[120:123], v[146:149], v[190:193], v[120:123]
	v_mfma_f32_16x16x32_bf16 v[108:111], v[132:135], v[198:201], v[108:111]
	v_mfma_f32_16x16x32_bf16 v[104:107], v[146:149], v[198:201], v[104:107]
	v_mfma_f32_16x16x32_bf16 v[92:95], v[132:135], v[206:209], v[92:95]
	v_mfma_f32_16x16x32_bf16 v[88:91], v[146:149], v[206:209], v[88:91]
	v_mfma_f32_16x16x32_bf16 v[76:79], v[132:135], v[214:217], v[76:79]
	v_mfma_f32_16x16x32_bf16 v[72:75], v[146:149], v[214:217], v[72:75]
	v_mfma_f32_16x16x32_bf16 v[116:119], v[150:153], v[186:189], v[116:119]
	v_mfma_f32_16x16x32_bf16 v[112:115], v[158:161], v[186:189], v[112:115]
	v_mfma_f32_16x16x32_bf16 v[100:103], v[150:153], v[194:197], v[100:103]
	v_mfma_f32_16x16x32_bf16 v[96:99], v[158:161], v[194:197], v[96:99]
	v_mfma_f32_16x16x32_bf16 v[84:87], v[150:153], v[202:205], v[84:87]
	v_mfma_f32_16x16x32_bf16 v[80:83], v[158:161], v[202:205], v[80:83]
	v_mfma_f32_16x16x32_bf16 v[68:71], v[150:153], v[210:213], v[68:71]
	v_mfma_f32_16x16x32_bf16 v[64:67], v[158:161], v[210:213], v[64:67]
	v_mfma_f32_16x16x32_bf16 v[116:119], v[154:157], v[190:193], v[116:119]
	v_mfma_f32_16x16x32_bf16 v[112:115], v[162:165], v[190:193], v[112:115]
	v_mfma_f32_16x16x32_bf16 v[100:103], v[154:157], v[198:201], v[100:103]
	v_mfma_f32_16x16x32_bf16 v[96:99], v[162:165], v[198:201], v[96:99]
	v_mfma_f32_16x16x32_bf16 v[84:87], v[154:157], v[206:209], v[84:87]
	v_mfma_f32_16x16x32_bf16 v[80:83], v[162:165], v[206:209], v[80:83]
	v_mfma_f32_16x16x32_bf16 v[68:71], v[154:157], v[214:217], v[68:71]
	v_mfma_f32_16x16x32_bf16 v[64:67], v[162:165], v[214:217], v[64:67]
	s_setprio 0
	s_barrier
	s_add_i32 s20, s46, s26
	v_lshl_add_u64 v[166:167], v[166:167], 0, s[28:29]
	s_mov_b32 m0, s20
	ds_read_b128 v[186:189], v220 offset:49152
	ds_read_b128 v[190:193], v220 offset:50176
	ds_read_b128 v[194:197], v220 offset:51200
	ds_read_b128 v[198:201], v220 offset:52224
	ds_read_b128 v[202:205], v220 offset:53248
	ds_read_b128 v[206:209], v220 offset:54272
	ds_read_b128 v[210:213], v220 offset:55296
	ds_read_b128 v[214:217], v220 offset:56320
	global_load_lds_dwordx4 v[166:167], off
	s_add_i32 m0, s20, 0x2000
	s_add_u32 s2, s2, 0x100080
	v_lshl_add_u64 v[166:167], v[222:223], 0, s[28:29]
	s_addc_u32 s3, s3, 0
	s_add_i32 s20, s47, s26
	global_load_lds_dwordx4 v[166:167], off
	v_lshl_add_u64 v[166:167], s[2:3], 0, v[168:169]
	s_mov_b32 m0, s20
	s_nop 0
	global_load_lds_dwordx4 v[166:167], off
	v_lshl_add_u64 v[166:167], s[2:3], 0, v[136:137]
	s_add_i32 m0, s20, 0x2000
	s_nop 0
	global_load_lds_dwordx4 v[166:167], off
	v_lshl_add_u64 v[166:167], v[234:235], 0, s[28:29]
	s_mov_b32 m0, s48
	s_nop 0
	global_load_lds_dwordx4 v[166:167], off
	v_lshl_add_u64 v[166:167], v[236:237], 0, s[28:29]
	s_mov_b32 m0, s49
	s_nop 0
	global_load_lds_dwordx4 v[166:167], off
	s_waitcnt vmcnt(8)
	s_waitcnt lgkmcnt(0)
	s_barrier
	s_setprio 1
	s_waitcnt lgkmcnt(0)
	v_mfma_f32_16x16x32_bf16 v[60:63], v[128:131], v[186:189], v[60:63]
	v_mfma_f32_16x16x32_bf16 v[56:59], v[142:145], v[186:189], v[56:59]
	v_mfma_f32_16x16x32_bf16 v[44:47], v[128:131], v[194:197], v[44:47]
	v_mfma_f32_16x16x32_bf16 v[40:43], v[142:145], v[194:197], v[40:43]
	v_mfma_f32_16x16x32_bf16 v[28:31], v[128:131], v[202:205], v[28:31]
	v_mfma_f32_16x16x32_bf16 v[24:27], v[142:145], v[202:205], v[24:27]
	v_mfma_f32_16x16x32_bf16 v[12:15], v[128:131], v[210:213], v[12:15]
	v_mfma_f32_16x16x32_bf16 v[8:11], v[142:145], v[210:213], v[8:11]
	v_mfma_f32_16x16x32_bf16 v[60:63], v[132:135], v[190:193], v[60:63]
	v_mfma_f32_16x16x32_bf16 v[56:59], v[146:149], v[190:193], v[56:59]
	v_mfma_f32_16x16x32_bf16 v[44:47], v[132:135], v[198:201], v[44:47]
	v_mfma_f32_16x16x32_bf16 v[40:43], v[146:149], v[198:201], v[40:43]
	v_mfma_f32_16x16x32_bf16 v[28:31], v[132:135], v[206:209], v[28:31]
	v_mfma_f32_16x16x32_bf16 v[24:27], v[146:149], v[206:209], v[24:27]
	v_mfma_f32_16x16x32_bf16 v[12:15], v[132:135], v[214:217], v[12:15]
	v_mfma_f32_16x16x32_bf16 v[8:11], v[146:149], v[214:217], v[8:11]
	v_mfma_f32_16x16x32_bf16 v[52:55], v[150:153], v[186:189], v[52:55]
	v_mfma_f32_16x16x32_bf16 v[48:51], v[158:161], v[186:189], v[48:51]
	v_mfma_f32_16x16x32_bf16 v[36:39], v[150:153], v[194:197], v[36:39]
	v_mfma_f32_16x16x32_bf16 v[32:35], v[158:161], v[194:197], v[32:35]
	v_mfma_f32_16x16x32_bf16 v[20:23], v[150:153], v[202:205], v[20:23]
	v_mfma_f32_16x16x32_bf16 v[16:19], v[158:161], v[202:205], v[16:19]
	v_mfma_f32_16x16x32_bf16 v[4:7], v[150:153], v[210:213], v[4:7]
	v_mfma_f32_16x16x32_bf16 v[0:3], v[158:161], v[210:213], v[0:3]
	v_mfma_f32_16x16x32_bf16 v[52:55], v[154:157], v[190:193], v[52:55]
	v_mfma_f32_16x16x32_bf16 v[48:51], v[162:165], v[190:193], v[48:51]
	v_mfma_f32_16x16x32_bf16 v[36:39], v[154:157], v[198:201], v[36:39]
	v_mfma_f32_16x16x32_bf16 v[32:35], v[162:165], v[198:201], v[32:35]
	v_mfma_f32_16x16x32_bf16 v[20:23], v[154:157], v[206:209], v[20:23]
	v_mfma_f32_16x16x32_bf16 v[16:19], v[162:165], v[206:209], v[16:19]
	v_mfma_f32_16x16x32_bf16 v[4:7], v[154:157], v[214:217], v[4:7]
	v_mfma_f32_16x16x32_bf16 v[0:3], v[162:165], v[214:217], v[0:3]
	s_setprio 0
	s_barrier
	s_add_u32 s0, s0, 0x100
	s_addc_u32 s1, s1, 0
	s_add_u32 s43, s43, 0x100
	s_addc_u32 s44, s44, 0
	s_cmp_ge_i32 s45, s73
	s_mov_b32 s2, s45
	s_cbranch_scc0 .LBB0_90
	s_mov_b64 s[42:43], s[68:69]

.LBB0_138:
	s_add_i32 s65, s22, 2
	s_add_u32 s23, s20, 0xfffc0080
	s_addc_u32 s26, s21, -1
	s_add_i32 s67, 0, 0x10000
	s_cmp_eq_u32 s77, s22
	s_cselect_b32 s27, s1, s26
	s_cselect_b32 s26, s40, s23
	s_cselect_b32 s23, s41, s53
	s_cselect_b32 s22, s44, s45
	s_add_i32 s50, 0, 0x14000
	v_add_u32_e32 v76, s67, v209
	v_add_u32_e32 v100, s50, v209
	ds_read_b128 v[64:67], v76
	ds_read_b128 v[68:71], v76 offset:1024
	ds_read_b128 v[72:75], v76 offset:2048
	ds_read_b128 v[76:79], v76 offset:3072
	ds_read_b128 v[88:91], v100
	ds_read_b128 v[92:95], v100 offset:1024
	ds_read_b128 v[96:99], v100 offset:2048
	ds_read_b128 v[100:103], v100 offset:3072
	v_lshl_add_u64 v[234:235], s[20:21], 0, v[192:193]
	s_add_i32 m0, s3, 0xc000
	ds_read_b128 v[160:163], v210
	ds_read_b128 v[164:167], v210 offset:1024
	ds_read_b128 v[196:199], v210 offset:2048
	ds_read_b128 v[200:203], v210 offset:3072
	ds_read_b128 v[204:207], v210 offset:4096
	ds_read_b128 v[212:215], v210 offset:5120
	ds_read_b128 v[216:219], v210 offset:6144
	ds_read_b128 v[220:223], v210 offset:7168
	global_load_lds_dwordx4 v[234:235], off
	v_lshl_add_u64 v[234:235], s[20:21], 0, v[194:195]
	s_add_i32 m0, s3, 0xe000
	s_nop 0
	global_load_lds_dwordx4 v[234:235], off
	s_waitcnt vmcnt(8)
	s_waitcnt lgkmcnt(0)
	s_barrier
	s_setprio 1
	s_waitcnt lgkmcnt(0)
	v_mfma_f32_16x16x32_bf16 v[152:155], v[64:67], v[160:163], v[152:155]
	v_mfma_f32_16x16x32_bf16 v[156:159], v[72:75], v[160:163], v[156:159]
	v_mfma_f32_16x16x32_bf16 v[136:139], v[64:67], v[196:199], v[136:139]
	v_mfma_f32_16x16x32_bf16 v[140:143], v[72:75], v[196:199], v[140:143]
	v_mfma_f32_16x16x32_bf16 v[120:123], v[64:67], v[204:207], v[120:123]
	v_mfma_f32_16x16x32_bf16 v[124:127], v[72:75], v[204:207], v[124:127]
	v_mfma_f32_16x16x32_bf16 v[104:107], v[64:67], v[216:219], v[104:107]
	v_mfma_f32_16x16x32_bf16 v[108:111], v[72:75], v[216:219], v[108:111]
	v_mfma_f32_16x16x32_bf16 v[152:155], v[68:71], v[164:167], v[152:155]
	v_mfma_f32_16x16x32_bf16 v[156:159], v[76:79], v[164:167], v[156:159]
	v_mfma_f32_16x16x32_bf16 v[136:139], v[68:71], v[200:203], v[136:139]
	v_mfma_f32_16x16x32_bf16 v[140:143], v[76:79], v[200:203], v[140:143]
	v_mfma_f32_16x16x32_bf16 v[120:123], v[68:71], v[212:215], v[120:123]
	v_mfma_f32_16x16x32_bf16 v[124:127], v[76:79], v[212:215], v[124:127]
	v_mfma_f32_16x16x32_bf16 v[104:107], v[68:71], v[220:223], v[104:107]
	v_mfma_f32_16x16x32_bf16 v[108:111], v[76:79], v[220:223], v[108:111]
	v_mfma_f32_16x16x32_bf16 v[144:147], v[88:91], v[160:163], v[144:147]
	v_mfma_f32_16x16x32_bf16 v[148:151], v[96:99], v[160:163], v[148:151]
	v_mfma_f32_16x16x32_bf16 v[128:131], v[88:91], v[196:199], v[128:131]
	v_mfma_f32_16x16x32_bf16 v[132:135], v[96:99], v[196:199], v[132:135]
	v_mfma_f32_16x16x32_bf16 v[112:115], v[88:91], v[204:207], v[112:115]
	v_mfma_f32_16x16x32_bf16 v[116:119], v[96:99], v[204:207], v[116:119]
	v_mfma_f32_16x16x32_bf16 v[80:83], v[88:91], v[216:219], v[80:83]
	v_mfma_f32_16x16x32_bf16 v[84:87], v[96:99], v[216:219], v[84:87]
	v_mfma_f32_16x16x32_bf16 v[144:147], v[92:95], v[164:167], v[144:147]
	v_mfma_f32_16x16x32_bf16 v[148:151], v[100:103], v[164:167], v[148:151]
	v_mfma_f32_16x16x32_bf16 v[128:131], v[92:95], v[200:203], v[128:131]
	v_mfma_f32_16x16x32_bf16 v[132:135], v[100:103], v[200:203], v[132:135]
	v_mfma_f32_16x16x32_bf16 v[112:115], v[92:95], v[212:215], v[112:115]
	v_mfma_f32_16x16x32_bf16 v[116:119], v[100:103], v[212:215], v[116:119]
	v_mfma_f32_16x16x32_bf16 v[80:83], v[92:95], v[220:223], v[80:83]
	v_mfma_f32_16x16x32_bf16 v[84:87], v[100:103], v[220:223], v[84:87]
	s_setprio 0
	s_barrier
	s_add_i32 s51, s67, s73
	v_lshl_add_u64 v[234:235], s[22:23], 0, v[168:169]
	s_mov_b32 m0, s51
	ds_read_b128 v[160:163], v210 offset:16384
	ds_read_b128 v[164:167], v210 offset:17408
	ds_read_b128 v[196:199], v210 offset:18432
	ds_read_b128 v[200:203], v210 offset:19456
	ds_read_b128 v[204:207], v210 offset:20480
	ds_read_b128 v[212:215], v210 offset:21504
	ds_read_b128 v[216:219], v210 offset:22528
	ds_read_b128 v[220:223], v210 offset:23552
	global_load_lds_dwordx4 v[234:235], off
	s_add_i32 m0, s51, 0x2000
	s_add_u32 vcc_lo, s22, 0x40000
	v_lshl_add_u64 v[236:237], s[22:23], 0, v[190:191]
	s_addc_u32 vcc_hi, s23, 0
	s_add_i32 s50, s50, s73
	global_load_lds_dwordx4 v[236:237], off
	v_lshl_add_u64 v[242:243], vcc, 0, v[168:169]
	s_mov_b32 m0, s50
	v_lshl_add_u64 v[244:245], s[26:27], 0, v[188:189]
	global_load_lds_dwordx4 v[242:243], off
	v_lshl_add_u64 v[242:243], vcc, 0, v[190:191]
	s_add_i32 m0, s50, 0x2000
	s_nop 0
	global_load_lds_dwordx4 v[242:243], off
	v_lshl_add_u64 v[242:243], s[26:27], 0, v[186:187]
	s_mov_b32 m0, s3
	s_nop 0
	global_load_lds_dwordx4 v[242:243], off
	s_mov_b32 m0, s74
	s_nop 0
	global_load_lds_dwordx4 v[244:245], off
	s_waitcnt vmcnt(8)
	s_waitcnt lgkmcnt(0)
	s_barrier
	s_setprio 1
	s_waitcnt lgkmcnt(0)
	v_mfma_f32_16x16x32_bf16 v[56:59], v[64:67], v[160:163], v[56:59]
	v_mfma_f32_16x16x32_bf16 v[60:63], v[72:75], v[160:163], v[60:63]
	v_mfma_f32_16x16x32_bf16 v[40:43], v[64:67], v[196:199], v[40:43]
	v_mfma_f32_16x16x32_bf16 v[44:47], v[72:75], v[196:199], v[44:47]
	v_mfma_f32_16x16x32_bf16 v[24:27], v[64:67], v[204:207], v[24:27]
	v_mfma_f32_16x16x32_bf16 v[28:31], v[72:75], v[204:207], v[28:31]
	v_mfma_f32_16x16x32_bf16 v[8:11], v[64:67], v[216:219], v[8:11]
	v_mfma_f32_16x16x32_bf16 v[12:15], v[72:75], v[216:219], v[12:15]
	v_mfma_f32_16x16x32_bf16 v[56:59], v[68:71], v[164:167], v[56:59]
	v_mfma_f32_16x16x32_bf16 v[60:63], v[76:79], v[164:167], v[60:63]
	v_mfma_f32_16x16x32_bf16 v[40:43], v[68:71], v[200:203], v[40:43]
	v_mfma_f32_16x16x32_bf16 v[44:47], v[76:79], v[200:203], v[44:47]
	v_mfma_f32_16x16x32_bf16 v[24:27], v[68:71], v[212:215], v[24:27]
	v_mfma_f32_16x16x32_bf16 v[28:31], v[76:79], v[212:215], v[28:31]
	v_mfma_f32_16x16x32_bf16 v[8:11], v[68:71], v[220:223], v[8:11]
	v_mfma_f32_16x16x32_bf16 v[12:15], v[76:79], v[220:223], v[12:15]
	v_mfma_f32_16x16x32_bf16 v[48:51], v[88:91], v[160:163], v[48:51]
	v_mfma_f32_16x16x32_bf16 v[52:55], v[96:99], v[160:163], v[52:55]
	v_mfma_f32_16x16x32_bf16 v[32:35], v[88:91], v[196:199], v[32:35]
	v_mfma_f32_16x16x32_bf16 v[36:39], v[96:99], v[196:199], v[36:39]
	v_mfma_f32_16x16x32_bf16 v[16:19], v[88:91], v[204:207], v[16:19]
	v_mfma_f32_16x16x32_bf16 v[20:23], v[96:99], v[204:207], v[20:23]
	v_mfma_f32_16x16x32_bf16 v[0:3], v[88:91], v[216:219], v[0:3]
	v_mfma_f32_16x16x32_bf16 v[4:7], v[96:99], v[216:219], v[4:7]
	v_mfma_f32_16x16x32_bf16 v[48:51], v[92:95], v[164:167], v[48:51]
	v_mfma_f32_16x16x32_bf16 v[52:55], v[100:103], v[164:167], v[52:55]
	v_mfma_f32_16x16x32_bf16 v[32:35], v[92:95], v[200:203], v[32:35]
	v_mfma_f32_16x16x32_bf16 v[36:39], v[100:103], v[200:203], v[36:39]
	v_mfma_f32_16x16x32_bf16 v[16:19], v[92:95], v[212:215], v[16:19]
	v_mfma_f32_16x16x32_bf16 v[20:23], v[100:103], v[212:215], v[20:23]
	v_mfma_f32_16x16x32_bf16 v[0:3], v[92:95], v[220:223], v[0:3]
	v_mfma_f32_16x16x32_bf16 v[4:7], v[100:103], v[220:223], v[4:7]
	s_setprio 0
	s_barrier
	s_add_i32 s50, 0, 0x18000
	s_add_i32 s51, 0, 0x1c000
	v_add_u32_e32 v76, s50, v209
	v_add_u32_e32 v100, s51, v209
	ds_read_b128 v[64:67], v76
	ds_read_b128 v[68:71], v76 offset:1024
	ds_read_b128 v[72:75], v76 offset:2048
	ds_read_b128 v[76:79], v76 offset:3072
	ds_read_b128 v[88:91], v100
	ds_read_b128 v[92:95], v100 offset:1024
	ds_read_b128 v[96:99], v100 offset:2048
	ds_read_b128 v[100:103], v100 offset:3072
	s_add_u32 s26, s26, 0x40000
	s_addc_u32 s27, s27, 0
	s_mov_b32 m0, s75
	v_lshl_add_u64 v[246:247], s[26:27], 0, v[186:187]
	ds_read_b128 v[160:163], v210 offset:32768
	ds_read_b128 v[164:167], v210 offset:33792
	ds_read_b128 v[196:199], v210 offset:34816
	ds_read_b128 v[200:203], v210 offset:35840
	ds_read_b128 v[204:207], v210 offset:36864
	ds_read_b128 v[212:215], v210 offset:37888
	ds_read_b128 v[216:219], v210 offset:38912
	ds_read_b128 v[220:223], v210 offset:39936
	global_load_lds_dwordx4 v[246:247], off
	v_lshl_add_u64 v[246:247], s[26:27], 0, v[188:189]
	s_mov_b32 m0, s76
	s_nop 0
	global_load_lds_dwordx4 v[246:247], off
	s_waitcnt vmcnt(8)
	s_waitcnt lgkmcnt(0)
	s_barrier
	s_setprio 1
	s_waitcnt lgkmcnt(0)
	v_mfma_f32_16x16x32_bf16 v[152:155], v[64:67], v[160:163], v[152:155]
	v_mfma_f32_16x16x32_bf16 v[156:159], v[72:75], v[160:163], v[156:159]
	v_mfma_f32_16x16x32_bf16 v[136:139], v[64:67], v[196:199], v[136:139]
	v_mfma_f32_16x16x32_bf16 v[140:143], v[72:75], v[196:199], v[140:143]
	v_mfma_f32_16x16x32_bf16 v[120:123], v[64:67], v[204:207], v[120:123]
	v_mfma_f32_16x16x32_bf16 v[124:127], v[72:75], v[204:207], v[124:127]
	v_mfma_f32_16x16x32_bf16 v[104:107], v[64:67], v[216:219], v[104:107]
	v_mfma_f32_16x16x32_bf16 v[108:111], v[72:75], v[216:219], v[108:111]
	v_mfma_f32_16x16x32_bf16 v[152:155], v[68:71], v[164:167], v[152:155]
	v_mfma_f32_16x16x32_bf16 v[156:159], v[76:79], v[164:167], v[156:159]
	v_mfma_f32_16x16x32_bf16 v[136:139], v[68:71], v[200:203], v[136:139]
	v_mfma_f32_16x16x32_bf16 v[140:143], v[76:79], v[200:203], v[140:143]
	v_mfma_f32_16x16x32_bf16 v[120:123], v[68:71], v[212:215], v[120:123]
	v_mfma_f32_16x16x32_bf16 v[124:127], v[76:79], v[212:215], v[124:127]
	v_mfma_f32_16x16x32_bf16 v[104:107], v[68:71], v[220:223], v[104:107]
	v_mfma_f32_16x16x32_bf16 v[108:111], v[76:79], v[220:223], v[108:111]
	v_mfma_f32_16x16x32_bf16 v[144:147], v[88:91], v[160:163], v[144:147]
	v_mfma_f32_16x16x32_bf16 v[148:151], v[96:99], v[160:163], v[148:151]
	v_mfma_f32_16x16x32_bf16 v[128:131], v[88:91], v[196:199], v[128:131]
	v_mfma_f32_16x16x32_bf16 v[132:135], v[96:99], v[196:199], v[132:135]
	v_mfma_f32_16x16x32_bf16 v[112:115], v[88:91], v[204:207], v[112:115]
	v_mfma_f32_16x16x32_bf16 v[116:119], v[96:99], v[204:207], v[116:119]
	v_mfma_f32_16x16x32_bf16 v[80:83], v[88:91], v[216:219], v[80:83]
	v_mfma_f32_16x16x32_bf16 v[84:87], v[96:99], v[216:219], v[84:87]
	v_mfma_f32_16x16x32_bf16 v[144:147], v[92:95], v[164:167], v[144:147]
	v_mfma_f32_16x16x32_bf16 v[148:151], v[100:103], v[164:167], v[148:151]
	v_mfma_f32_16x16x32_bf16 v[128:131], v[92:95], v[200:203], v[128:131]
	v_mfma_f32_16x16x32_bf16 v[132:135], v[100:103], v[200:203], v[132:135]
	v_mfma_f32_16x16x32_bf16 v[112:115], v[92:95], v[212:215], v[112:115]
	v_mfma_f32_16x16x32_bf16 v[116:119], v[100:103], v[212:215], v[116:119]
	v_mfma_f32_16x16x32_bf16 v[80:83], v[92:95], v[220:223], v[80:83]
	v_mfma_f32_16x16x32_bf16 v[84:87], v[100:103], v[220:223], v[84:87]
	s_setprio 0
	s_barrier
	s_add_i32 s26, s50, s73
	v_lshl_add_u64 v[234:235], v[234:235], 0, s[28:29]
	s_mov_b32 m0, s26
	ds_read_b128 v[160:163], v210 offset:49152
	ds_read_b128 v[164:167], v210 offset:50176
	ds_read_b128 v[196:199], v210 offset:51200
	ds_read_b128 v[200:203], v210 offset:52224
	ds_read_b128 v[204:207], v210 offset:53248
	ds_read_b128 v[212:215], v210 offset:54272
	ds_read_b128 v[216:219], v210 offset:55296
	ds_read_b128 v[220:223], v210 offset:56320
	global_load_lds_dwordx4 v[234:235], off
	s_add_i32 m0, s26, 0x2000
	s_add_u32 s22, s22, 0x40080
	v_lshl_add_u64 v[234:235], v[236:237], 0, s[28:29]
	s_addc_u32 s23, s23, 0
	s_add_i32 s26, s51, s73
	global_load_lds_dwordx4 v[234:235], off
	v_lshl_add_u64 v[234:235], s[22:23], 0, v[168:169]
	s_mov_b32 m0, s26
	s_nop 0
	global_load_lds_dwordx4 v[234:235], off
	v_lshl_add_u64 v[234:235], s[22:23], 0, v[190:191]
	s_add_i32 m0, s26, 0x2000
	s_nop 0
	global_load_lds_dwordx4 v[234:235], off
	v_lshl_add_u64 v[234:235], v[242:243], 0, s[28:29]
	s_mov_b32 m0, s46
	s_nop 0
	global_load_lds_dwordx4 v[234:235], off
	v_lshl_add_u64 v[234:235], v[244:245], 0, s[28:29]
	s_mov_b32 m0, s47
	s_nop 0
	global_load_lds_dwordx4 v[234:235], off
	s_waitcnt vmcnt(8)
	s_waitcnt lgkmcnt(0)
	s_barrier
	s_setprio 1
	s_waitcnt lgkmcnt(0)
	v_mfma_f32_16x16x32_bf16 v[56:59], v[64:67], v[160:163], v[56:59]
	v_mfma_f32_16x16x32_bf16 v[60:63], v[72:75], v[160:163], v[60:63]
	v_mfma_f32_16x16x32_bf16 v[40:43], v[64:67], v[196:199], v[40:43]
	v_mfma_f32_16x16x32_bf16 v[44:47], v[72:75], v[196:199], v[44:47]
	v_mfma_f32_16x16x32_bf16 v[24:27], v[64:67], v[204:207], v[24:27]
	v_mfma_f32_16x16x32_bf16 v[28:31], v[72:75], v[204:207], v[28:31]
	v_mfma_f32_16x16x32_bf16 v[8:11], v[64:67], v[216:219], v[8:11]
	v_mfma_f32_16x16x32_bf16 v[12:15], v[72:75], v[216:219], v[12:15]
	v_mfma_f32_16x16x32_bf16 v[56:59], v[68:71], v[164:167], v[56:59]
	v_mfma_f32_16x16x32_bf16 v[60:63], v[76:79], v[164:167], v[60:63]
	v_mfma_f32_16x16x32_bf16 v[40:43], v[68:71], v[200:203], v[40:43]
	v_mfma_f32_16x16x32_bf16 v[44:47], v[76:79], v[200:203], v[44:47]
	v_mfma_f32_16x16x32_bf16 v[24:27], v[68:71], v[212:215], v[24:27]
	v_mfma_f32_16x16x32_bf16 v[28:31], v[76:79], v[212:215], v[28:31]
	v_mfma_f32_16x16x32_bf16 v[8:11], v[68:71], v[220:223], v[8:11]
	v_mfma_f32_16x16x32_bf16 v[12:15], v[76:79], v[220:223], v[12:15]
	v_mfma_f32_16x16x32_bf16 v[48:51], v[88:91], v[160:163], v[48:51]
	v_mfma_f32_16x16x32_bf16 v[52:55], v[96:99], v[160:163], v[52:55]
	v_mfma_f32_16x16x32_bf16 v[32:35], v[88:91], v[196:199], v[32:35]
	v_mfma_f32_16x16x32_bf16 v[36:39], v[96:99], v[196:199], v[36:39]
	v_mfma_f32_16x16x32_bf16 v[16:19], v[88:91], v[204:207], v[16:19]
	v_mfma_f32_16x16x32_bf16 v[20:23], v[96:99], v[204:207], v[20:23]
	v_mfma_f32_16x16x32_bf16 v[0:3], v[88:91], v[216:219], v[0:3]
	v_mfma_f32_16x16x32_bf16 v[4:7], v[96:99], v[216:219], v[4:7]
	v_mfma_f32_16x16x32_bf16 v[48:51], v[92:95], v[164:167], v[48:51]
	v_mfma_f32_16x16x32_bf16 v[52:55], v[100:103], v[164:167], v[52:55]
	v_mfma_f32_16x16x32_bf16 v[32:35], v[92:95], v[200:203], v[32:35]
	v_mfma_f32_16x16x32_bf16 v[36:39], v[100:103], v[200:203], v[36:39]
	v_mfma_f32_16x16x32_bf16 v[16:19], v[92:95], v[212:215], v[16:19]
	v_mfma_f32_16x16x32_bf16 v[20:23], v[100:103], v[212:215], v[20:23]
	v_mfma_f32_16x16x32_bf16 v[0:3], v[92:95], v[220:223], v[0:3]
	v_mfma_f32_16x16x32_bf16 v[4:7], v[100:103], v[220:223], v[4:7]
	s_setprio 0
	s_barrier
	s_add_u32 s20, s20, 0x100
	s_addc_u32 s21, s21, 0
	s_add_u32 s45, s45, 0x100
	s_addc_u32 s53, s53, 0
	s_cmp_ge_i32 s65, s42
	s_mov_b32 s22, s65
	s_cbranch_scc0 .LBB0_138

.LBB0_199:
	s_add_i32 s47, s2, 2
	s_add_u32 s3, s0, 0xfffc0080
	s_addc_u32 s20, s1, -1
	s_add_i32 s61, 0, 0x10000
	s_cmp_eq_u32 s77, s2
	s_cselect_b32 s21, s41, s20
	s_cselect_b32 s20, s42, s3
	s_cselect_b32 s3, s43, s46
	s_cselect_b32 s2, s44, s45
	s_add_i32 s63, 0, 0x14000
	v_add_u32_e32 v146, s61, v219
	v_add_u32_e32 v162, s63, v219
	ds_read_b128 v[128:131], v146
	ds_read_b128 v[132:135], v146 offset:1024
	ds_read_b128 v[142:145], v146 offset:2048
	ds_read_b128 v[146:149], v146 offset:3072
	ds_read_b128 v[150:153], v162
	ds_read_b128 v[154:157], v162 offset:1024
	ds_read_b128 v[158:161], v162 offset:2048
	ds_read_b128 v[162:165], v162 offset:3072
	v_lshl_add_u64 v[166:167], s[0:1], 0, v[138:139]
	s_add_i32 m0, s25, 0xc000
	ds_read_b128 v[186:189], v220
	ds_read_b128 v[190:193], v220 offset:1024
	ds_read_b128 v[194:197], v220 offset:2048
	ds_read_b128 v[198:201], v220 offset:3072
	ds_read_b128 v[202:205], v220 offset:4096
	ds_read_b128 v[206:209], v220 offset:5120
	ds_read_b128 v[210:213], v220 offset:6144
	ds_read_b128 v[214:217], v220 offset:7168
	global_load_lds_dwordx4 v[166:167], off
	v_lshl_add_u64 v[166:167], s[0:1], 0, v[140:141]
	s_add_i32 m0, s25, 0xe000
	s_nop 0
	global_load_lds_dwordx4 v[166:167], off
	s_waitcnt vmcnt(8)
	s_waitcnt lgkmcnt(0)
	s_barrier
	s_setprio 1
	s_waitcnt lgkmcnt(0)
	v_mfma_f32_16x16x32_bf16 v[124:127], v[128:131], v[186:189], v[124:127]
	v_mfma_f32_16x16x32_bf16 v[120:123], v[142:145], v[186:189], v[120:123]
	v_mfma_f32_16x16x32_bf16 v[108:111], v[128:131], v[194:197], v[108:111]
	v_mfma_f32_16x16x32_bf16 v[104:107], v[142:145], v[194:197], v[104:107]
	v_mfma_f32_16x16x32_bf16 v[92:95], v[128:131], v[202:205], v[92:95]
	v_mfma_f32_16x16x32_bf16 v[88:91], v[142:145], v[202:205], v[88:91]
	v_mfma_f32_16x16x32_bf16 v[76:79], v[128:131], v[210:213], v[76:79]
	v_mfma_f32_16x16x32_bf16 v[72:75], v[142:145], v[210:213], v[72:75]
	v_mfma_f32_16x16x32_bf16 v[124:127], v[132:135], v[190:193], v[124:127]
	v_mfma_f32_16x16x32_bf16 v[120:123], v[146:149], v[190:193], v[120:123]
	v_mfma_f32_16x16x32_bf16 v[108:111], v[132:135], v[198:201], v[108:111]
	v_mfma_f32_16x16x32_bf16 v[104:107], v[146:149], v[198:201], v[104:107]
	v_mfma_f32_16x16x32_bf16 v[92:95], v[132:135], v[206:209], v[92:95]
	v_mfma_f32_16x16x32_bf16 v[88:91], v[146:149], v[206:209], v[88:91]
	v_mfma_f32_16x16x32_bf16 v[76:79], v[132:135], v[214:217], v[76:79]
	v_mfma_f32_16x16x32_bf16 v[72:75], v[146:149], v[214:217], v[72:75]
	v_mfma_f32_16x16x32_bf16 v[116:119], v[150:153], v[186:189], v[116:119]
	v_mfma_f32_16x16x32_bf16 v[112:115], v[158:161], v[186:189], v[112:115]
	v_mfma_f32_16x16x32_bf16 v[100:103], v[150:153], v[194:197], v[100:103]
	v_mfma_f32_16x16x32_bf16 v[96:99], v[158:161], v[194:197], v[96:99]
	v_mfma_f32_16x16x32_bf16 v[84:87], v[150:153], v[202:205], v[84:87]
	v_mfma_f32_16x16x32_bf16 v[80:83], v[158:161], v[202:205], v[80:83]
	v_mfma_f32_16x16x32_bf16 v[68:71], v[150:153], v[210:213], v[68:71]
	v_mfma_f32_16x16x32_bf16 v[64:67], v[158:161], v[210:213], v[64:67]
	v_mfma_f32_16x16x32_bf16 v[116:119], v[154:157], v[190:193], v[116:119]
	v_mfma_f32_16x16x32_bf16 v[112:115], v[162:165], v[190:193], v[112:115]
	v_mfma_f32_16x16x32_bf16 v[100:103], v[154:157], v[198:201], v[100:103]
	v_mfma_f32_16x16x32_bf16 v[96:99], v[162:165], v[198:201], v[96:99]
	v_mfma_f32_16x16x32_bf16 v[84:87], v[154:157], v[206:209], v[84:87]
	v_mfma_f32_16x16x32_bf16 v[80:83], v[162:165], v[206:209], v[80:83]
	v_mfma_f32_16x16x32_bf16 v[68:71], v[154:157], v[214:217], v[68:71]
	v_mfma_f32_16x16x32_bf16 v[64:67], v[162:165], v[214:217], v[64:67]
	s_setprio 0
	s_barrier
	s_add_i32 s61, s61, s26
	v_lshl_add_u64 v[166:167], s[2:3], 0, v[168:169]
	s_mov_b32 m0, s61
	ds_read_b128 v[186:189], v220 offset:16384
	ds_read_b128 v[190:193], v220 offset:17408
	ds_read_b128 v[194:197], v220 offset:18432
	ds_read_b128 v[198:201], v220 offset:19456
	ds_read_b128 v[202:205], v220 offset:20480
	ds_read_b128 v[206:209], v220 offset:21504
	ds_read_b128 v[210:213], v220 offset:22528
	ds_read_b128 v[214:217], v220 offset:23552
	global_load_lds_dwordx4 v[166:167], off
	s_add_i32 m0, s61, 0x2000
	s_add_u32 s68, s2, 0x40000
	v_lshl_add_u64 v[222:223], s[2:3], 0, v[136:137]
	s_addc_u32 s69, s3, 0
	s_add_i32 s61, s63, s26
	global_load_lds_dwordx4 v[222:223], off
	v_lshl_add_u64 v[234:235], s[68:69], 0, v[168:169]
	s_mov_b32 m0, s61
	v_lshl_add_u64 v[236:237], s[20:21], 0, v[136:137]
	global_load_lds_dwordx4 v[234:235], off
	v_lshl_add_u64 v[234:235], s[68:69], 0, v[136:137]
	s_add_i32 m0, s61, 0x2000
	s_nop 0
	global_load_lds_dwordx4 v[234:235], off
	v_lshl_add_u64 v[234:235], s[20:21], 0, v[168:169]
	s_mov_b32 m0, s25
	s_nop 0
	global_load_lds_dwordx4 v[234:235], off
	s_mov_b32 m0, s27
	s_nop 0
	global_load_lds_dwordx4 v[236:237], off
	s_waitcnt vmcnt(8)
	s_waitcnt lgkmcnt(0)
	s_barrier
	s_setprio 1
	s_waitcnt lgkmcnt(0)
	v_mfma_f32_16x16x32_bf16 v[60:63], v[128:131], v[186:189], v[60:63]
	v_mfma_f32_16x16x32_bf16 v[56:59], v[142:145], v[186:189], v[56:59]
	v_mfma_f32_16x16x32_bf16 v[44:47], v[128:131], v[194:197], v[44:47]
	v_mfma_f32_16x16x32_bf16 v[40:43], v[142:145], v[194:197], v[40:43]
	v_mfma_f32_16x16x32_bf16 v[28:31], v[128:131], v[202:205], v[28:31]
	v_mfma_f32_16x16x32_bf16 v[24:27], v[142:145], v[202:205], v[24:27]
	v_mfma_f32_16x16x32_bf16 v[12:15], v[128:131], v[210:213], v[12:15]
	v_mfma_f32_16x16x32_bf16 v[8:11], v[142:145], v[210:213], v[8:11]
	v_mfma_f32_16x16x32_bf16 v[60:63], v[132:135], v[190:193], v[60:63]
	v_mfma_f32_16x16x32_bf16 v[56:59], v[146:149], v[190:193], v[56:59]
	v_mfma_f32_16x16x32_bf16 v[44:47], v[132:135], v[198:201], v[44:47]
	v_mfma_f32_16x16x32_bf16 v[40:43], v[146:149], v[198:201], v[40:43]
	v_mfma_f32_16x16x32_bf16 v[28:31], v[132:135], v[206:209], v[28:31]
	v_mfma_f32_16x16x32_bf16 v[24:27], v[146:149], v[206:209], v[24:27]
	v_mfma_f32_16x16x32_bf16 v[12:15], v[132:135], v[214:217], v[12:15]
	v_mfma_f32_16x16x32_bf16 v[8:11], v[146:149], v[214:217], v[8:11]
	v_mfma_f32_16x16x32_bf16 v[52:55], v[150:153], v[186:189], v[52:55]
	v_mfma_f32_16x16x32_bf16 v[48:51], v[158:161], v[186:189], v[48:51]
	v_mfma_f32_16x16x32_bf16 v[36:39], v[150:153], v[194:197], v[36:39]
	v_mfma_f32_16x16x32_bf16 v[32:35], v[158:161], v[194:197], v[32:35]
	v_mfma_f32_16x16x32_bf16 v[20:23], v[150:153], v[202:205], v[20:23]
	v_mfma_f32_16x16x32_bf16 v[16:19], v[158:161], v[202:205], v[16:19]
	v_mfma_f32_16x16x32_bf16 v[4:7], v[150:153], v[210:213], v[4:7]
	v_mfma_f32_16x16x32_bf16 v[0:3], v[158:161], v[210:213], v[0:3]
	v_mfma_f32_16x16x32_bf16 v[52:55], v[154:157], v[190:193], v[52:55]
	v_mfma_f32_16x16x32_bf16 v[48:51], v[162:165], v[190:193], v[48:51]
	v_mfma_f32_16x16x32_bf16 v[36:39], v[154:157], v[198:201], v[36:39]
	v_mfma_f32_16x16x32_bf16 v[32:35], v[162:165], v[198:201], v[32:35]
	v_mfma_f32_16x16x32_bf16 v[20:23], v[154:157], v[206:209], v[20:23]
	v_mfma_f32_16x16x32_bf16 v[16:19], v[162:165], v[206:209], v[16:19]
	v_mfma_f32_16x16x32_bf16 v[4:7], v[154:157], v[214:217], v[4:7]
	v_mfma_f32_16x16x32_bf16 v[0:3], v[162:165], v[214:217], v[0:3]
	s_setprio 0
	s_barrier
	s_add_i32 s61, 0, 0x18000
	s_add_i32 s63, 0, 0x1c000
	v_add_u32_e32 v146, s61, v219
	v_add_u32_e32 v162, s63, v219
	ds_read_b128 v[128:131], v146
	ds_read_b128 v[132:135], v146 offset:1024
	ds_read_b128 v[142:145], v146 offset:2048
	ds_read_b128 v[146:149], v146 offset:3072
	ds_read_b128 v[150:153], v162
	ds_read_b128 v[154:157], v162 offset:1024
	ds_read_b128 v[158:161], v162 offset:2048
	ds_read_b128 v[162:165], v162 offset:3072
	s_add_u32 s20, s20, 0x40000
	s_addc_u32 s21, s21, 0
	s_mov_b32 m0, s70
	v_lshl_add_u64 v[242:243], s[20:21], 0, v[168:169]
	ds_read_b128 v[186:189], v220 offset:32768
	ds_read_b128 v[190:193], v220 offset:33792
	ds_read_b128 v[194:197], v220 offset:34816
	ds_read_b128 v[198:201], v220 offset:35840
	ds_read_b128 v[202:205], v220 offset:36864
	ds_read_b128 v[206:209], v220 offset:37888
	ds_read_b128 v[210:213], v220 offset:38912
	ds_read_b128 v[214:217], v220 offset:39936
	global_load_lds_dwordx4 v[242:243], off
	v_lshl_add_u64 v[242:243], s[20:21], 0, v[136:137]
	s_mov_b32 m0, s71
	s_nop 0
	global_load_lds_dwordx4 v[242:243], off
	s_waitcnt vmcnt(8)
	s_waitcnt lgkmcnt(0)
	s_barrier
	s_setprio 1
	s_waitcnt lgkmcnt(0)
	v_mfma_f32_16x16x32_bf16 v[124:127], v[128:131], v[186:189], v[124:127]
	v_mfma_f32_16x16x32_bf16 v[120:123], v[142:145], v[186:189], v[120:123]
	v_mfma_f32_16x16x32_bf16 v[108:111], v[128:131], v[194:197], v[108:111]
	v_mfma_f32_16x16x32_bf16 v[104:107], v[142:145], v[194:197], v[104:107]
	v_mfma_f32_16x16x32_bf16 v[92:95], v[128:131], v[202:205], v[92:95]
	v_mfma_f32_16x16x32_bf16 v[88:91], v[142:145], v[202:205], v[88:91]
	v_mfma_f32_16x16x32_bf16 v[76:79], v[128:131], v[210:213], v[76:79]
	v_mfma_f32_16x16x32_bf16 v[72:75], v[142:145], v[210:213], v[72:75]
	v_mfma_f32_16x16x32_bf16 v[124:127], v[132:135], v[190:193], v[124:127]
	v_mfma_f32_16x16x32_bf16 v[120:123], v[146:149], v[190:193], v[120:123]
	v_mfma_f32_16x16x32_bf16 v[108:111], v[132:135], v[198:201], v[108:111]
	v_mfma_f32_16x16x32_bf16 v[104:107], v[146:149], v[198:201], v[104:107]
	v_mfma_f32_16x16x32_bf16 v[92:95], v[132:135], v[206:209], v[92:95]
	v_mfma_f32_16x16x32_bf16 v[88:91], v[146:149], v[206:209], v[88:91]
	v_mfma_f32_16x16x32_bf16 v[76:79], v[132:135], v[214:217], v[76:79]
	v_mfma_f32_16x16x32_bf16 v[72:75], v[146:149], v[214:217], v[72:75]
	v_mfma_f32_16x16x32_bf16 v[116:119], v[150:153], v[186:189], v[116:119]
	v_mfma_f32_16x16x32_bf16 v[112:115], v[158:161], v[186:189], v[112:115]
	v_mfma_f32_16x16x32_bf16 v[100:103], v[150:153], v[194:197], v[100:103]
	v_mfma_f32_16x16x32_bf16 v[96:99], v[158:161], v[194:197], v[96:99]
	v_mfma_f32_16x16x32_bf16 v[84:87], v[150:153], v[202:205], v[84:87]
	v_mfma_f32_16x16x32_bf16 v[80:83], v[158:161], v[202:205], v[80:83]
	v_mfma_f32_16x16x32_bf16 v[68:71], v[150:153], v[210:213], v[68:71]
	v_mfma_f32_16x16x32_bf16 v[64:67], v[158:161], v[210:213], v[64:67]
	v_mfma_f32_16x16x32_bf16 v[116:119], v[154:157], v[190:193], v[116:119]
	v_mfma_f32_16x16x32_bf16 v[112:115], v[162:165], v[190:193], v[112:115]
	v_mfma_f32_16x16x32_bf16 v[100:103], v[154:157], v[198:201], v[100:103]
	v_mfma_f32_16x16x32_bf16 v[96:99], v[162:165], v[198:201], v[96:99]
	v_mfma_f32_16x16x32_bf16 v[84:87], v[154:157], v[206:209], v[84:87]
	v_mfma_f32_16x16x32_bf16 v[80:83], v[162:165], v[206:209], v[80:83]
	v_mfma_f32_16x16x32_bf16 v[68:71], v[154:157], v[214:217], v[68:71]
	v_mfma_f32_16x16x32_bf16 v[64:67], v[162:165], v[214:217], v[64:67]
	s_setprio 0
	s_barrier
	s_add_i32 s20, s61, s26
	v_lshl_add_u64 v[166:167], v[166:167], 0, s[28:29]
	s_mov_b32 m0, s20
	ds_read_b128 v[186:189], v220 offset:49152
	ds_read_b128 v[190:193], v220 offset:50176
	ds_read_b128 v[194:197], v220 offset:51200
	ds_read_b128 v[198:201], v220 offset:52224
	ds_read_b128 v[202:205], v220 offset:53248
	ds_read_b128 v[206:209], v220 offset:54272
	ds_read_b128 v[210:213], v220 offset:55296
	ds_read_b128 v[214:217], v220 offset:56320
	global_load_lds_dwordx4 v[166:167], off
	s_add_i32 m0, s20, 0x2000
	s_add_u32 s2, s2, 0x40080
	v_lshl_add_u64 v[166:167], v[222:223], 0, s[28:29]
	s_addc_u32 s3, s3, 0
	s_add_i32 s20, s63, s26
	global_load_lds_dwordx4 v[166:167], off
	v_lshl_add_u64 v[166:167], s[2:3], 0, v[168:169]
	s_mov_b32 m0, s20
	s_nop 0
	global_load_lds_dwordx4 v[166:167], off
	v_lshl_add_u64 v[166:167], s[2:3], 0, v[136:137]
	s_add_i32 m0, s20, 0x2000
	s_nop 0
	global_load_lds_dwordx4 v[166:167], off
	v_lshl_add_u64 v[166:167], v[234:235], 0, s[28:29]
	s_mov_b32 m0, s74
	s_nop 0
	global_load_lds_dwordx4 v[166:167], off
	v_lshl_add_u64 v[166:167], v[236:237], 0, s[28:29]
	s_mov_b32 m0, s75
	s_nop 0
	global_load_lds_dwordx4 v[166:167], off
	s_waitcnt vmcnt(8)
	s_waitcnt lgkmcnt(0)
	s_barrier
	s_setprio 1
	s_waitcnt lgkmcnt(0)
	v_mfma_f32_16x16x32_bf16 v[60:63], v[128:131], v[186:189], v[60:63]
	v_mfma_f32_16x16x32_bf16 v[56:59], v[142:145], v[186:189], v[56:59]
	v_mfma_f32_16x16x32_bf16 v[44:47], v[128:131], v[194:197], v[44:47]
	v_mfma_f32_16x16x32_bf16 v[40:43], v[142:145], v[194:197], v[40:43]
	v_mfma_f32_16x16x32_bf16 v[28:31], v[128:131], v[202:205], v[28:31]
	v_mfma_f32_16x16x32_bf16 v[24:27], v[142:145], v[202:205], v[24:27]
	v_mfma_f32_16x16x32_bf16 v[12:15], v[128:131], v[210:213], v[12:15]
	v_mfma_f32_16x16x32_bf16 v[8:11], v[142:145], v[210:213], v[8:11]
	v_mfma_f32_16x16x32_bf16 v[60:63], v[132:135], v[190:193], v[60:63]
	v_mfma_f32_16x16x32_bf16 v[56:59], v[146:149], v[190:193], v[56:59]
	v_mfma_f32_16x16x32_bf16 v[44:47], v[132:135], v[198:201], v[44:47]
	v_mfma_f32_16x16x32_bf16 v[40:43], v[146:149], v[198:201], v[40:43]
	v_mfma_f32_16x16x32_bf16 v[28:31], v[132:135], v[206:209], v[28:31]
	v_mfma_f32_16x16x32_bf16 v[24:27], v[146:149], v[206:209], v[24:27]
	v_mfma_f32_16x16x32_bf16 v[12:15], v[132:135], v[214:217], v[12:15]
	v_mfma_f32_16x16x32_bf16 v[8:11], v[146:149], v[214:217], v[8:11]
	v_mfma_f32_16x16x32_bf16 v[52:55], v[150:153], v[186:189], v[52:55]
	v_mfma_f32_16x16x32_bf16 v[48:51], v[158:161], v[186:189], v[48:51]
	v_mfma_f32_16x16x32_bf16 v[36:39], v[150:153], v[194:197], v[36:39]
	v_mfma_f32_16x16x32_bf16 v[32:35], v[158:161], v[194:197], v[32:35]
	v_mfma_f32_16x16x32_bf16 v[20:23], v[150:153], v[202:205], v[20:23]
	v_mfma_f32_16x16x32_bf16 v[16:19], v[158:161], v[202:205], v[16:19]
	v_mfma_f32_16x16x32_bf16 v[4:7], v[150:153], v[210:213], v[4:7]
	v_mfma_f32_16x16x32_bf16 v[0:3], v[158:161], v[210:213], v[0:3]
	v_mfma_f32_16x16x32_bf16 v[52:55], v[154:157], v[190:193], v[52:55]
	v_mfma_f32_16x16x32_bf16 v[48:51], v[162:165], v[190:193], v[48:51]
	v_mfma_f32_16x16x32_bf16 v[36:39], v[154:157], v[198:201], v[36:39]
	v_mfma_f32_16x16x32_bf16 v[32:35], v[162:165], v[198:201], v[32:35]
	v_mfma_f32_16x16x32_bf16 v[20:23], v[154:157], v[206:209], v[20:23]
	v_mfma_f32_16x16x32_bf16 v[16:19], v[162:165], v[206:209], v[16:19]
	v_mfma_f32_16x16x32_bf16 v[4:7], v[154:157], v[214:217], v[4:7]
	v_mfma_f32_16x16x32_bf16 v[0:3], v[162:165], v[214:217], v[0:3]
	s_setprio 0
	s_barrier
	s_add_u32 s0, s0, 0x100
	s_addc_u32 s1, s1, 0
	s_add_u32 s45, s45, 0x100
	s_addc_u32 s46, s46, 0
	s_cmp_ge_i32 s47, s52
	s_mov_b32 s2, s47
	s_cbranch_scc0 .LBB0_199

.LBB0_250:
	s_add_i32 s53, s41, 2
	s_add_u32 s59, s0, 0xfffc0080
	s_addc_u32 s61, s1, -1
	s_add_i32 s79, 0, 0x10000
	s_cmp_eq_u32 s73, s41
	s_cselect_b32 s65, s55, s61
	s_cselect_b32 s64, s54, s59
	s_cselect_b32 s63, s57, s27
	s_cselect_b32 s62, s56, s3
	s_add_i32 s41, 0, 0x14000
	v_add_u32_e32 v154, s79, v148
	v_add_u32_e32 v166, s41, v148
	ds_read_b128 v[138:141], v154
	ds_read_b128 v[142:145], v154 offset:1024
	ds_read_b128 v[150:153], v154 offset:2048
	ds_read_b128 v[154:157], v154 offset:3072
	ds_read_b128 v[158:161], v166
	ds_read_b128 v[162:165], v166 offset:1024
	s_waitcnt vmcnt(0)
	ds_read_b128 v[186:189], v166 offset:2048
	ds_read_b128 v[190:193], v166 offset:3072
	v_lshl_add_u64 v[166:167], s[0:1], 0, v[134:135]
	s_add_i32 m0, s46, 0xc000
	ds_read_b128 v[194:197], v149
	ds_read_b128 v[198:201], v149 offset:1024
	ds_read_b128 v[202:205], v149 offset:2048
	ds_read_b128 v[206:209], v149 offset:3072
	ds_read_b128 v[210:213], v149 offset:4096
	ds_read_b128 v[214:217], v149 offset:5120
	ds_read_b128 v[218:221], v149 offset:6144
	ds_read_b128 v[242:245], v149 offset:7168
	global_load_lds_dwordx4 v[166:167], off
	v_lshl_add_u64 v[166:167], s[0:1], 0, v[136:137]
	s_add_i32 m0, s46, 0xe000
	s_nop 0
	global_load_lds_dwordx4 v[166:167], off
	s_waitcnt vmcnt(8)
	s_waitcnt lgkmcnt(0)
	s_barrier
	s_setprio 1
	s_waitcnt lgkmcnt(0)
	v_mfma_f32_16x16x32_bf16 v[124:127], v[138:141], v[194:197], v[124:127]
	v_mfma_f32_16x16x32_bf16 v[120:123], v[150:153], v[194:197], v[120:123]
	v_mfma_f32_16x16x32_bf16 v[108:111], v[138:141], v[202:205], v[108:111]
	v_mfma_f32_16x16x32_bf16 v[104:107], v[150:153], v[202:205], v[104:107]
	v_mfma_f32_16x16x32_bf16 v[92:95], v[138:141], v[210:213], v[92:95]
	v_mfma_f32_16x16x32_bf16 v[88:91], v[150:153], v[210:213], v[88:91]
	v_mfma_f32_16x16x32_bf16 v[76:79], v[138:141], v[218:221], v[76:79]
	v_mfma_f32_16x16x32_bf16 v[72:75], v[150:153], v[218:221], v[72:75]
	v_mfma_f32_16x16x32_bf16 v[124:127], v[142:145], v[198:201], v[124:127]
	v_mfma_f32_16x16x32_bf16 v[120:123], v[154:157], v[198:201], v[120:123]
	v_mfma_f32_16x16x32_bf16 v[108:111], v[142:145], v[206:209], v[108:111]
	v_mfma_f32_16x16x32_bf16 v[104:107], v[154:157], v[206:209], v[104:107]
	v_mfma_f32_16x16x32_bf16 v[92:95], v[142:145], v[214:217], v[92:95]
	v_mfma_f32_16x16x32_bf16 v[88:91], v[154:157], v[214:217], v[88:91]
	v_mfma_f32_16x16x32_bf16 v[76:79], v[142:145], v[242:245], v[76:79]
	v_mfma_f32_16x16x32_bf16 v[72:75], v[154:157], v[242:245], v[72:75]
	v_mfma_f32_16x16x32_bf16 v[116:119], v[158:161], v[194:197], v[116:119]
	v_mfma_f32_16x16x32_bf16 v[112:115], v[186:189], v[194:197], v[112:115]
	v_mfma_f32_16x16x32_bf16 v[100:103], v[158:161], v[202:205], v[100:103]
	v_mfma_f32_16x16x32_bf16 v[96:99], v[186:189], v[202:205], v[96:99]
	v_mfma_f32_16x16x32_bf16 v[84:87], v[158:161], v[210:213], v[84:87]
	v_mfma_f32_16x16x32_bf16 v[80:83], v[186:189], v[210:213], v[80:83]
	v_mfma_f32_16x16x32_bf16 v[68:71], v[158:161], v[218:221], v[68:71]
	v_mfma_f32_16x16x32_bf16 v[64:67], v[186:189], v[218:221], v[64:67]
	v_mfma_f32_16x16x32_bf16 v[116:119], v[162:165], v[198:201], v[116:119]
	v_mfma_f32_16x16x32_bf16 v[112:115], v[190:193], v[198:201], v[112:115]
	v_mfma_f32_16x16x32_bf16 v[100:103], v[162:165], v[206:209], v[100:103]
	v_mfma_f32_16x16x32_bf16 v[96:99], v[190:193], v[206:209], v[96:99]
	v_mfma_f32_16x16x32_bf16 v[84:87], v[162:165], v[214:217], v[84:87]
	v_mfma_f32_16x16x32_bf16 v[80:83], v[190:193], v[214:217], v[80:83]
	v_mfma_f32_16x16x32_bf16 v[68:71], v[162:165], v[242:245], v[68:71]
	v_mfma_f32_16x16x32_bf16 v[64:67], v[190:193], v[242:245], v[64:67]
	s_setprio 0
	s_barrier
	s_add_i32 s59, s79, s45
	v_lshl_add_u64 v[166:167], s[62:63], 0, v[168:169]
	s_mov_b32 m0, s59
	ds_read_b128 v[194:197], v149 offset:16384
	ds_read_b128 v[198:201], v149 offset:17408
	ds_read_b128 v[202:205], v149 offset:18432
	ds_read_b128 v[206:209], v149 offset:19456
	ds_read_b128 v[210:213], v149 offset:20480
	ds_read_b128 v[214:217], v149 offset:21504
	ds_read_b128 v[218:221], v149 offset:22528
	ds_read_b128 v[242:245], v149 offset:23552
	global_load_lds_dwordx4 v[166:167], off
	s_add_i32 m0, s59, 0x2000
	s_add_u32 vcc_lo, s62, 0x10000
	v_lshl_add_u64 v[222:223], s[62:63], 0, v[132:133]
	s_addc_u32 vcc_hi, s63, 0
	s_add_i32 s41, s41, s45
	global_load_lds_dwordx4 v[222:223], off
	v_lshl_add_u64 v[234:235], vcc, 0, v[168:169]
	s_mov_b32 m0, s41
	v_lshl_add_u64 v[236:237], s[64:65], 0, v[130:131]
	global_load_lds_dwordx4 v[234:235], off
	v_lshl_add_u64 v[234:235], vcc, 0, v[132:133]
	s_add_i32 m0, s41, 0x2000
	s_nop 0
	global_load_lds_dwordx4 v[234:235], off
	v_lshl_add_u64 v[234:235], s[64:65], 0, v[128:129]
	s_mov_b32 m0, s46
	s_nop 0
	global_load_lds_dwordx4 v[234:235], off
	s_mov_b32 m0, s47
	s_nop 0
	global_load_lds_dwordx4 v[236:237], off
	s_waitcnt vmcnt(8)
	s_waitcnt lgkmcnt(0)
	s_barrier
	s_setprio 1
	s_waitcnt lgkmcnt(0)
	v_mfma_f32_16x16x32_bf16 v[60:63], v[138:141], v[194:197], v[60:63]
	v_mfma_f32_16x16x32_bf16 v[56:59], v[150:153], v[194:197], v[56:59]
	v_mfma_f32_16x16x32_bf16 v[44:47], v[138:141], v[202:205], v[44:47]
	v_mfma_f32_16x16x32_bf16 v[40:43], v[150:153], v[202:205], v[40:43]
	v_mfma_f32_16x16x32_bf16 v[28:31], v[138:141], v[210:213], v[28:31]
	v_mfma_f32_16x16x32_bf16 v[24:27], v[150:153], v[210:213], v[24:27]
	v_mfma_f32_16x16x32_bf16 v[12:15], v[138:141], v[218:221], v[12:15]
	v_mfma_f32_16x16x32_bf16 v[8:11], v[150:153], v[218:221], v[8:11]
	v_mfma_f32_16x16x32_bf16 v[60:63], v[142:145], v[198:201], v[60:63]
	v_mfma_f32_16x16x32_bf16 v[56:59], v[154:157], v[198:201], v[56:59]
	v_mfma_f32_16x16x32_bf16 v[44:47], v[142:145], v[206:209], v[44:47]
	v_mfma_f32_16x16x32_bf16 v[40:43], v[154:157], v[206:209], v[40:43]
	v_mfma_f32_16x16x32_bf16 v[28:31], v[142:145], v[214:217], v[28:31]
	v_mfma_f32_16x16x32_bf16 v[24:27], v[154:157], v[214:217], v[24:27]
	v_mfma_f32_16x16x32_bf16 v[12:15], v[142:145], v[242:245], v[12:15]
	v_mfma_f32_16x16x32_bf16 v[8:11], v[154:157], v[242:245], v[8:11]
	v_mfma_f32_16x16x32_bf16 v[52:55], v[158:161], v[194:197], v[52:55]
	v_mfma_f32_16x16x32_bf16 v[48:51], v[186:189], v[194:197], v[48:51]
	v_mfma_f32_16x16x32_bf16 v[36:39], v[158:161], v[202:205], v[36:39]
	v_mfma_f32_16x16x32_bf16 v[32:35], v[186:189], v[202:205], v[32:35]
	v_mfma_f32_16x16x32_bf16 v[20:23], v[158:161], v[210:213], v[20:23]
	v_mfma_f32_16x16x32_bf16 v[16:19], v[186:189], v[210:213], v[16:19]
	v_mfma_f32_16x16x32_bf16 v[4:7], v[158:161], v[218:221], v[4:7]
	v_mfma_f32_16x16x32_bf16 v[0:3], v[186:189], v[218:221], v[0:3]
	v_mfma_f32_16x16x32_bf16 v[52:55], v[162:165], v[198:201], v[52:55]
	v_mfma_f32_16x16x32_bf16 v[48:51], v[190:193], v[198:201], v[48:51]
	v_mfma_f32_16x16x32_bf16 v[36:39], v[162:165], v[206:209], v[36:39]
	v_mfma_f32_16x16x32_bf16 v[32:35], v[190:193], v[206:209], v[32:35]
	v_mfma_f32_16x16x32_bf16 v[20:23], v[162:165], v[214:217], v[20:23]
	v_mfma_f32_16x16x32_bf16 v[16:19], v[190:193], v[214:217], v[16:19]
	v_mfma_f32_16x16x32_bf16 v[4:7], v[162:165], v[242:245], v[4:7]
	v_mfma_f32_16x16x32_bf16 v[0:3], v[190:193], v[242:245], v[0:3]
	s_setprio 0
	s_barrier
	s_add_i32 s41, 0, 0x18000
	s_add_i32 s59, 0, 0x1c000
	v_add_u32_e32 v154, s41, v148
	v_add_u32_e32 v174, s59, v148
	ds_read_b128 v[138:141], v154
	ds_read_b128 v[142:145], v154 offset:1024
	ds_read_b128 v[150:153], v154 offset:2048
	ds_read_b128 v[154:157], v154 offset:3072
	ds_read_b128 v[158:161], v174
	ds_read_b128 v[162:165], v174 offset:1024
	ds_read_b128 v[186:189], v174 offset:2048
	ds_read_b128 v[190:193], v174 offset:3072
	s_add_u32 s64, s64, 0x40000
	s_addc_u32 s65, s65, 0
	s_mov_b32 m0, s66
	v_lshl_add_u64 v[246:247], s[64:65], 0, v[128:129]
	ds_read_b128 v[194:197], v149 offset:32768
	ds_read_b128 v[198:201], v149 offset:33792
	ds_read_b128 v[202:205], v149 offset:34816
	ds_read_b128 v[206:209], v149 offset:35840
	ds_read_b128 v[210:213], v149 offset:36864
	ds_read_b128 v[214:217], v149 offset:37888
	ds_read_b128 v[218:221], v149 offset:38912
	ds_read_b128 v[242:245], v149 offset:39936
	global_load_lds_dwordx4 v[246:247], off
	v_lshl_add_u64 v[246:247], s[64:65], 0, v[130:131]
	s_mov_b32 m0, s67
	s_nop 0
	global_load_lds_dwordx4 v[246:247], off
	s_waitcnt vmcnt(8)
	s_waitcnt lgkmcnt(0)
	s_barrier
	s_setprio 1
	s_waitcnt lgkmcnt(0)
	v_mfma_f32_16x16x32_bf16 v[124:127], v[138:141], v[194:197], v[124:127]
	v_mfma_f32_16x16x32_bf16 v[120:123], v[150:153], v[194:197], v[120:123]
	v_mfma_f32_16x16x32_bf16 v[108:111], v[138:141], v[202:205], v[108:111]
	v_mfma_f32_16x16x32_bf16 v[104:107], v[150:153], v[202:205], v[104:107]
	v_mfma_f32_16x16x32_bf16 v[92:95], v[138:141], v[210:213], v[92:95]
	v_mfma_f32_16x16x32_bf16 v[88:91], v[150:153], v[210:213], v[88:91]
	v_mfma_f32_16x16x32_bf16 v[76:79], v[138:141], v[218:221], v[76:79]
	v_mfma_f32_16x16x32_bf16 v[72:75], v[150:153], v[218:221], v[72:75]
	v_mfma_f32_16x16x32_bf16 v[124:127], v[142:145], v[198:201], v[124:127]
	v_mfma_f32_16x16x32_bf16 v[120:123], v[154:157], v[198:201], v[120:123]
	v_mfma_f32_16x16x32_bf16 v[108:111], v[142:145], v[206:209], v[108:111]
	v_mfma_f32_16x16x32_bf16 v[104:107], v[154:157], v[206:209], v[104:107]
	v_mfma_f32_16x16x32_bf16 v[92:95], v[142:145], v[214:217], v[92:95]
	v_mfma_f32_16x16x32_bf16 v[88:91], v[154:157], v[214:217], v[88:91]
	v_mfma_f32_16x16x32_bf16 v[76:79], v[142:145], v[242:245], v[76:79]
	v_mfma_f32_16x16x32_bf16 v[72:75], v[154:157], v[242:245], v[72:75]
	v_mfma_f32_16x16x32_bf16 v[116:119], v[158:161], v[194:197], v[116:119]
	v_mfma_f32_16x16x32_bf16 v[112:115], v[186:189], v[194:197], v[112:115]
	v_mfma_f32_16x16x32_bf16 v[100:103], v[158:161], v[202:205], v[100:103]
	v_mfma_f32_16x16x32_bf16 v[96:99], v[186:189], v[202:205], v[96:99]
	v_mfma_f32_16x16x32_bf16 v[84:87], v[158:161], v[210:213], v[84:87]
	v_mfma_f32_16x16x32_bf16 v[80:83], v[186:189], v[210:213], v[80:83]
	v_mfma_f32_16x16x32_bf16 v[68:71], v[158:161], v[218:221], v[68:71]
	v_mfma_f32_16x16x32_bf16 v[64:67], v[186:189], v[218:221], v[64:67]
	v_mfma_f32_16x16x32_bf16 v[116:119], v[162:165], v[198:201], v[116:119]
	v_mfma_f32_16x16x32_bf16 v[112:115], v[190:193], v[198:201], v[112:115]
	v_mfma_f32_16x16x32_bf16 v[100:103], v[162:165], v[206:209], v[100:103]
	v_mfma_f32_16x16x32_bf16 v[96:99], v[190:193], v[206:209], v[96:99]
	v_mfma_f32_16x16x32_bf16 v[84:87], v[162:165], v[214:217], v[84:87]
	v_mfma_f32_16x16x32_bf16 v[80:83], v[190:193], v[214:217], v[80:83]
	v_mfma_f32_16x16x32_bf16 v[68:71], v[162:165], v[242:245], v[68:71]
	v_mfma_f32_16x16x32_bf16 v[64:67], v[190:193], v[242:245], v[64:67]
	s_setprio 0
	s_barrier
	s_add_i32 s41, s41, s45
	v_lshl_add_u64 v[166:167], v[166:167], 0, s[28:29]
	s_mov_b32 m0, s41
	ds_read_b128 v[194:197], v149 offset:49152
	ds_read_b128 v[198:201], v149 offset:50176
	ds_read_b128 v[202:205], v149 offset:51200
	ds_read_b128 v[206:209], v149 offset:52224
	ds_read_b128 v[210:213], v149 offset:53248
	ds_read_b128 v[214:217], v149 offset:54272
	ds_read_b128 v[218:221], v149 offset:55296
	ds_read_b128 v[242:245], v149 offset:56320
	global_load_lds_dwordx4 v[166:167], off
	s_add_i32 m0, s41, 0x2000
	s_add_u32 s62, s62, 0x10080
	v_lshl_add_u64 v[166:167], v[222:223], 0, s[28:29]
	s_addc_u32 s63, s63, 0
	s_add_i32 s41, s59, s45
	global_load_lds_dwordx4 v[166:167], off
	v_lshl_add_u64 v[166:167], s[62:63], 0, v[168:169]
	s_mov_b32 m0, s41
	s_nop 0
	global_load_lds_dwordx4 v[166:167], off
	v_lshl_add_u64 v[166:167], s[62:63], 0, v[132:133]
	s_add_i32 m0, s41, 0x2000
	s_nop 0
	global_load_lds_dwordx4 v[166:167], off
	v_lshl_add_u64 v[166:167], v[234:235], 0, s[28:29]
	s_mov_b32 m0, s71
	s_nop 0
	global_load_lds_dwordx4 v[166:167], off
	v_lshl_add_u64 v[166:167], v[236:237], 0, s[28:29]
	s_mov_b32 m0, s72
	s_nop 0
	global_load_lds_dwordx4 v[166:167], off
	s_waitcnt vmcnt(8)
	s_waitcnt lgkmcnt(0)
	s_barrier
	s_setprio 1
	s_waitcnt lgkmcnt(0)
	v_mfma_f32_16x16x32_bf16 v[60:63], v[138:141], v[194:197], v[60:63]
	v_mfma_f32_16x16x32_bf16 v[56:59], v[150:153], v[194:197], v[56:59]
	v_mfma_f32_16x16x32_bf16 v[44:47], v[138:141], v[202:205], v[44:47]
	v_mfma_f32_16x16x32_bf16 v[40:43], v[150:153], v[202:205], v[40:43]
	v_mfma_f32_16x16x32_bf16 v[28:31], v[138:141], v[210:213], v[28:31]
	v_mfma_f32_16x16x32_bf16 v[24:27], v[150:153], v[210:213], v[24:27]
	v_mfma_f32_16x16x32_bf16 v[12:15], v[138:141], v[218:221], v[12:15]
	v_mfma_f32_16x16x32_bf16 v[8:11], v[150:153], v[218:221], v[8:11]
	v_mfma_f32_16x16x32_bf16 v[60:63], v[142:145], v[198:201], v[60:63]
	v_mfma_f32_16x16x32_bf16 v[56:59], v[154:157], v[198:201], v[56:59]
	v_mfma_f32_16x16x32_bf16 v[44:47], v[142:145], v[206:209], v[44:47]
	v_mfma_f32_16x16x32_bf16 v[40:43], v[154:157], v[206:209], v[40:43]
	v_mfma_f32_16x16x32_bf16 v[28:31], v[142:145], v[214:217], v[28:31]
	v_mfma_f32_16x16x32_bf16 v[24:27], v[154:157], v[214:217], v[24:27]
	v_mfma_f32_16x16x32_bf16 v[12:15], v[142:145], v[242:245], v[12:15]
	v_mfma_f32_16x16x32_bf16 v[8:11], v[154:157], v[242:245], v[8:11]
	v_mfma_f32_16x16x32_bf16 v[52:55], v[158:161], v[194:197], v[52:55]
	v_mfma_f32_16x16x32_bf16 v[48:51], v[186:189], v[194:197], v[48:51]
	v_mfma_f32_16x16x32_bf16 v[36:39], v[158:161], v[202:205], v[36:39]
	v_mfma_f32_16x16x32_bf16 v[32:35], v[186:189], v[202:205], v[32:35]
	v_mfma_f32_16x16x32_bf16 v[20:23], v[158:161], v[210:213], v[20:23]
	v_mfma_f32_16x16x32_bf16 v[16:19], v[186:189], v[210:213], v[16:19]
	v_mfma_f32_16x16x32_bf16 v[4:7], v[158:161], v[218:221], v[4:7]
	v_mfma_f32_16x16x32_bf16 v[0:3], v[186:189], v[218:221], v[0:3]
	v_mfma_f32_16x16x32_bf16 v[52:55], v[162:165], v[198:201], v[52:55]
	v_mfma_f32_16x16x32_bf16 v[48:51], v[190:193], v[198:201], v[48:51]
	v_mfma_f32_16x16x32_bf16 v[36:39], v[162:165], v[206:209], v[36:39]
	v_mfma_f32_16x16x32_bf16 v[32:35], v[190:193], v[206:209], v[32:35]
	v_mfma_f32_16x16x32_bf16 v[20:23], v[162:165], v[214:217], v[20:23]
	v_mfma_f32_16x16x32_bf16 v[16:19], v[190:193], v[214:217], v[16:19]
	v_mfma_f32_16x16x32_bf16 v[4:7], v[162:165], v[242:245], v[4:7]
	v_mfma_f32_16x16x32_bf16 v[0:3], v[190:193], v[242:245], v[0:3]
	s_setprio 0
	s_barrier
	s_add_u32 s0, s0, 0x100
	s_addc_u32 s1, s1, 0
	s_add_u32 s3, s3, 0x100
	s_addc_u32 s27, s27, 0
	s_cmp_ge_i32 s53, s68
	s_mov_b32 s41, s53
	s_cbranch_scc0 .LBB0_250

.LBB0_317:
	s_add_i32 s59, s20, 2
	s_add_u32 s21, s2, 0xfffc0080
	s_addc_u32 s22, s3, -1
	s_add_i32 s65, 0, 0x10000
	s_cmp_eq_u32 s74, s20
	s_cselect_b32 s23, s1, s22
	s_cselect_b32 s22, s0, s21
	s_cselect_b32 s21, s61, s57
	s_cselect_b32 s20, s60, s55
	s_add_i32 s67, 0, 0x14000
	v_add_u32_e32 v154, s65, v144
	v_add_u32_e32 v166, s67, v144
	ds_read_b128 v[138:141], v154
	ds_read_b128 v[146:149], v154 offset:1024
	ds_read_b128 v[150:153], v154 offset:2048
	ds_read_b128 v[154:157], v154 offset:3072
	ds_read_b128 v[158:161], v166
	ds_read_b128 v[162:165], v166 offset:1024
	s_waitcnt vmcnt(0)
	ds_read_b128 v[186:189], v166 offset:2048
	ds_read_b128 v[190:193], v166 offset:3072
	v_lshl_add_u64 v[166:167], s[2:3], 0, v[134:135]
	s_add_i32 m0, s42, 0xc000
	ds_read_b128 v[194:197], v145
	ds_read_b128 v[198:201], v145 offset:1024
	ds_read_b128 v[202:205], v145 offset:2048
	ds_read_b128 v[206:209], v145 offset:3072
	ds_read_b128 v[210:213], v145 offset:4096
	ds_read_b128 v[214:217], v145 offset:5120
	ds_read_b128 v[218:221], v145 offset:6144
	ds_read_b128 v[242:245], v145 offset:7168
	global_load_lds_dwordx4 v[166:167], off
	v_lshl_add_u64 v[166:167], s[2:3], 0, v[136:137]
	s_add_i32 m0, s42, 0xe000
	s_nop 0
	global_load_lds_dwordx4 v[166:167], off
	s_waitcnt vmcnt(8)
	s_waitcnt lgkmcnt(0)
	s_barrier
	s_setprio 1
	s_waitcnt lgkmcnt(0)
	v_mfma_f32_16x16x32_bf16 v[124:127], v[138:141], v[194:197], v[124:127]
	v_mfma_f32_16x16x32_bf16 v[120:123], v[150:153], v[194:197], v[120:123]
	v_mfma_f32_16x16x32_bf16 v[108:111], v[138:141], v[202:205], v[108:111]
	v_mfma_f32_16x16x32_bf16 v[104:107], v[150:153], v[202:205], v[104:107]
	v_mfma_f32_16x16x32_bf16 v[92:95], v[138:141], v[210:213], v[92:95]
	v_mfma_f32_16x16x32_bf16 v[88:91], v[150:153], v[210:213], v[88:91]
	v_mfma_f32_16x16x32_bf16 v[76:79], v[138:141], v[218:221], v[76:79]
	v_mfma_f32_16x16x32_bf16 v[72:75], v[150:153], v[218:221], v[72:75]
	v_mfma_f32_16x16x32_bf16 v[124:127], v[146:149], v[198:201], v[124:127]
	v_mfma_f32_16x16x32_bf16 v[120:123], v[154:157], v[198:201], v[120:123]
	v_mfma_f32_16x16x32_bf16 v[108:111], v[146:149], v[206:209], v[108:111]
	v_mfma_f32_16x16x32_bf16 v[104:107], v[154:157], v[206:209], v[104:107]
	v_mfma_f32_16x16x32_bf16 v[92:95], v[146:149], v[214:217], v[92:95]
	v_mfma_f32_16x16x32_bf16 v[88:91], v[154:157], v[214:217], v[88:91]
	v_mfma_f32_16x16x32_bf16 v[76:79], v[146:149], v[242:245], v[76:79]
	v_mfma_f32_16x16x32_bf16 v[72:75], v[154:157], v[242:245], v[72:75]
	v_mfma_f32_16x16x32_bf16 v[116:119], v[158:161], v[194:197], v[116:119]
	v_mfma_f32_16x16x32_bf16 v[112:115], v[186:189], v[194:197], v[112:115]
	v_mfma_f32_16x16x32_bf16 v[100:103], v[158:161], v[202:205], v[100:103]
	v_mfma_f32_16x16x32_bf16 v[96:99], v[186:189], v[202:205], v[96:99]
	v_mfma_f32_16x16x32_bf16 v[84:87], v[158:161], v[210:213], v[84:87]
	v_mfma_f32_16x16x32_bf16 v[80:83], v[186:189], v[210:213], v[80:83]
	v_mfma_f32_16x16x32_bf16 v[68:71], v[158:161], v[218:221], v[68:71]
	v_mfma_f32_16x16x32_bf16 v[64:67], v[186:189], v[218:221], v[64:67]
	v_mfma_f32_16x16x32_bf16 v[116:119], v[162:165], v[198:201], v[116:119]
	v_mfma_f32_16x16x32_bf16 v[112:115], v[190:193], v[198:201], v[112:115]
	v_mfma_f32_16x16x32_bf16 v[100:103], v[162:165], v[206:209], v[100:103]
	v_mfma_f32_16x16x32_bf16 v[96:99], v[190:193], v[206:209], v[96:99]
	v_mfma_f32_16x16x32_bf16 v[84:87], v[162:165], v[214:217], v[84:87]
	v_mfma_f32_16x16x32_bf16 v[80:83], v[190:193], v[214:217], v[80:83]
	v_mfma_f32_16x16x32_bf16 v[68:71], v[162:165], v[242:245], v[68:71]
	v_mfma_f32_16x16x32_bf16 v[64:67], v[190:193], v[242:245], v[64:67]
	s_setprio 0
	s_barrier
	s_add_i32 s65, s65, s34
	v_lshl_add_u64 v[166:167], s[20:21], 0, v[168:169]
	s_mov_b32 m0, s65
	ds_read_b128 v[194:197], v145 offset:16384
	ds_read_b128 v[198:201], v145 offset:17408
	ds_read_b128 v[202:205], v145 offset:18432
	ds_read_b128 v[206:209], v145 offset:19456
	ds_read_b128 v[210:213], v145 offset:20480
	ds_read_b128 v[214:217], v145 offset:21504
	ds_read_b128 v[218:221], v145 offset:22528
	ds_read_b128 v[242:245], v145 offset:23552
	global_load_lds_dwordx4 v[166:167], off
	s_add_i32 m0, s65, 0x2000
	s_add_u32 vcc_lo, s20, 0x40000
	v_lshl_add_u64 v[222:223], s[20:21], 0, v[132:133]
	s_addc_u32 vcc_hi, s21, 0
	s_add_i32 s65, s67, s34
	global_load_lds_dwordx4 v[222:223], off
	v_lshl_add_u64 v[234:235], vcc, 0, v[168:169]
	s_mov_b32 m0, s65
	v_lshl_add_u64 v[236:237], s[22:23], 0, v[130:131]
	global_load_lds_dwordx4 v[234:235], off
	v_lshl_add_u64 v[234:235], vcc, 0, v[132:133]
	s_add_i32 m0, s65, 0x2000
	s_nop 0
	global_load_lds_dwordx4 v[234:235], off
	v_lshl_add_u64 v[234:235], s[22:23], 0, v[128:129]
	s_mov_b32 m0, s42
	s_nop 0
	global_load_lds_dwordx4 v[234:235], off
	s_mov_b32 m0, s43
	s_nop 0
	global_load_lds_dwordx4 v[236:237], off
	s_waitcnt vmcnt(8)
	s_waitcnt lgkmcnt(0)
	s_barrier
	s_setprio 1
	s_waitcnt lgkmcnt(0)
	v_mfma_f32_16x16x32_bf16 v[60:63], v[138:141], v[194:197], v[60:63]
	v_mfma_f32_16x16x32_bf16 v[56:59], v[150:153], v[194:197], v[56:59]
	v_mfma_f32_16x16x32_bf16 v[44:47], v[138:141], v[202:205], v[44:47]
	v_mfma_f32_16x16x32_bf16 v[40:43], v[150:153], v[202:205], v[40:43]
	v_mfma_f32_16x16x32_bf16 v[28:31], v[138:141], v[210:213], v[28:31]
	v_mfma_f32_16x16x32_bf16 v[24:27], v[150:153], v[210:213], v[24:27]
	v_mfma_f32_16x16x32_bf16 v[12:15], v[138:141], v[218:221], v[12:15]
	v_mfma_f32_16x16x32_bf16 v[8:11], v[150:153], v[218:221], v[8:11]
	v_mfma_f32_16x16x32_bf16 v[60:63], v[146:149], v[198:201], v[60:63]
	v_mfma_f32_16x16x32_bf16 v[56:59], v[154:157], v[198:201], v[56:59]
	v_mfma_f32_16x16x32_bf16 v[44:47], v[146:149], v[206:209], v[44:47]
	v_mfma_f32_16x16x32_bf16 v[40:43], v[154:157], v[206:209], v[40:43]
	v_mfma_f32_16x16x32_bf16 v[28:31], v[146:149], v[214:217], v[28:31]
	v_mfma_f32_16x16x32_bf16 v[24:27], v[154:157], v[214:217], v[24:27]
	v_mfma_f32_16x16x32_bf16 v[12:15], v[146:149], v[242:245], v[12:15]
	v_mfma_f32_16x16x32_bf16 v[8:11], v[154:157], v[242:245], v[8:11]
	v_mfma_f32_16x16x32_bf16 v[52:55], v[158:161], v[194:197], v[52:55]
	v_mfma_f32_16x16x32_bf16 v[48:51], v[186:189], v[194:197], v[48:51]
	v_mfma_f32_16x16x32_bf16 v[36:39], v[158:161], v[202:205], v[36:39]
	v_mfma_f32_16x16x32_bf16 v[32:35], v[186:189], v[202:205], v[32:35]
	v_mfma_f32_16x16x32_bf16 v[20:23], v[158:161], v[210:213], v[20:23]
	v_mfma_f32_16x16x32_bf16 v[16:19], v[186:189], v[210:213], v[16:19]
	v_mfma_f32_16x16x32_bf16 v[4:7], v[158:161], v[218:221], v[4:7]
	v_mfma_f32_16x16x32_bf16 v[0:3], v[186:189], v[218:221], v[0:3]
	v_mfma_f32_16x16x32_bf16 v[52:55], v[162:165], v[198:201], v[52:55]
	v_mfma_f32_16x16x32_bf16 v[48:51], v[190:193], v[198:201], v[48:51]
	v_mfma_f32_16x16x32_bf16 v[36:39], v[162:165], v[206:209], v[36:39]
	v_mfma_f32_16x16x32_bf16 v[32:35], v[190:193], v[206:209], v[32:35]
	v_mfma_f32_16x16x32_bf16 v[20:23], v[162:165], v[214:217], v[20:23]
	v_mfma_f32_16x16x32_bf16 v[16:19], v[190:193], v[214:217], v[16:19]
	v_mfma_f32_16x16x32_bf16 v[4:7], v[162:165], v[242:245], v[4:7]
	v_mfma_f32_16x16x32_bf16 v[0:3], v[190:193], v[242:245], v[0:3]
	s_setprio 0
	s_barrier
	s_add_i32 s65, 0, 0x18000
	s_add_i32 s67, 0, 0x1c000
	v_add_u32_e32 v154, s65, v144
	v_add_u32_e32 v174, s67, v144
	ds_read_b128 v[138:141], v154
	ds_read_b128 v[146:149], v154 offset:1024
	ds_read_b128 v[150:153], v154 offset:2048
	ds_read_b128 v[154:157], v154 offset:3072
	ds_read_b128 v[158:161], v174
	ds_read_b128 v[162:165], v174 offset:1024
	ds_read_b128 v[186:189], v174 offset:2048
	ds_read_b128 v[190:193], v174 offset:3072
	s_add_u32 s22, s22, 0x40000
	s_addc_u32 s23, s23, 0
	s_mov_b32 m0, s46
	v_lshl_add_u64 v[246:247], s[22:23], 0, v[128:129]
	ds_read_b128 v[194:197], v145 offset:32768
	ds_read_b128 v[198:201], v145 offset:33792
	ds_read_b128 v[202:205], v145 offset:34816
	ds_read_b128 v[206:209], v145 offset:35840
	ds_read_b128 v[210:213], v145 offset:36864
	ds_read_b128 v[214:217], v145 offset:37888
	ds_read_b128 v[218:221], v145 offset:38912
	ds_read_b128 v[242:245], v145 offset:39936
	global_load_lds_dwordx4 v[246:247], off
	v_lshl_add_u64 v[246:247], s[22:23], 0, v[130:131]
	s_mov_b32 m0, s47
	s_nop 0
	global_load_lds_dwordx4 v[246:247], off
	s_waitcnt vmcnt(8)
	s_waitcnt lgkmcnt(0)
	s_barrier
	s_setprio 1
	s_waitcnt lgkmcnt(0)
	v_mfma_f32_16x16x32_bf16 v[124:127], v[138:141], v[194:197], v[124:127]
	v_mfma_f32_16x16x32_bf16 v[120:123], v[150:153], v[194:197], v[120:123]
	v_mfma_f32_16x16x32_bf16 v[108:111], v[138:141], v[202:205], v[108:111]
	v_mfma_f32_16x16x32_bf16 v[104:107], v[150:153], v[202:205], v[104:107]
	v_mfma_f32_16x16x32_bf16 v[92:95], v[138:141], v[210:213], v[92:95]
	v_mfma_f32_16x16x32_bf16 v[88:91], v[150:153], v[210:213], v[88:91]
	v_mfma_f32_16x16x32_bf16 v[76:79], v[138:141], v[218:221], v[76:79]
	v_mfma_f32_16x16x32_bf16 v[72:75], v[150:153], v[218:221], v[72:75]
	v_mfma_f32_16x16x32_bf16 v[124:127], v[146:149], v[198:201], v[124:127]
	v_mfma_f32_16x16x32_bf16 v[120:123], v[154:157], v[198:201], v[120:123]
	v_mfma_f32_16x16x32_bf16 v[108:111], v[146:149], v[206:209], v[108:111]
	v_mfma_f32_16x16x32_bf16 v[104:107], v[154:157], v[206:209], v[104:107]
	v_mfma_f32_16x16x32_bf16 v[92:95], v[146:149], v[214:217], v[92:95]
	v_mfma_f32_16x16x32_bf16 v[88:91], v[154:157], v[214:217], v[88:91]
	v_mfma_f32_16x16x32_bf16 v[76:79], v[146:149], v[242:245], v[76:79]
	v_mfma_f32_16x16x32_bf16 v[72:75], v[154:157], v[242:245], v[72:75]
	v_mfma_f32_16x16x32_bf16 v[116:119], v[158:161], v[194:197], v[116:119]
	v_mfma_f32_16x16x32_bf16 v[112:115], v[186:189], v[194:197], v[112:115]
	v_mfma_f32_16x16x32_bf16 v[100:103], v[158:161], v[202:205], v[100:103]
	v_mfma_f32_16x16x32_bf16 v[96:99], v[186:189], v[202:205], v[96:99]
	v_mfma_f32_16x16x32_bf16 v[84:87], v[158:161], v[210:213], v[84:87]
	v_mfma_f32_16x16x32_bf16 v[80:83], v[186:189], v[210:213], v[80:83]
	v_mfma_f32_16x16x32_bf16 v[68:71], v[158:161], v[218:221], v[68:71]
	v_mfma_f32_16x16x32_bf16 v[64:67], v[186:189], v[218:221], v[64:67]
	v_mfma_f32_16x16x32_bf16 v[116:119], v[162:165], v[198:201], v[116:119]
	v_mfma_f32_16x16x32_bf16 v[112:115], v[190:193], v[198:201], v[112:115]
	v_mfma_f32_16x16x32_bf16 v[100:103], v[162:165], v[206:209], v[100:103]
	v_mfma_f32_16x16x32_bf16 v[96:99], v[190:193], v[206:209], v[96:99]
	v_mfma_f32_16x16x32_bf16 v[84:87], v[162:165], v[214:217], v[84:87]
	v_mfma_f32_16x16x32_bf16 v[80:83], v[190:193], v[214:217], v[80:83]
	v_mfma_f32_16x16x32_bf16 v[68:71], v[162:165], v[242:245], v[68:71]
	v_mfma_f32_16x16x32_bf16 v[64:67], v[190:193], v[242:245], v[64:67]
	s_setprio 0
	s_barrier
	s_add_i32 s22, s65, s34
	v_lshl_add_u64 v[166:167], v[166:167], 0, s[28:29]
	s_mov_b32 m0, s22
	ds_read_b128 v[194:197], v145 offset:49152
	ds_read_b128 v[198:201], v145 offset:50176
	ds_read_b128 v[202:205], v145 offset:51200
	ds_read_b128 v[206:209], v145 offset:52224
	ds_read_b128 v[210:213], v145 offset:53248
	ds_read_b128 v[214:217], v145 offset:54272
	ds_read_b128 v[218:221], v145 offset:55296
	ds_read_b128 v[242:245], v145 offset:56320
	global_load_lds_dwordx4 v[166:167], off
	s_add_i32 m0, s22, 0x2000
	s_add_u32 s20, s20, 0x40080
	v_lshl_add_u64 v[166:167], v[222:223], 0, s[28:29]
	s_addc_u32 s21, s21, 0
	s_add_i32 s22, s67, s34
	global_load_lds_dwordx4 v[166:167], off
	v_lshl_add_u64 v[166:167], s[20:21], 0, v[168:169]
	s_mov_b32 m0, s22
	s_nop 0
	global_load_lds_dwordx4 v[166:167], off
	v_lshl_add_u64 v[166:167], s[20:21], 0, v[132:133]
	s_add_i32 m0, s22, 0x2000
	s_nop 0
	global_load_lds_dwordx4 v[166:167], off
	v_lshl_add_u64 v[166:167], v[234:235], 0, s[28:29]
	s_mov_b32 m0, s72
	s_nop 0
	global_load_lds_dwordx4 v[166:167], off
	v_lshl_add_u64 v[166:167], v[236:237], 0, s[28:29]
	s_mov_b32 m0, s73
	s_nop 0
	global_load_lds_dwordx4 v[166:167], off
	s_waitcnt vmcnt(8)
	s_waitcnt lgkmcnt(0)
	s_barrier
	s_setprio 1
	s_waitcnt lgkmcnt(0)
	v_mfma_f32_16x16x32_bf16 v[60:63], v[138:141], v[194:197], v[60:63]
	v_mfma_f32_16x16x32_bf16 v[56:59], v[150:153], v[194:197], v[56:59]
	v_mfma_f32_16x16x32_bf16 v[44:47], v[138:141], v[202:205], v[44:47]
	v_mfma_f32_16x16x32_bf16 v[40:43], v[150:153], v[202:205], v[40:43]
	v_mfma_f32_16x16x32_bf16 v[28:31], v[138:141], v[210:213], v[28:31]
	v_mfma_f32_16x16x32_bf16 v[24:27], v[150:153], v[210:213], v[24:27]
	v_mfma_f32_16x16x32_bf16 v[12:15], v[138:141], v[218:221], v[12:15]
	v_mfma_f32_16x16x32_bf16 v[8:11], v[150:153], v[218:221], v[8:11]
	v_mfma_f32_16x16x32_bf16 v[60:63], v[146:149], v[198:201], v[60:63]
	v_mfma_f32_16x16x32_bf16 v[56:59], v[154:157], v[198:201], v[56:59]
	v_mfma_f32_16x16x32_bf16 v[44:47], v[146:149], v[206:209], v[44:47]
	v_mfma_f32_16x16x32_bf16 v[40:43], v[154:157], v[206:209], v[40:43]
	v_mfma_f32_16x16x32_bf16 v[28:31], v[146:149], v[214:217], v[28:31]
	v_mfma_f32_16x16x32_bf16 v[24:27], v[154:157], v[214:217], v[24:27]
	v_mfma_f32_16x16x32_bf16 v[12:15], v[146:149], v[242:245], v[12:15]
	v_mfma_f32_16x16x32_bf16 v[8:11], v[154:157], v[242:245], v[8:11]
	v_mfma_f32_16x16x32_bf16 v[52:55], v[158:161], v[194:197], v[52:55]
	v_mfma_f32_16x16x32_bf16 v[48:51], v[186:189], v[194:197], v[48:51]
	v_mfma_f32_16x16x32_bf16 v[36:39], v[158:161], v[202:205], v[36:39]
	v_mfma_f32_16x16x32_bf16 v[32:35], v[186:189], v[202:205], v[32:35]
	v_mfma_f32_16x16x32_bf16 v[20:23], v[158:161], v[210:213], v[20:23]
	v_mfma_f32_16x16x32_bf16 v[16:19], v[186:189], v[210:213], v[16:19]
	v_mfma_f32_16x16x32_bf16 v[4:7], v[158:161], v[218:221], v[4:7]
	v_mfma_f32_16x16x32_bf16 v[0:3], v[186:189], v[218:221], v[0:3]
	v_mfma_f32_16x16x32_bf16 v[52:55], v[162:165], v[198:201], v[52:55]
	v_mfma_f32_16x16x32_bf16 v[48:51], v[190:193], v[198:201], v[48:51]
	v_mfma_f32_16x16x32_bf16 v[36:39], v[162:165], v[206:209], v[36:39]
	v_mfma_f32_16x16x32_bf16 v[32:35], v[190:193], v[206:209], v[32:35]
	v_mfma_f32_16x16x32_bf16 v[20:23], v[162:165], v[214:217], v[20:23]
	v_mfma_f32_16x16x32_bf16 v[16:19], v[190:193], v[214:217], v[16:19]
	v_mfma_f32_16x16x32_bf16 v[4:7], v[162:165], v[242:245], v[4:7]
	v_mfma_f32_16x16x32_bf16 v[0:3], v[190:193], v[242:245], v[0:3]
	s_setprio 0
	s_barrier
	s_add_u32 s2, s2, 0x100
	s_addc_u32 s3, s3, 0
	s_add_u32 s55, s55, 0x100
	s_addc_u32 s57, s57, 0
	s_cmp_ge_i32 s59, s69
	s_mov_b32 s20, s59
	s_cbranch_scc0 .LBB0_317

.LBB0_378:
	s_add_i32 s65, s22, 2
	s_add_u32 s23, s20, 0xfffc0080
	s_addc_u32 s26, s21, -1
	s_add_i32 s79, 0, 0x10000
	s_cmp_eq_u32 s76, s22
	s_cselect_b32 s27, s1, s26
	s_cselect_b32 s26, s40, s23
	s_cselect_b32 s23, s41, s63
	s_cselect_b32 s22, s44, s45
	s_add_i32 s48, 0, 0x14000
	v_add_u32_e32 v88, s79, v211
	v_add_u32_e32 v108, s48, v211
	ds_read_b128 v[72:75], v88
	ds_read_b128 v[76:79], v88 offset:1024
	ds_read_b128 v[84:87], v88 offset:2048
	ds_read_b128 v[88:91], v88 offset:3072
	ds_read_b128 v[96:99], v108
	ds_read_b128 v[100:103], v108 offset:1024
	ds_read_b128 v[104:107], v108 offset:2048
	ds_read_b128 v[108:111], v108 offset:3072
	v_lshl_add_u64 v[208:209], s[20:21], 0, v[192:193]
	s_add_i32 m0, s3, 0xc000
	ds_read_b128 v[160:163], v212
	ds_read_b128 v[164:167], v212 offset:1024
	ds_read_b128 v[196:199], v212 offset:2048
	ds_read_b128 v[200:203], v212 offset:3072
	ds_read_b128 v[204:207], v212 offset:4096
	ds_read_b128 v[214:217], v212 offset:5120
	ds_read_b128 v[218:221], v212 offset:6144
	ds_read_b128 v[242:245], v212 offset:7168
	global_load_lds_dwordx4 v[208:209], off
	v_lshl_add_u64 v[208:209], s[20:21], 0, v[194:195]
	s_add_i32 m0, s3, 0xe000
	s_nop 0
	global_load_lds_dwordx4 v[208:209], off
	s_waitcnt vmcnt(8)
	s_waitcnt lgkmcnt(0)
	s_barrier
	s_setprio 1
	s_waitcnt lgkmcnt(0)
	v_mfma_f32_16x16x32_bf16 v[156:159], v[72:75], v[160:163], v[156:159]
	v_mfma_f32_16x16x32_bf16 v[152:155], v[84:87], v[160:163], v[152:155]
	v_mfma_f32_16x16x32_bf16 v[140:143], v[72:75], v[196:199], v[140:143]
	v_mfma_f32_16x16x32_bf16 v[136:139], v[84:87], v[196:199], v[136:139]
	v_mfma_f32_16x16x32_bf16 v[124:127], v[72:75], v[204:207], v[124:127]
	v_mfma_f32_16x16x32_bf16 v[120:123], v[84:87], v[204:207], v[120:123]
	v_mfma_f32_16x16x32_bf16 v[92:95], v[72:75], v[218:221], v[92:95]
	v_mfma_f32_16x16x32_bf16 v[80:83], v[84:87], v[218:221], v[80:83]
	v_mfma_f32_16x16x32_bf16 v[156:159], v[76:79], v[164:167], v[156:159]
	v_mfma_f32_16x16x32_bf16 v[152:155], v[88:91], v[164:167], v[152:155]
	v_mfma_f32_16x16x32_bf16 v[140:143], v[76:79], v[200:203], v[140:143]
	v_mfma_f32_16x16x32_bf16 v[136:139], v[88:91], v[200:203], v[136:139]
	v_mfma_f32_16x16x32_bf16 v[124:127], v[76:79], v[214:217], v[124:127]
	v_mfma_f32_16x16x32_bf16 v[120:123], v[88:91], v[214:217], v[120:123]
	v_mfma_f32_16x16x32_bf16 v[92:95], v[76:79], v[242:245], v[92:95]
	v_mfma_f32_16x16x32_bf16 v[80:83], v[88:91], v[242:245], v[80:83]
	v_mfma_f32_16x16x32_bf16 v[148:151], v[96:99], v[160:163], v[148:151]
	v_mfma_f32_16x16x32_bf16 v[144:147], v[104:107], v[160:163], v[144:147]
	v_mfma_f32_16x16x32_bf16 v[132:135], v[96:99], v[196:199], v[132:135]
	v_mfma_f32_16x16x32_bf16 v[128:131], v[104:107], v[196:199], v[128:131]
	v_mfma_f32_16x16x32_bf16 v[116:119], v[96:99], v[204:207], v[116:119]
	v_mfma_f32_16x16x32_bf16 v[112:115], v[104:107], v[204:207], v[112:115]
	v_mfma_f32_16x16x32_bf16 v[68:71], v[96:99], v[218:221], v[68:71]
	v_mfma_f32_16x16x32_bf16 v[64:67], v[104:107], v[218:221], v[64:67]
	v_mfma_f32_16x16x32_bf16 v[148:151], v[100:103], v[164:167], v[148:151]
	v_mfma_f32_16x16x32_bf16 v[144:147], v[108:111], v[164:167], v[144:147]
	v_mfma_f32_16x16x32_bf16 v[132:135], v[100:103], v[200:203], v[132:135]
	v_mfma_f32_16x16x32_bf16 v[128:131], v[108:111], v[200:203], v[128:131]
	v_mfma_f32_16x16x32_bf16 v[116:119], v[100:103], v[214:217], v[116:119]
	v_mfma_f32_16x16x32_bf16 v[112:115], v[108:111], v[214:217], v[112:115]
	v_mfma_f32_16x16x32_bf16 v[68:71], v[100:103], v[242:245], v[68:71]
	v_mfma_f32_16x16x32_bf16 v[64:67], v[108:111], v[242:245], v[64:67]
	s_setprio 0
	s_barrier
	s_add_i32 s49, s79, s43
	v_lshl_add_u64 v[208:209], s[22:23], 0, v[168:169]
	s_mov_b32 m0, s49
	ds_read_b128 v[160:163], v212 offset:16384
	ds_read_b128 v[164:167], v212 offset:17408
	ds_read_b128 v[196:199], v212 offset:18432
	ds_read_b128 v[200:203], v212 offset:19456
	ds_read_b128 v[204:207], v212 offset:20480
	ds_read_b128 v[214:217], v212 offset:21504
	ds_read_b128 v[218:221], v212 offset:22528
	ds_read_b128 v[242:245], v212 offset:23552
	global_load_lds_dwordx4 v[208:209], off
	s_add_i32 m0, s49, 0x2000
	s_add_u32 vcc_lo, s22, 0x40000
	v_lshl_add_u64 v[222:223], s[22:23], 0, v[190:191]
	s_addc_u32 vcc_hi, s23, 0
	s_add_i32 s48, s48, s43
	global_load_lds_dwordx4 v[222:223], off
	v_lshl_add_u64 v[234:235], vcc, 0, v[168:169]
	s_mov_b32 m0, s48
	v_lshl_add_u64 v[236:237], s[26:27], 0, v[188:189]
	global_load_lds_dwordx4 v[234:235], off
	v_lshl_add_u64 v[234:235], vcc, 0, v[190:191]
	s_add_i32 m0, s48, 0x2000
	s_nop 0
	global_load_lds_dwordx4 v[234:235], off
	v_lshl_add_u64 v[234:235], s[26:27], 0, v[186:187]
	s_mov_b32 m0, s3
	s_nop 0
	global_load_lds_dwordx4 v[234:235], off
	s_mov_b32 m0, s46
	s_nop 0
	global_load_lds_dwordx4 v[236:237], off
	s_waitcnt vmcnt(8)
	s_waitcnt lgkmcnt(0)
	s_barrier
	s_setprio 1
	s_waitcnt lgkmcnt(0)
	v_mfma_f32_16x16x32_bf16 v[60:63], v[72:75], v[160:163], v[60:63]
	v_mfma_f32_16x16x32_bf16 v[56:59], v[84:87], v[160:163], v[56:59]
	v_mfma_f32_16x16x32_bf16 v[44:47], v[72:75], v[196:199], v[44:47]
	v_mfma_f32_16x16x32_bf16 v[40:43], v[84:87], v[196:199], v[40:43]
	v_mfma_f32_16x16x32_bf16 v[28:31], v[72:75], v[204:207], v[28:31]
	v_mfma_f32_16x16x32_bf16 v[24:27], v[84:87], v[204:207], v[24:27]
	v_mfma_f32_16x16x32_bf16 v[12:15], v[72:75], v[218:221], v[12:15]
	v_mfma_f32_16x16x32_bf16 v[8:11], v[84:87], v[218:221], v[8:11]
	v_mfma_f32_16x16x32_bf16 v[60:63], v[76:79], v[164:167], v[60:63]
	v_mfma_f32_16x16x32_bf16 v[56:59], v[88:91], v[164:167], v[56:59]
	v_mfma_f32_16x16x32_bf16 v[44:47], v[76:79], v[200:203], v[44:47]
	v_mfma_f32_16x16x32_bf16 v[40:43], v[88:91], v[200:203], v[40:43]
	v_mfma_f32_16x16x32_bf16 v[28:31], v[76:79], v[214:217], v[28:31]
	v_mfma_f32_16x16x32_bf16 v[24:27], v[88:91], v[214:217], v[24:27]
	v_mfma_f32_16x16x32_bf16 v[12:15], v[76:79], v[242:245], v[12:15]
	v_mfma_f32_16x16x32_bf16 v[8:11], v[88:91], v[242:245], v[8:11]
	v_mfma_f32_16x16x32_bf16 v[52:55], v[96:99], v[160:163], v[52:55]
	v_mfma_f32_16x16x32_bf16 v[48:51], v[104:107], v[160:163], v[48:51]
	v_mfma_f32_16x16x32_bf16 v[36:39], v[96:99], v[196:199], v[36:39]
	v_mfma_f32_16x16x32_bf16 v[32:35], v[104:107], v[196:199], v[32:35]
	v_mfma_f32_16x16x32_bf16 v[20:23], v[96:99], v[204:207], v[20:23]
	v_mfma_f32_16x16x32_bf16 v[16:19], v[104:107], v[204:207], v[16:19]
	v_mfma_f32_16x16x32_bf16 v[4:7], v[96:99], v[218:221], v[4:7]
	v_mfma_f32_16x16x32_bf16 v[0:3], v[104:107], v[218:221], v[0:3]
	v_mfma_f32_16x16x32_bf16 v[52:55], v[100:103], v[164:167], v[52:55]
	v_mfma_f32_16x16x32_bf16 v[48:51], v[108:111], v[164:167], v[48:51]
	v_mfma_f32_16x16x32_bf16 v[36:39], v[100:103], v[200:203], v[36:39]
	v_mfma_f32_16x16x32_bf16 v[32:35], v[108:111], v[200:203], v[32:35]
	v_mfma_f32_16x16x32_bf16 v[20:23], v[100:103], v[214:217], v[20:23]
	v_mfma_f32_16x16x32_bf16 v[16:19], v[108:111], v[214:217], v[16:19]
	v_mfma_f32_16x16x32_bf16 v[4:7], v[100:103], v[242:245], v[4:7]
	v_mfma_f32_16x16x32_bf16 v[0:3], v[108:111], v[242:245], v[0:3]
	s_setprio 0
	s_barrier
	s_add_i32 s48, 0, 0x18000
	s_add_i32 s49, 0, 0x1c000
	v_add_u32_e32 v88, s48, v211
	v_add_u32_e32 v108, s49, v211
	ds_read_b128 v[72:75], v88
	ds_read_b128 v[76:79], v88 offset:1024
	ds_read_b128 v[84:87], v88 offset:2048
	ds_read_b128 v[88:91], v88 offset:3072
	ds_read_b128 v[96:99], v108
	ds_read_b128 v[100:103], v108 offset:1024
	ds_read_b128 v[104:107], v108 offset:2048
	ds_read_b128 v[108:111], v108 offset:3072
	s_add_u32 s26, s26, 0x40000
	s_addc_u32 s27, s27, 0
	s_mov_b32 m0, s47
	v_lshl_add_u64 v[246:247], s[26:27], 0, v[186:187]
	ds_read_b128 v[160:163], v212 offset:32768
	ds_read_b128 v[164:167], v212 offset:33792
	ds_read_b128 v[196:199], v212 offset:34816
	ds_read_b128 v[200:203], v212 offset:35840
	ds_read_b128 v[204:207], v212 offset:36864
	ds_read_b128 v[214:217], v212 offset:37888
	ds_read_b128 v[218:221], v212 offset:38912
	ds_read_b128 v[242:245], v212 offset:39936
	global_load_lds_dwordx4 v[246:247], off
	v_lshl_add_u64 v[246:247], s[26:27], 0, v[188:189]
	s_mov_b32 m0, s70
	s_nop 0
	global_load_lds_dwordx4 v[246:247], off
	s_waitcnt vmcnt(8)
	s_waitcnt lgkmcnt(0)
	s_barrier
	s_setprio 1
	s_waitcnt lgkmcnt(0)
	v_mfma_f32_16x16x32_bf16 v[156:159], v[72:75], v[160:163], v[156:159]
	v_mfma_f32_16x16x32_bf16 v[152:155], v[84:87], v[160:163], v[152:155]
	v_mfma_f32_16x16x32_bf16 v[140:143], v[72:75], v[196:199], v[140:143]
	v_mfma_f32_16x16x32_bf16 v[136:139], v[84:87], v[196:199], v[136:139]
	v_mfma_f32_16x16x32_bf16 v[124:127], v[72:75], v[204:207], v[124:127]
	v_mfma_f32_16x16x32_bf16 v[120:123], v[84:87], v[204:207], v[120:123]
	v_mfma_f32_16x16x32_bf16 v[92:95], v[72:75], v[218:221], v[92:95]
	v_mfma_f32_16x16x32_bf16 v[80:83], v[84:87], v[218:221], v[80:83]
	v_mfma_f32_16x16x32_bf16 v[156:159], v[76:79], v[164:167], v[156:159]
	v_mfma_f32_16x16x32_bf16 v[152:155], v[88:91], v[164:167], v[152:155]
	v_mfma_f32_16x16x32_bf16 v[140:143], v[76:79], v[200:203], v[140:143]
	v_mfma_f32_16x16x32_bf16 v[136:139], v[88:91], v[200:203], v[136:139]
	v_mfma_f32_16x16x32_bf16 v[124:127], v[76:79], v[214:217], v[124:127]
	v_mfma_f32_16x16x32_bf16 v[120:123], v[88:91], v[214:217], v[120:123]
	v_mfma_f32_16x16x32_bf16 v[92:95], v[76:79], v[242:245], v[92:95]
	v_mfma_f32_16x16x32_bf16 v[80:83], v[88:91], v[242:245], v[80:83]
	v_mfma_f32_16x16x32_bf16 v[148:151], v[96:99], v[160:163], v[148:151]
	v_mfma_f32_16x16x32_bf16 v[144:147], v[104:107], v[160:163], v[144:147]
	v_mfma_f32_16x16x32_bf16 v[132:135], v[96:99], v[196:199], v[132:135]
	v_mfma_f32_16x16x32_bf16 v[128:131], v[104:107], v[196:199], v[128:131]
	v_mfma_f32_16x16x32_bf16 v[116:119], v[96:99], v[204:207], v[116:119]
	v_mfma_f32_16x16x32_bf16 v[112:115], v[104:107], v[204:207], v[112:115]
	v_mfma_f32_16x16x32_bf16 v[68:71], v[96:99], v[218:221], v[68:71]
	v_mfma_f32_16x16x32_bf16 v[64:67], v[104:107], v[218:221], v[64:67]
	v_mfma_f32_16x16x32_bf16 v[148:151], v[100:103], v[164:167], v[148:151]
	v_mfma_f32_16x16x32_bf16 v[144:147], v[108:111], v[164:167], v[144:147]
	v_mfma_f32_16x16x32_bf16 v[132:135], v[100:103], v[200:203], v[132:135]
	v_mfma_f32_16x16x32_bf16 v[128:131], v[108:111], v[200:203], v[128:131]
	v_mfma_f32_16x16x32_bf16 v[116:119], v[100:103], v[214:217], v[116:119]
	v_mfma_f32_16x16x32_bf16 v[112:115], v[108:111], v[214:217], v[112:115]
	v_mfma_f32_16x16x32_bf16 v[68:71], v[100:103], v[242:245], v[68:71]
	v_mfma_f32_16x16x32_bf16 v[64:67], v[108:111], v[242:245], v[64:67]
	s_setprio 0
	s_barrier
	s_add_i32 s26, s48, s43
	v_lshl_add_u64 v[208:209], v[208:209], 0, s[28:29]
	s_mov_b32 m0, s26
	ds_read_b128 v[160:163], v212 offset:49152
	ds_read_b128 v[164:167], v212 offset:50176
	ds_read_b128 v[196:199], v212 offset:51200
	ds_read_b128 v[200:203], v212 offset:52224
	ds_read_b128 v[204:207], v212 offset:53248
	ds_read_b128 v[214:217], v212 offset:54272
	ds_read_b128 v[218:221], v212 offset:55296
	ds_read_b128 v[242:245], v212 offset:56320
	global_load_lds_dwordx4 v[208:209], off
	s_add_i32 m0, s26, 0x2000
	s_add_u32 s22, s22, 0x40080
	v_lshl_add_u64 v[208:209], v[222:223], 0, s[28:29]
	s_addc_u32 s23, s23, 0
	s_add_i32 s26, s49, s43
	global_load_lds_dwordx4 v[208:209], off
	v_lshl_add_u64 v[208:209], s[22:23], 0, v[168:169]
	s_mov_b32 m0, s26
	s_nop 0
	global_load_lds_dwordx4 v[208:209], off
	v_lshl_add_u64 v[208:209], s[22:23], 0, v[190:191]
	s_add_i32 m0, s26, 0x2000
	s_nop 0
	global_load_lds_dwordx4 v[208:209], off
	v_lshl_add_u64 v[208:209], v[234:235], 0, s[28:29]
	s_mov_b32 m0, s74
	s_nop 0
	global_load_lds_dwordx4 v[208:209], off
	v_lshl_add_u64 v[208:209], v[236:237], 0, s[28:29]
	s_mov_b32 m0, s75
	s_nop 0
	global_load_lds_dwordx4 v[208:209], off
	s_waitcnt vmcnt(8)
	s_waitcnt lgkmcnt(0)
	s_barrier
	s_setprio 1
	s_waitcnt lgkmcnt(0)
	v_mfma_f32_16x16x32_bf16 v[60:63], v[72:75], v[160:163], v[60:63]
	v_mfma_f32_16x16x32_bf16 v[56:59], v[84:87], v[160:163], v[56:59]
	v_mfma_f32_16x16x32_bf16 v[44:47], v[72:75], v[196:199], v[44:47]
	v_mfma_f32_16x16x32_bf16 v[40:43], v[84:87], v[196:199], v[40:43]
	v_mfma_f32_16x16x32_bf16 v[28:31], v[72:75], v[204:207], v[28:31]
	v_mfma_f32_16x16x32_bf16 v[24:27], v[84:87], v[204:207], v[24:27]
	v_mfma_f32_16x16x32_bf16 v[12:15], v[72:75], v[218:221], v[12:15]
	v_mfma_f32_16x16x32_bf16 v[8:11], v[84:87], v[218:221], v[8:11]
	v_mfma_f32_16x16x32_bf16 v[60:63], v[76:79], v[164:167], v[60:63]
	v_mfma_f32_16x16x32_bf16 v[56:59], v[88:91], v[164:167], v[56:59]
	v_mfma_f32_16x16x32_bf16 v[44:47], v[76:79], v[200:203], v[44:47]
	v_mfma_f32_16x16x32_bf16 v[40:43], v[88:91], v[200:203], v[40:43]
	v_mfma_f32_16x16x32_bf16 v[28:31], v[76:79], v[214:217], v[28:31]
	v_mfma_f32_16x16x32_bf16 v[24:27], v[88:91], v[214:217], v[24:27]
	v_mfma_f32_16x16x32_bf16 v[12:15], v[76:79], v[242:245], v[12:15]
	v_mfma_f32_16x16x32_bf16 v[8:11], v[88:91], v[242:245], v[8:11]
	v_mfma_f32_16x16x32_bf16 v[52:55], v[96:99], v[160:163], v[52:55]
	v_mfma_f32_16x16x32_bf16 v[48:51], v[104:107], v[160:163], v[48:51]
	v_mfma_f32_16x16x32_bf16 v[36:39], v[96:99], v[196:199], v[36:39]
	v_mfma_f32_16x16x32_bf16 v[32:35], v[104:107], v[196:199], v[32:35]
	v_mfma_f32_16x16x32_bf16 v[20:23], v[96:99], v[204:207], v[20:23]
	v_mfma_f32_16x16x32_bf16 v[16:19], v[104:107], v[204:207], v[16:19]
	v_mfma_f32_16x16x32_bf16 v[4:7], v[96:99], v[218:221], v[4:7]
	v_mfma_f32_16x16x32_bf16 v[0:3], v[104:107], v[218:221], v[0:3]
	v_mfma_f32_16x16x32_bf16 v[52:55], v[100:103], v[164:167], v[52:55]
	v_mfma_f32_16x16x32_bf16 v[48:51], v[108:111], v[164:167], v[48:51]
	v_mfma_f32_16x16x32_bf16 v[36:39], v[100:103], v[200:203], v[36:39]
	v_mfma_f32_16x16x32_bf16 v[32:35], v[108:111], v[200:203], v[32:35]
	v_mfma_f32_16x16x32_bf16 v[20:23], v[100:103], v[214:217], v[20:23]
	v_mfma_f32_16x16x32_bf16 v[16:19], v[108:111], v[214:217], v[16:19]
	v_mfma_f32_16x16x32_bf16 v[4:7], v[100:103], v[242:245], v[4:7]
	v_mfma_f32_16x16x32_bf16 v[0:3], v[108:111], v[242:245], v[0:3]
	s_setprio 0
	s_barrier
	s_add_u32 s20, s20, 0x100
	s_addc_u32 s21, s21, 0
	s_add_u32 s45, s45, 0x100
	s_addc_u32 s63, s63, 0
	s_cmp_ge_i32 s65, s71
	s_mov_b32 s22, s65
	s_cbranch_scc0 .LBB0_378

.LBB0_444:
	s_add_i32 s59, s2, 2
	s_add_u32 s3, s0, 0xfffc0080
	s_addc_u32 s20, s1, -1
	s_add_i32 s74, 0, 0x10000
	s_cmp_eq_u32 s68, s2
	s_cselect_b32 s21, s41, s20
	s_cselect_b32 s20, s42, s3
	s_cselect_b32 s3, s43, s58
	s_cselect_b32 s2, s51, s53
	s_add_i32 s76, 0, 0x14000
	v_add_u32_e32 v146, s74, v219
	v_add_u32_e32 v162, s76, v219
	ds_read_b128 v[128:131], v146
	ds_read_b128 v[132:135], v146 offset:1024
	ds_read_b128 v[142:145], v146 offset:2048
	ds_read_b128 v[146:149], v146 offset:3072
	ds_read_b128 v[150:153], v162
	ds_read_b128 v[154:157], v162 offset:1024
	ds_read_b128 v[158:161], v162 offset:2048
	ds_read_b128 v[162:165], v162 offset:3072
	v_lshl_add_u64 v[166:167], s[0:1], 0, v[138:139]
	s_add_i32 m0, s23, 0xc000
	ds_read_b128 v[186:189], v220
	ds_read_b128 v[190:193], v220 offset:1024
	ds_read_b128 v[194:197], v220 offset:2048
	ds_read_b128 v[198:201], v220 offset:3072
	ds_read_b128 v[202:205], v220 offset:4096
	ds_read_b128 v[206:209], v220 offset:5120
	ds_read_b128 v[210:213], v220 offset:6144
	ds_read_b128 v[214:217], v220 offset:7168
	global_load_lds_dwordx4 v[166:167], off
	v_lshl_add_u64 v[166:167], s[0:1], 0, v[140:141]
	s_add_i32 m0, s23, 0xe000
	s_nop 0
	global_load_lds_dwordx4 v[166:167], off
	s_waitcnt vmcnt(8)
	s_waitcnt lgkmcnt(0)
	s_barrier
	s_setprio 1
	s_waitcnt lgkmcnt(0)
	v_mfma_f32_16x16x32_bf16 v[124:127], v[128:131], v[186:189], v[124:127]
	v_mfma_f32_16x16x32_bf16 v[120:123], v[142:145], v[186:189], v[120:123]
	v_mfma_f32_16x16x32_bf16 v[108:111], v[128:131], v[194:197], v[108:111]
	v_mfma_f32_16x16x32_bf16 v[104:107], v[142:145], v[194:197], v[104:107]
	v_mfma_f32_16x16x32_bf16 v[92:95], v[128:131], v[202:205], v[92:95]
	v_mfma_f32_16x16x32_bf16 v[88:91], v[142:145], v[202:205], v[88:91]
	v_mfma_f32_16x16x32_bf16 v[76:79], v[128:131], v[210:213], v[76:79]
	v_mfma_f32_16x16x32_bf16 v[72:75], v[142:145], v[210:213], v[72:75]
	v_mfma_f32_16x16x32_bf16 v[124:127], v[132:135], v[190:193], v[124:127]
	v_mfma_f32_16x16x32_bf16 v[120:123], v[146:149], v[190:193], v[120:123]
	v_mfma_f32_16x16x32_bf16 v[108:111], v[132:135], v[198:201], v[108:111]
	v_mfma_f32_16x16x32_bf16 v[104:107], v[146:149], v[198:201], v[104:107]
	v_mfma_f32_16x16x32_bf16 v[92:95], v[132:135], v[206:209], v[92:95]
	v_mfma_f32_16x16x32_bf16 v[88:91], v[146:149], v[206:209], v[88:91]
	v_mfma_f32_16x16x32_bf16 v[76:79], v[132:135], v[214:217], v[76:79]
	v_mfma_f32_16x16x32_bf16 v[72:75], v[146:149], v[214:217], v[72:75]
	v_mfma_f32_16x16x32_bf16 v[116:119], v[150:153], v[186:189], v[116:119]
	v_mfma_f32_16x16x32_bf16 v[112:115], v[158:161], v[186:189], v[112:115]
	v_mfma_f32_16x16x32_bf16 v[100:103], v[150:153], v[194:197], v[100:103]
	v_mfma_f32_16x16x32_bf16 v[96:99], v[158:161], v[194:197], v[96:99]
	v_mfma_f32_16x16x32_bf16 v[84:87], v[150:153], v[202:205], v[84:87]
	v_mfma_f32_16x16x32_bf16 v[80:83], v[158:161], v[202:205], v[80:83]
	v_mfma_f32_16x16x32_bf16 v[68:71], v[150:153], v[210:213], v[68:71]
	v_mfma_f32_16x16x32_bf16 v[64:67], v[158:161], v[210:213], v[64:67]
	v_mfma_f32_16x16x32_bf16 v[116:119], v[154:157], v[190:193], v[116:119]
	v_mfma_f32_16x16x32_bf16 v[112:115], v[162:165], v[190:193], v[112:115]
	v_mfma_f32_16x16x32_bf16 v[100:103], v[154:157], v[198:201], v[100:103]
	v_mfma_f32_16x16x32_bf16 v[96:99], v[162:165], v[198:201], v[96:99]
	v_mfma_f32_16x16x32_bf16 v[84:87], v[154:157], v[206:209], v[84:87]
	v_mfma_f32_16x16x32_bf16 v[80:83], v[162:165], v[206:209], v[80:83]
	v_mfma_f32_16x16x32_bf16 v[68:71], v[154:157], v[214:217], v[68:71]
	v_mfma_f32_16x16x32_bf16 v[64:67], v[162:165], v[214:217], v[64:67]
	s_setprio 0
	s_barrier
	s_add_i32 s74, s74, s22
	v_lshl_add_u64 v[166:167], s[2:3], 0, v[168:169]
	s_mov_b32 m0, s74
	ds_read_b128 v[186:189], v220 offset:16384
	ds_read_b128 v[190:193], v220 offset:17408
	ds_read_b128 v[194:197], v220 offset:18432
	ds_read_b128 v[198:201], v220 offset:19456
	ds_read_b128 v[202:205], v220 offset:20480
	ds_read_b128 v[206:209], v220 offset:21504
	ds_read_b128 v[210:213], v220 offset:22528
	ds_read_b128 v[214:217], v220 offset:23552
	global_load_lds_dwordx4 v[166:167], off
	s_add_i32 m0, s74, 0x2000
	s_add_u32 s74, s2, 0x40000
	v_lshl_add_u64 v[222:223], s[2:3], 0, v[136:137]
	s_addc_u32 s75, s3, 0
	s_add_i32 s76, s76, s22
	global_load_lds_dwordx4 v[222:223], off
	v_lshl_add_u64 v[234:235], s[74:75], 0, v[168:169]
	s_mov_b32 m0, s76
	v_lshl_add_u64 v[236:237], s[20:21], 0, v[136:137]
	global_load_lds_dwordx4 v[234:235], off
	v_lshl_add_u64 v[234:235], s[74:75], 0, v[136:137]
	s_add_i32 m0, s76, 0x2000
	s_nop 0
	global_load_lds_dwordx4 v[234:235], off
	v_lshl_add_u64 v[234:235], s[20:21], 0, v[168:169]
	s_mov_b32 m0, s23
	s_nop 0
	global_load_lds_dwordx4 v[234:235], off
	s_mov_b32 m0, s25
	s_nop 0
	global_load_lds_dwordx4 v[236:237], off
	s_waitcnt vmcnt(8)
	s_waitcnt lgkmcnt(0)
	s_barrier
	s_setprio 1
	s_waitcnt lgkmcnt(0)
	v_mfma_f32_16x16x32_bf16 v[60:63], v[128:131], v[186:189], v[60:63]
	v_mfma_f32_16x16x32_bf16 v[56:59], v[142:145], v[186:189], v[56:59]
	v_mfma_f32_16x16x32_bf16 v[44:47], v[128:131], v[194:197], v[44:47]
	v_mfma_f32_16x16x32_bf16 v[40:43], v[142:145], v[194:197], v[40:43]
	v_mfma_f32_16x16x32_bf16 v[28:31], v[128:131], v[202:205], v[28:31]
	v_mfma_f32_16x16x32_bf16 v[24:27], v[142:145], v[202:205], v[24:27]
	v_mfma_f32_16x16x32_bf16 v[12:15], v[128:131], v[210:213], v[12:15]
	v_mfma_f32_16x16x32_bf16 v[8:11], v[142:145], v[210:213], v[8:11]
	v_mfma_f32_16x16x32_bf16 v[60:63], v[132:135], v[190:193], v[60:63]
	v_mfma_f32_16x16x32_bf16 v[56:59], v[146:149], v[190:193], v[56:59]
	v_mfma_f32_16x16x32_bf16 v[44:47], v[132:135], v[198:201], v[44:47]
	v_mfma_f32_16x16x32_bf16 v[40:43], v[146:149], v[198:201], v[40:43]
	v_mfma_f32_16x16x32_bf16 v[28:31], v[132:135], v[206:209], v[28:31]
	v_mfma_f32_16x16x32_bf16 v[24:27], v[146:149], v[206:209], v[24:27]
	v_mfma_f32_16x16x32_bf16 v[12:15], v[132:135], v[214:217], v[12:15]
	v_mfma_f32_16x16x32_bf16 v[8:11], v[146:149], v[214:217], v[8:11]
	v_mfma_f32_16x16x32_bf16 v[52:55], v[150:153], v[186:189], v[52:55]
	v_mfma_f32_16x16x32_bf16 v[48:51], v[158:161], v[186:189], v[48:51]
	v_mfma_f32_16x16x32_bf16 v[36:39], v[150:153], v[194:197], v[36:39]
	v_mfma_f32_16x16x32_bf16 v[32:35], v[158:161], v[194:197], v[32:35]
	v_mfma_f32_16x16x32_bf16 v[20:23], v[150:153], v[202:205], v[20:23]
	v_mfma_f32_16x16x32_bf16 v[16:19], v[158:161], v[202:205], v[16:19]
	v_mfma_f32_16x16x32_bf16 v[4:7], v[150:153], v[210:213], v[4:7]
	v_mfma_f32_16x16x32_bf16 v[0:3], v[158:161], v[210:213], v[0:3]
	v_mfma_f32_16x16x32_bf16 v[52:55], v[154:157], v[190:193], v[52:55]
	v_mfma_f32_16x16x32_bf16 v[48:51], v[162:165], v[190:193], v[48:51]
	v_mfma_f32_16x16x32_bf16 v[36:39], v[154:157], v[198:201], v[36:39]
	v_mfma_f32_16x16x32_bf16 v[32:35], v[162:165], v[198:201], v[32:35]
	v_mfma_f32_16x16x32_bf16 v[20:23], v[154:157], v[206:209], v[20:23]
	v_mfma_f32_16x16x32_bf16 v[16:19], v[162:165], v[206:209], v[16:19]
	v_mfma_f32_16x16x32_bf16 v[4:7], v[154:157], v[214:217], v[4:7]
	v_mfma_f32_16x16x32_bf16 v[0:3], v[162:165], v[214:217], v[0:3]
	s_setprio 0
	s_barrier
	s_add_i32 s74, 0, 0x18000
	s_add_i32 s75, 0, 0x1c000
	v_add_u32_e32 v146, s74, v219
	v_add_u32_e32 v162, s75, v219
	ds_read_b128 v[128:131], v146
	ds_read_b128 v[132:135], v146 offset:1024
	ds_read_b128 v[142:145], v146 offset:2048
	ds_read_b128 v[146:149], v146 offset:3072
	ds_read_b128 v[150:153], v162
	ds_read_b128 v[154:157], v162 offset:1024
	ds_read_b128 v[158:161], v162 offset:2048
	ds_read_b128 v[162:165], v162 offset:3072
	s_add_u32 s20, s20, 0x40000
	s_addc_u32 s21, s21, 0
	s_mov_b32 m0, s61
	v_lshl_add_u64 v[242:243], s[20:21], 0, v[168:169]
	ds_read_b128 v[186:189], v220 offset:32768
	ds_read_b128 v[190:193], v220 offset:33792
	ds_read_b128 v[194:197], v220 offset:34816
	ds_read_b128 v[198:201], v220 offset:35840
	ds_read_b128 v[202:205], v220 offset:36864
	ds_read_b128 v[206:209], v220 offset:37888
	ds_read_b128 v[210:213], v220 offset:38912
	ds_read_b128 v[214:217], v220 offset:39936
	global_load_lds_dwordx4 v[242:243], off
	v_lshl_add_u64 v[242:243], s[20:21], 0, v[136:137]
	s_mov_b32 m0, s62
	s_nop 0
	global_load_lds_dwordx4 v[242:243], off
	s_waitcnt vmcnt(8)
	s_waitcnt lgkmcnt(0)
	s_barrier
	s_setprio 1
	s_waitcnt lgkmcnt(0)
	v_mfma_f32_16x16x32_bf16 v[124:127], v[128:131], v[186:189], v[124:127]
	v_mfma_f32_16x16x32_bf16 v[120:123], v[142:145], v[186:189], v[120:123]
	v_mfma_f32_16x16x32_bf16 v[108:111], v[128:131], v[194:197], v[108:111]
	v_mfma_f32_16x16x32_bf16 v[104:107], v[142:145], v[194:197], v[104:107]
	v_mfma_f32_16x16x32_bf16 v[92:95], v[128:131], v[202:205], v[92:95]
	v_mfma_f32_16x16x32_bf16 v[88:91], v[142:145], v[202:205], v[88:91]
	v_mfma_f32_16x16x32_bf16 v[76:79], v[128:131], v[210:213], v[76:79]
	v_mfma_f32_16x16x32_bf16 v[72:75], v[142:145], v[210:213], v[72:75]
	v_mfma_f32_16x16x32_bf16 v[124:127], v[132:135], v[190:193], v[124:127]
	v_mfma_f32_16x16x32_bf16 v[120:123], v[146:149], v[190:193], v[120:123]
	v_mfma_f32_16x16x32_bf16 v[108:111], v[132:135], v[198:201], v[108:111]
	v_mfma_f32_16x16x32_bf16 v[104:107], v[146:149], v[198:201], v[104:107]
	v_mfma_f32_16x16x32_bf16 v[92:95], v[132:135], v[206:209], v[92:95]
	v_mfma_f32_16x16x32_bf16 v[88:91], v[146:149], v[206:209], v[88:91]
	v_mfma_f32_16x16x32_bf16 v[76:79], v[132:135], v[214:217], v[76:79]
	v_mfma_f32_16x16x32_bf16 v[72:75], v[146:149], v[214:217], v[72:75]
	v_mfma_f32_16x16x32_bf16 v[116:119], v[150:153], v[186:189], v[116:119]
	v_mfma_f32_16x16x32_bf16 v[112:115], v[158:161], v[186:189], v[112:115]
	v_mfma_f32_16x16x32_bf16 v[100:103], v[150:153], v[194:197], v[100:103]
	v_mfma_f32_16x16x32_bf16 v[96:99], v[158:161], v[194:197], v[96:99]
	v_mfma_f32_16x16x32_bf16 v[84:87], v[150:153], v[202:205], v[84:87]
	v_mfma_f32_16x16x32_bf16 v[80:83], v[158:161], v[202:205], v[80:83]
	v_mfma_f32_16x16x32_bf16 v[68:71], v[150:153], v[210:213], v[68:71]
	v_mfma_f32_16x16x32_bf16 v[64:67], v[158:161], v[210:213], v[64:67]
	v_mfma_f32_16x16x32_bf16 v[116:119], v[154:157], v[190:193], v[116:119]
	v_mfma_f32_16x16x32_bf16 v[112:115], v[162:165], v[190:193], v[112:115]
	v_mfma_f32_16x16x32_bf16 v[100:103], v[154:157], v[198:201], v[100:103]
	v_mfma_f32_16x16x32_bf16 v[96:99], v[162:165], v[198:201], v[96:99]
	v_mfma_f32_16x16x32_bf16 v[84:87], v[154:157], v[206:209], v[84:87]
	v_mfma_f32_16x16x32_bf16 v[80:83], v[162:165], v[206:209], v[80:83]
	v_mfma_f32_16x16x32_bf16 v[68:71], v[154:157], v[214:217], v[68:71]
	v_mfma_f32_16x16x32_bf16 v[64:67], v[162:165], v[214:217], v[64:67]
	s_setprio 0
	s_barrier
	s_add_i32 s20, s74, s22
	v_lshl_add_u64 v[166:167], v[166:167], 0, s[28:29]
	s_mov_b32 m0, s20
	ds_read_b128 v[186:189], v220 offset:49152
	ds_read_b128 v[190:193], v220 offset:50176
	ds_read_b128 v[194:197], v220 offset:51200
	ds_read_b128 v[198:201], v220 offset:52224
	ds_read_b128 v[202:205], v220 offset:53248
	ds_read_b128 v[206:209], v220 offset:54272
	ds_read_b128 v[210:213], v220 offset:55296
	ds_read_b128 v[214:217], v220 offset:56320
	global_load_lds_dwordx4 v[166:167], off
	s_add_i32 m0, s20, 0x2000
	s_add_u32 s2, s2, 0x40080
	v_lshl_add_u64 v[166:167], v[222:223], 0, s[28:29]
	s_addc_u32 s3, s3, 0
	s_add_i32 s20, s75, s22
	global_load_lds_dwordx4 v[166:167], off
	v_lshl_add_u64 v[166:167], s[2:3], 0, v[168:169]
	s_mov_b32 m0, s20
	s_nop 0
	global_load_lds_dwordx4 v[166:167], off
	v_lshl_add_u64 v[166:167], s[2:3], 0, v[136:137]
	s_add_i32 m0, s20, 0x2000
	s_nop 0
	global_load_lds_dwordx4 v[166:167], off
	v_lshl_add_u64 v[166:167], v[234:235], 0, s[28:29]
	s_mov_b32 m0, s66
	s_nop 0
	global_load_lds_dwordx4 v[166:167], off
	v_lshl_add_u64 v[166:167], v[236:237], 0, s[28:29]
	s_mov_b32 m0, s67
	s_nop 0
	global_load_lds_dwordx4 v[166:167], off
	s_waitcnt vmcnt(8)
	s_waitcnt lgkmcnt(0)
	s_barrier
	s_setprio 1
	s_waitcnt lgkmcnt(0)
	v_mfma_f32_16x16x32_bf16 v[60:63], v[128:131], v[186:189], v[60:63]
	v_mfma_f32_16x16x32_bf16 v[56:59], v[142:145], v[186:189], v[56:59]
	v_mfma_f32_16x16x32_bf16 v[44:47], v[128:131], v[194:197], v[44:47]
	v_mfma_f32_16x16x32_bf16 v[40:43], v[142:145], v[194:197], v[40:43]
	v_mfma_f32_16x16x32_bf16 v[28:31], v[128:131], v[202:205], v[28:31]
	v_mfma_f32_16x16x32_bf16 v[24:27], v[142:145], v[202:205], v[24:27]
	v_mfma_f32_16x16x32_bf16 v[12:15], v[128:131], v[210:213], v[12:15]
	v_mfma_f32_16x16x32_bf16 v[8:11], v[142:145], v[210:213], v[8:11]
	v_mfma_f32_16x16x32_bf16 v[60:63], v[132:135], v[190:193], v[60:63]
	v_mfma_f32_16x16x32_bf16 v[56:59], v[146:149], v[190:193], v[56:59]
	v_mfma_f32_16x16x32_bf16 v[44:47], v[132:135], v[198:201], v[44:47]
	v_mfma_f32_16x16x32_bf16 v[40:43], v[146:149], v[198:201], v[40:43]
	v_mfma_f32_16x16x32_bf16 v[28:31], v[132:135], v[206:209], v[28:31]
	v_mfma_f32_16x16x32_bf16 v[24:27], v[146:149], v[206:209], v[24:27]
	v_mfma_f32_16x16x32_bf16 v[12:15], v[132:135], v[214:217], v[12:15]
	v_mfma_f32_16x16x32_bf16 v[8:11], v[146:149], v[214:217], v[8:11]
	v_mfma_f32_16x16x32_bf16 v[52:55], v[150:153], v[186:189], v[52:55]
	v_mfma_f32_16x16x32_bf16 v[48:51], v[158:161], v[186:189], v[48:51]
	v_mfma_f32_16x16x32_bf16 v[36:39], v[150:153], v[194:197], v[36:39]
	v_mfma_f32_16x16x32_bf16 v[32:35], v[158:161], v[194:197], v[32:35]
	v_mfma_f32_16x16x32_bf16 v[20:23], v[150:153], v[202:205], v[20:23]
	v_mfma_f32_16x16x32_bf16 v[16:19], v[158:161], v[202:205], v[16:19]
	v_mfma_f32_16x16x32_bf16 v[4:7], v[150:153], v[210:213], v[4:7]
	v_mfma_f32_16x16x32_bf16 v[0:3], v[158:161], v[210:213], v[0:3]
	v_mfma_f32_16x16x32_bf16 v[52:55], v[154:157], v[190:193], v[52:55]
	v_mfma_f32_16x16x32_bf16 v[48:51], v[162:165], v[190:193], v[48:51]
	v_mfma_f32_16x16x32_bf16 v[36:39], v[154:157], v[198:201], v[36:39]
	v_mfma_f32_16x16x32_bf16 v[32:35], v[162:165], v[198:201], v[32:35]
	v_mfma_f32_16x16x32_bf16 v[20:23], v[154:157], v[206:209], v[20:23]
	v_mfma_f32_16x16x32_bf16 v[16:19], v[162:165], v[206:209], v[16:19]
	v_mfma_f32_16x16x32_bf16 v[4:7], v[154:157], v[214:217], v[4:7]
	v_mfma_f32_16x16x32_bf16 v[0:3], v[162:165], v[214:217], v[0:3]
	s_setprio 0
	s_barrier
	s_add_u32 s0, s0, 0x100
	s_addc_u32 s1, s1, 0
	s_add_u32 s53, s53, 0x100
	s_addc_u32 s58, s58, 0
	s_cmp_ge_i32 s59, s63
	s_mov_b32 s2, s59
	s_cbranch_scc0 .LBB0_444

.LBB0_491:
	s_add_i32 s73, s20, 2
	s_add_u32 s21, s2, 0xfffc0080
	s_addc_u32 s22, s3, -1
	s_add_i32 s74, 0, 0x10000
	s_cmp_eq_u32 s67, s20
	s_cselect_b32 s23, s1, s22
	s_cselect_b32 s22, s25, s21
	s_cselect_b32 s21, s40, s51
	s_cselect_b32 s20, s41, s49
	s_add_i32 s76, 0, 0x14000
	v_add_u32_e32 v146, s74, v195
	v_add_u32_e32 v162, s76, v195
	ds_read_b128 v[134:137], v146
	ds_read_b128 v[138:141], v146 offset:1024
	ds_read_b128 v[142:145], v146 offset:2048
	ds_read_b128 v[146:149], v146 offset:3072
	ds_read_b128 v[150:153], v162
	ds_read_b128 v[154:157], v162 offset:1024
	ds_read_b128 v[158:161], v162 offset:2048
	ds_read_b128 v[162:165], v162 offset:3072
	v_lshl_add_u64 v[166:167], s[2:3], 0, v[130:131]
	s_add_i32 m0, s57, 0xc000
	s_waitcnt vmcnt(0)
	ds_read_b128 v[186:189], v196
	ds_read_b128 v[190:193], v196 offset:1024
	ds_read_b128 v[198:201], v196 offset:2048
	ds_read_b128 v[202:205], v196 offset:3072
	ds_read_b128 v[206:209], v196 offset:4096
	ds_read_b128 v[210:213], v196 offset:5120
	ds_read_b128 v[214:217], v196 offset:6144
	ds_read_b128 v[218:221], v196 offset:7168
	global_load_lds_dwordx4 v[166:167], off
	v_lshl_add_u64 v[166:167], s[2:3], 0, v[132:133]
	s_add_i32 m0, s57, 0xe000
	s_nop 0
	global_load_lds_dwordx4 v[166:167], off
	s_waitcnt vmcnt(8)
	s_waitcnt lgkmcnt(0)
	s_barrier
	s_setprio 1
	s_waitcnt lgkmcnt(0)
	v_mfma_f32_16x16x32_bf16 v[124:127], v[134:137], v[186:189], v[124:127]
	v_mfma_f32_16x16x32_bf16 v[120:123], v[142:145], v[186:189], v[120:123]
	v_mfma_f32_16x16x32_bf16 v[108:111], v[134:137], v[198:201], v[108:111]
	v_mfma_f32_16x16x32_bf16 v[104:107], v[142:145], v[198:201], v[104:107]
	v_mfma_f32_16x16x32_bf16 v[92:95], v[134:137], v[206:209], v[92:95]
	v_mfma_f32_16x16x32_bf16 v[88:91], v[142:145], v[206:209], v[88:91]
	v_mfma_f32_16x16x32_bf16 v[76:79], v[134:137], v[214:217], v[76:79]
	v_mfma_f32_16x16x32_bf16 v[72:75], v[142:145], v[214:217], v[72:75]
	v_mfma_f32_16x16x32_bf16 v[124:127], v[138:141], v[190:193], v[124:127]
	v_mfma_f32_16x16x32_bf16 v[120:123], v[146:149], v[190:193], v[120:123]
	v_mfma_f32_16x16x32_bf16 v[108:111], v[138:141], v[202:205], v[108:111]
	v_mfma_f32_16x16x32_bf16 v[104:107], v[146:149], v[202:205], v[104:107]
	v_mfma_f32_16x16x32_bf16 v[92:95], v[138:141], v[210:213], v[92:95]
	v_mfma_f32_16x16x32_bf16 v[88:91], v[146:149], v[210:213], v[88:91]
	v_mfma_f32_16x16x32_bf16 v[76:79], v[138:141], v[218:221], v[76:79]
	v_mfma_f32_16x16x32_bf16 v[72:75], v[146:149], v[218:221], v[72:75]
	v_mfma_f32_16x16x32_bf16 v[116:119], v[150:153], v[186:189], v[116:119]
	v_mfma_f32_16x16x32_bf16 v[112:115], v[158:161], v[186:189], v[112:115]
	v_mfma_f32_16x16x32_bf16 v[100:103], v[150:153], v[198:201], v[100:103]
	v_mfma_f32_16x16x32_bf16 v[96:99], v[158:161], v[198:201], v[96:99]
	v_mfma_f32_16x16x32_bf16 v[84:87], v[150:153], v[206:209], v[84:87]
	v_mfma_f32_16x16x32_bf16 v[80:83], v[158:161], v[206:209], v[80:83]
	v_mfma_f32_16x16x32_bf16 v[68:71], v[150:153], v[214:217], v[68:71]
	v_mfma_f32_16x16x32_bf16 v[64:67], v[158:161], v[214:217], v[64:67]
	v_mfma_f32_16x16x32_bf16 v[116:119], v[154:157], v[190:193], v[116:119]
	v_mfma_f32_16x16x32_bf16 v[112:115], v[162:165], v[190:193], v[112:115]
	v_mfma_f32_16x16x32_bf16 v[100:103], v[154:157], v[202:205], v[100:103]
	v_mfma_f32_16x16x32_bf16 v[96:99], v[162:165], v[202:205], v[96:99]
	v_mfma_f32_16x16x32_bf16 v[84:87], v[154:157], v[210:213], v[84:87]
	v_mfma_f32_16x16x32_bf16 v[80:83], v[162:165], v[210:213], v[80:83]
	v_mfma_f32_16x16x32_bf16 v[68:71], v[154:157], v[218:221], v[68:71]
	v_mfma_f32_16x16x32_bf16 v[64:67], v[162:165], v[218:221], v[64:67]
	s_setprio 0
	s_barrier
	s_add_i32 s74, s74, s56
	v_lshl_add_u64 v[166:167], s[20:21], 0, v[168:169]
	s_mov_b32 m0, s74
	ds_read_b128 v[186:189], v196 offset:16384
	ds_read_b128 v[190:193], v196 offset:17408
	ds_read_b128 v[198:201], v196 offset:18432
	ds_read_b128 v[202:205], v196 offset:19456
	ds_read_b128 v[206:209], v196 offset:20480
	ds_read_b128 v[210:213], v196 offset:21504
	ds_read_b128 v[214:217], v196 offset:22528
	ds_read_b128 v[218:221], v196 offset:23552
	global_load_lds_dwordx4 v[166:167], off
	s_add_i32 m0, s74, 0x2000
	s_add_u32 s74, s20, 0x40000
	v_lshl_add_u64 v[222:223], s[20:21], 0, v[128:129]
	s_addc_u32 s75, s21, 0
	s_add_i32 s76, s76, s56
	global_load_lds_dwordx4 v[222:223], off
	v_lshl_add_u64 v[234:235], s[74:75], 0, v[168:169]
	s_mov_b32 m0, s76
	v_lshl_add_u64 v[236:237], s[22:23], 0, v[128:129]
	global_load_lds_dwordx4 v[234:235], off
	v_lshl_add_u64 v[234:235], s[74:75], 0, v[128:129]
	s_add_i32 m0, s76, 0x2000
	s_nop 0
	global_load_lds_dwordx4 v[234:235], off
	v_lshl_add_u64 v[234:235], s[22:23], 0, v[168:169]
	s_mov_b32 m0, s57
	s_nop 0
	global_load_lds_dwordx4 v[234:235], off
	s_mov_b32 m0, s58
	s_nop 0
	global_load_lds_dwordx4 v[236:237], off
	s_waitcnt vmcnt(8)
	s_waitcnt lgkmcnt(0)
	s_barrier
	s_setprio 1
	s_waitcnt lgkmcnt(0)
	v_mfma_f32_16x16x32_bf16 v[60:63], v[134:137], v[186:189], v[60:63]
	v_mfma_f32_16x16x32_bf16 v[56:59], v[142:145], v[186:189], v[56:59]
	v_mfma_f32_16x16x32_bf16 v[44:47], v[134:137], v[198:201], v[44:47]
	v_mfma_f32_16x16x32_bf16 v[40:43], v[142:145], v[198:201], v[40:43]
	v_mfma_f32_16x16x32_bf16 v[28:31], v[134:137], v[206:209], v[28:31]
	v_mfma_f32_16x16x32_bf16 v[24:27], v[142:145], v[206:209], v[24:27]
	v_mfma_f32_16x16x32_bf16 v[12:15], v[134:137], v[214:217], v[12:15]
	v_mfma_f32_16x16x32_bf16 v[8:11], v[142:145], v[214:217], v[8:11]
	v_mfma_f32_16x16x32_bf16 v[60:63], v[138:141], v[190:193], v[60:63]
	v_mfma_f32_16x16x32_bf16 v[56:59], v[146:149], v[190:193], v[56:59]
	v_mfma_f32_16x16x32_bf16 v[44:47], v[138:141], v[202:205], v[44:47]
	v_mfma_f32_16x16x32_bf16 v[40:43], v[146:149], v[202:205], v[40:43]
	v_mfma_f32_16x16x32_bf16 v[28:31], v[138:141], v[210:213], v[28:31]
	v_mfma_f32_16x16x32_bf16 v[24:27], v[146:149], v[210:213], v[24:27]
	v_mfma_f32_16x16x32_bf16 v[12:15], v[138:141], v[218:221], v[12:15]
	v_mfma_f32_16x16x32_bf16 v[8:11], v[146:149], v[218:221], v[8:11]
	v_mfma_f32_16x16x32_bf16 v[52:55], v[150:153], v[186:189], v[52:55]
	v_mfma_f32_16x16x32_bf16 v[48:51], v[158:161], v[186:189], v[48:51]
	v_mfma_f32_16x16x32_bf16 v[36:39], v[150:153], v[198:201], v[36:39]
	v_mfma_f32_16x16x32_bf16 v[32:35], v[158:161], v[198:201], v[32:35]
	v_mfma_f32_16x16x32_bf16 v[20:23], v[150:153], v[206:209], v[20:23]
	v_mfma_f32_16x16x32_bf16 v[16:19], v[158:161], v[206:209], v[16:19]
	v_mfma_f32_16x16x32_bf16 v[4:7], v[150:153], v[214:217], v[4:7]
	v_mfma_f32_16x16x32_bf16 v[0:3], v[158:161], v[214:217], v[0:3]
	v_mfma_f32_16x16x32_bf16 v[52:55], v[154:157], v[190:193], v[52:55]
	v_mfma_f32_16x16x32_bf16 v[48:51], v[162:165], v[190:193], v[48:51]
	v_mfma_f32_16x16x32_bf16 v[36:39], v[154:157], v[202:205], v[36:39]
	v_mfma_f32_16x16x32_bf16 v[32:35], v[162:165], v[202:205], v[32:35]
	v_mfma_f32_16x16x32_bf16 v[20:23], v[154:157], v[210:213], v[20:23]
	v_mfma_f32_16x16x32_bf16 v[16:19], v[162:165], v[210:213], v[16:19]
	v_mfma_f32_16x16x32_bf16 v[4:7], v[154:157], v[218:221], v[4:7]
	v_mfma_f32_16x16x32_bf16 v[0:3], v[162:165], v[218:221], v[0:3]
	s_setprio 0
	s_barrier
	s_add_i32 s74, 0, 0x18000
	s_add_i32 s75, 0, 0x1c000
	v_add_u32_e32 v146, s74, v195
	v_add_u32_e32 v162, s75, v195
	ds_read_b128 v[134:137], v146
	ds_read_b128 v[138:141], v146 offset:1024
	ds_read_b128 v[142:145], v146 offset:2048
	ds_read_b128 v[146:149], v146 offset:3072
	ds_read_b128 v[150:153], v162
	ds_read_b128 v[154:157], v162 offset:1024
	ds_read_b128 v[158:161], v162 offset:2048
	ds_read_b128 v[162:165], v162 offset:3072
	s_add_u32 s22, s22, 0x40000
	s_addc_u32 s23, s23, 0
	s_mov_b32 m0, s59
	v_lshl_add_u64 v[242:243], s[22:23], 0, v[168:169]
	ds_read_b128 v[186:189], v196 offset:32768
	ds_read_b128 v[190:193], v196 offset:33792
	ds_read_b128 v[198:201], v196 offset:34816
	ds_read_b128 v[202:205], v196 offset:35840
	ds_read_b128 v[206:209], v196 offset:36864
	ds_read_b128 v[210:213], v196 offset:37888
	ds_read_b128 v[214:217], v196 offset:38912
	ds_read_b128 v[218:221], v196 offset:39936
	global_load_lds_dwordx4 v[242:243], off
	v_lshl_add_u64 v[242:243], s[22:23], 0, v[128:129]
	s_mov_b32 m0, s61
	s_nop 0
	global_load_lds_dwordx4 v[242:243], off
	s_waitcnt vmcnt(8)
	s_waitcnt lgkmcnt(0)
	s_barrier
	s_setprio 1
	s_waitcnt lgkmcnt(0)
	v_mfma_f32_16x16x32_bf16 v[124:127], v[134:137], v[186:189], v[124:127]
	v_mfma_f32_16x16x32_bf16 v[120:123], v[142:145], v[186:189], v[120:123]
	v_mfma_f32_16x16x32_bf16 v[108:111], v[134:137], v[198:201], v[108:111]
	v_mfma_f32_16x16x32_bf16 v[104:107], v[142:145], v[198:201], v[104:107]
	v_mfma_f32_16x16x32_bf16 v[92:95], v[134:137], v[206:209], v[92:95]
	v_mfma_f32_16x16x32_bf16 v[88:91], v[142:145], v[206:209], v[88:91]
	v_mfma_f32_16x16x32_bf16 v[76:79], v[134:137], v[214:217], v[76:79]
	v_mfma_f32_16x16x32_bf16 v[72:75], v[142:145], v[214:217], v[72:75]
	v_mfma_f32_16x16x32_bf16 v[124:127], v[138:141], v[190:193], v[124:127]
	v_mfma_f32_16x16x32_bf16 v[120:123], v[146:149], v[190:193], v[120:123]
	v_mfma_f32_16x16x32_bf16 v[108:111], v[138:141], v[202:205], v[108:111]
	v_mfma_f32_16x16x32_bf16 v[104:107], v[146:149], v[202:205], v[104:107]
	v_mfma_f32_16x16x32_bf16 v[92:95], v[138:141], v[210:213], v[92:95]
	v_mfma_f32_16x16x32_bf16 v[88:91], v[146:149], v[210:213], v[88:91]
	v_mfma_f32_16x16x32_bf16 v[76:79], v[138:141], v[218:221], v[76:79]
	v_mfma_f32_16x16x32_bf16 v[72:75], v[146:149], v[218:221], v[72:75]
	v_mfma_f32_16x16x32_bf16 v[116:119], v[150:153], v[186:189], v[116:119]
	v_mfma_f32_16x16x32_bf16 v[112:115], v[158:161], v[186:189], v[112:115]
	v_mfma_f32_16x16x32_bf16 v[100:103], v[150:153], v[198:201], v[100:103]
	v_mfma_f32_16x16x32_bf16 v[96:99], v[158:161], v[198:201], v[96:99]
	v_mfma_f32_16x16x32_bf16 v[84:87], v[150:153], v[206:209], v[84:87]
	v_mfma_f32_16x16x32_bf16 v[80:83], v[158:161], v[206:209], v[80:83]
	v_mfma_f32_16x16x32_bf16 v[68:71], v[150:153], v[214:217], v[68:71]
	v_mfma_f32_16x16x32_bf16 v[64:67], v[158:161], v[214:217], v[64:67]
	v_mfma_f32_16x16x32_bf16 v[116:119], v[154:157], v[190:193], v[116:119]
	v_mfma_f32_16x16x32_bf16 v[112:115], v[162:165], v[190:193], v[112:115]
	v_mfma_f32_16x16x32_bf16 v[100:103], v[154:157], v[202:205], v[100:103]
	v_mfma_f32_16x16x32_bf16 v[96:99], v[162:165], v[202:205], v[96:99]
	v_mfma_f32_16x16x32_bf16 v[84:87], v[154:157], v[210:213], v[84:87]
	v_mfma_f32_16x16x32_bf16 v[80:83], v[162:165], v[210:213], v[80:83]
	v_mfma_f32_16x16x32_bf16 v[68:71], v[154:157], v[218:221], v[68:71]
	v_mfma_f32_16x16x32_bf16 v[64:67], v[162:165], v[218:221], v[64:67]
	s_setprio 0
	s_barrier
	s_add_i32 s22, s74, s56
	v_lshl_add_u64 v[166:167], v[166:167], 0, s[28:29]
	s_mov_b32 m0, s22
	ds_read_b128 v[186:189], v196 offset:49152
	ds_read_b128 v[190:193], v196 offset:50176
	ds_read_b128 v[198:201], v196 offset:51200
	ds_read_b128 v[202:205], v196 offset:52224
	ds_read_b128 v[206:209], v196 offset:53248
	ds_read_b128 v[210:213], v196 offset:54272
	ds_read_b128 v[214:217], v196 offset:55296
	ds_read_b128 v[218:221], v196 offset:56320
	global_load_lds_dwordx4 v[166:167], off
	s_add_i32 m0, s22, 0x2000
	s_add_u32 s20, s20, 0x40080
	v_lshl_add_u64 v[166:167], v[222:223], 0, s[28:29]
	s_addc_u32 s21, s21, 0
	s_add_i32 s22, s75, s56
	global_load_lds_dwordx4 v[166:167], off
	v_lshl_add_u64 v[166:167], s[20:21], 0, v[168:169]
	s_mov_b32 m0, s22
	s_nop 0
	global_load_lds_dwordx4 v[166:167], off
	v_lshl_add_u64 v[166:167], s[20:21], 0, v[128:129]
	s_add_i32 m0, s22, 0x2000
	s_nop 0
	global_load_lds_dwordx4 v[166:167], off
	v_lshl_add_u64 v[166:167], v[234:235], 0, s[28:29]
	s_mov_b32 m0, s65
	s_nop 0
	global_load_lds_dwordx4 v[166:167], off
	v_lshl_add_u64 v[166:167], v[236:237], 0, s[28:29]
	s_mov_b32 m0, s66
	s_nop 0
	global_load_lds_dwordx4 v[166:167], off
	s_waitcnt vmcnt(8)
	s_waitcnt lgkmcnt(0)
	s_barrier
	s_setprio 1
	s_waitcnt lgkmcnt(0)
	v_mfma_f32_16x16x32_bf16 v[60:63], v[134:137], v[186:189], v[60:63]
	v_mfma_f32_16x16x32_bf16 v[56:59], v[142:145], v[186:189], v[56:59]
	v_mfma_f32_16x16x32_bf16 v[44:47], v[134:137], v[198:201], v[44:47]
	v_mfma_f32_16x16x32_bf16 v[40:43], v[142:145], v[198:201], v[40:43]
	v_mfma_f32_16x16x32_bf16 v[28:31], v[134:137], v[206:209], v[28:31]
	v_mfma_f32_16x16x32_bf16 v[24:27], v[142:145], v[206:209], v[24:27]
	v_mfma_f32_16x16x32_bf16 v[12:15], v[134:137], v[214:217], v[12:15]
	v_mfma_f32_16x16x32_bf16 v[8:11], v[142:145], v[214:217], v[8:11]
	v_mfma_f32_16x16x32_bf16 v[60:63], v[138:141], v[190:193], v[60:63]
	v_mfma_f32_16x16x32_bf16 v[56:59], v[146:149], v[190:193], v[56:59]
	v_mfma_f32_16x16x32_bf16 v[44:47], v[138:141], v[202:205], v[44:47]
	v_mfma_f32_16x16x32_bf16 v[40:43], v[146:149], v[202:205], v[40:43]
	v_mfma_f32_16x16x32_bf16 v[28:31], v[138:141], v[210:213], v[28:31]
	v_mfma_f32_16x16x32_bf16 v[24:27], v[146:149], v[210:213], v[24:27]
	v_mfma_f32_16x16x32_bf16 v[12:15], v[138:141], v[218:221], v[12:15]
	v_mfma_f32_16x16x32_bf16 v[8:11], v[146:149], v[218:221], v[8:11]
	v_mfma_f32_16x16x32_bf16 v[52:55], v[150:153], v[186:189], v[52:55]
	v_mfma_f32_16x16x32_bf16 v[48:51], v[158:161], v[186:189], v[48:51]
	v_mfma_f32_16x16x32_bf16 v[36:39], v[150:153], v[198:201], v[36:39]
	v_mfma_f32_16x16x32_bf16 v[32:35], v[158:161], v[198:201], v[32:35]
	v_mfma_f32_16x16x32_bf16 v[20:23], v[150:153], v[206:209], v[20:23]
	v_mfma_f32_16x16x32_bf16 v[16:19], v[158:161], v[206:209], v[16:19]
	v_mfma_f32_16x16x32_bf16 v[4:7], v[150:153], v[214:217], v[4:7]
	v_mfma_f32_16x16x32_bf16 v[0:3], v[158:161], v[214:217], v[0:3]
	v_mfma_f32_16x16x32_bf16 v[52:55], v[154:157], v[190:193], v[52:55]
	v_mfma_f32_16x16x32_bf16 v[48:51], v[162:165], v[190:193], v[48:51]
	v_mfma_f32_16x16x32_bf16 v[36:39], v[154:157], v[202:205], v[36:39]
	v_mfma_f32_16x16x32_bf16 v[32:35], v[162:165], v[202:205], v[32:35]
	v_mfma_f32_16x16x32_bf16 v[20:23], v[154:157], v[210:213], v[20:23]
	v_mfma_f32_16x16x32_bf16 v[16:19], v[162:165], v[210:213], v[16:19]
	v_mfma_f32_16x16x32_bf16 v[4:7], v[154:157], v[218:221], v[4:7]
	v_mfma_f32_16x16x32_bf16 v[0:3], v[162:165], v[218:221], v[0:3]
	s_setprio 0
	s_barrier
	s_add_u32 s2, s2, 0x100
	s_addc_u32 s3, s3, 0
	s_add_u32 s49, s49, 0x100
	s_addc_u32 s51, s51, 0
	s_cmp_ge_i32 s73, s62
	s_mov_b32 s20, s73
	s_cbranch_scc0 .LBB0_491

.LBB0_537:
	s_add_i32 s68, s26, 2
	s_add_u32 s22, s20, 0x100
	s_addc_u32 s23, s21, 0
	s_add_u32 s27, s66, s20
	s_addc_u32 s50, s67, s21
	s_add_i32 s69, 0, 0x10000
	s_cmp_eq_u32 s64, s26
	s_cselect_b32 s26, 0, s22
	s_cselect_b32 s51, s3, s50
	s_cselect_b32 s50, s47, s27
	s_cselect_b32 s27, 0, s23
	s_add_u32 s26, s0, s26
	s_addc_u32 s27, s1, s27
	s_add_i32 s70, 0, 0x14000
	v_add_u32_e32 v158, s69, v144
	v_add_u32_e32 v166, s70, v144
	ds_read_b128 v[146:149], v158
	ds_read_b128 v[150:153], v158 offset:1024
	ds_read_b128 v[154:157], v158 offset:2048
	ds_read_b128 v[158:161], v158 offset:3072
	ds_read_b128 v[162:165], v166
	s_waitcnt vmcnt(0)
	ds_read_b128 v[186:189], v166 offset:1024
	ds_read_b128 v[190:193], v166 offset:2048
	ds_read_b128 v[194:197], v166 offset:3072
	v_lshl_add_u64 v[166:167], v[138:139], 0, s[20:21]
	s_add_i32 m0, s55, 0xc000
	ds_read_b128 v[198:201], v145
	ds_read_b128 v[202:205], v145 offset:1024
	ds_read_b128 v[206:209], v145 offset:2048
	ds_read_b128 v[210:213], v145 offset:3072
	ds_read_b128 v[214:217], v145 offset:4096
	ds_read_b128 v[218:221], v145 offset:5120
	ds_read_b128 v[242:245], v145 offset:6144
	ds_read_b128 v[246:249], v145 offset:7168
	global_load_lds_dwordx4 v[166:167], off
	v_lshl_add_u64 v[166:167], v[140:141], 0, s[20:21]
	s_add_i32 m0, s55, 0xe000
	s_nop 0
	global_load_lds_dwordx4 v[166:167], off
	s_waitcnt vmcnt(8)
	s_waitcnt lgkmcnt(0)
	s_barrier
	s_setprio 1
	s_waitcnt lgkmcnt(0)
	v_mfma_f32_16x16x32_bf16 v[124:127], v[146:149], v[198:201], v[124:127]
	v_mfma_f32_16x16x32_bf16 v[120:123], v[154:157], v[198:201], v[120:123]
	v_mfma_f32_16x16x32_bf16 v[108:111], v[146:149], v[206:209], v[108:111]
	v_mfma_f32_16x16x32_bf16 v[104:107], v[154:157], v[206:209], v[104:107]
	v_mfma_f32_16x16x32_bf16 v[92:95], v[146:149], v[214:217], v[92:95]
	v_mfma_f32_16x16x32_bf16 v[88:91], v[154:157], v[214:217], v[88:91]
	v_mfma_f32_16x16x32_bf16 v[76:79], v[146:149], v[242:245], v[76:79]
	v_mfma_f32_16x16x32_bf16 v[72:75], v[154:157], v[242:245], v[72:75]
	v_mfma_f32_16x16x32_bf16 v[124:127], v[150:153], v[202:205], v[124:127]
	v_mfma_f32_16x16x32_bf16 v[120:123], v[158:161], v[202:205], v[120:123]
	v_mfma_f32_16x16x32_bf16 v[108:111], v[150:153], v[210:213], v[108:111]
	v_mfma_f32_16x16x32_bf16 v[104:107], v[158:161], v[210:213], v[104:107]
	v_mfma_f32_16x16x32_bf16 v[92:95], v[150:153], v[218:221], v[92:95]
	v_mfma_f32_16x16x32_bf16 v[88:91], v[158:161], v[218:221], v[88:91]
	v_mfma_f32_16x16x32_bf16 v[76:79], v[150:153], v[246:249], v[76:79]
	v_mfma_f32_16x16x32_bf16 v[72:75], v[158:161], v[246:249], v[72:75]
	v_mfma_f32_16x16x32_bf16 v[116:119], v[162:165], v[198:201], v[116:119]
	v_mfma_f32_16x16x32_bf16 v[112:115], v[190:193], v[198:201], v[112:115]
	v_mfma_f32_16x16x32_bf16 v[100:103], v[162:165], v[206:209], v[100:103]
	v_mfma_f32_16x16x32_bf16 v[96:99], v[190:193], v[206:209], v[96:99]
	v_mfma_f32_16x16x32_bf16 v[84:87], v[162:165], v[214:217], v[84:87]
	v_mfma_f32_16x16x32_bf16 v[80:83], v[190:193], v[214:217], v[80:83]
	v_mfma_f32_16x16x32_bf16 v[68:71], v[162:165], v[242:245], v[68:71]
	v_mfma_f32_16x16x32_bf16 v[64:67], v[190:193], v[242:245], v[64:67]
	v_mfma_f32_16x16x32_bf16 v[116:119], v[186:189], v[202:205], v[116:119]
	v_mfma_f32_16x16x32_bf16 v[112:115], v[194:197], v[202:205], v[112:115]
	v_mfma_f32_16x16x32_bf16 v[100:103], v[186:189], v[210:213], v[100:103]
	v_mfma_f32_16x16x32_bf16 v[96:99], v[194:197], v[210:213], v[96:99]
	v_mfma_f32_16x16x32_bf16 v[84:87], v[186:189], v[218:221], v[84:87]
	v_mfma_f32_16x16x32_bf16 v[80:83], v[194:197], v[218:221], v[80:83]
	v_mfma_f32_16x16x32_bf16 v[68:71], v[186:189], v[246:249], v[68:71]
	v_mfma_f32_16x16x32_bf16 v[64:67], v[194:197], v[246:249], v[64:67]
	s_setprio 0
	s_barrier
	s_add_i32 s20, s69, s54
	v_lshl_add_u64 v[166:167], s[26:27], 0, v[128:129]
	s_mov_b32 m0, s20
	ds_read_b128 v[198:201], v145 offset:16384
	ds_read_b128 v[202:205], v145 offset:17408
	ds_read_b128 v[206:209], v145 offset:18432
	ds_read_b128 v[210:213], v145 offset:19456
	ds_read_b128 v[214:217], v145 offset:20480
	ds_read_b128 v[218:221], v145 offset:21504
	ds_read_b128 v[242:245], v145 offset:22528
	ds_read_b128 v[246:249], v145 offset:23552
	global_load_lds_dwordx4 v[166:167], off
	s_add_i32 m0, s20, 0x2000
	s_add_u32 s20, s26, 0x10000
	v_lshl_add_u64 v[222:223], s[26:27], 0, v[132:133]
	s_addc_u32 s21, s27, 0
	s_add_i32 s69, s70, s54
	global_load_lds_dwordx4 v[222:223], off
	v_lshl_add_u64 v[236:237], s[20:21], 0, v[128:129]
	s_mov_b32 m0, s69
	v_lshl_add_u64 v[250:251], s[50:51], 0, v[130:131]
	global_load_lds_dwordx4 v[236:237], off
	v_lshl_add_u64 v[236:237], s[20:21], 0, v[132:133]
	s_add_i32 m0, s69, 0x2000
	s_nop 0
	global_load_lds_dwordx4 v[236:237], off
	v_lshl_add_u64 v[236:237], s[50:51], 0, v[168:169]
	s_mov_b32 m0, s55
	s_nop 0
	global_load_lds_dwordx4 v[236:237], off
	s_mov_b32 m0, s56
	s_nop 0
	global_load_lds_dwordx4 v[250:251], off
	s_waitcnt vmcnt(8)
	s_waitcnt lgkmcnt(0)
	s_barrier
	s_setprio 1
	s_waitcnt lgkmcnt(0)
	v_mfma_f32_16x16x32_bf16 v[60:63], v[146:149], v[198:201], v[60:63]
	v_mfma_f32_16x16x32_bf16 v[56:59], v[154:157], v[198:201], v[56:59]
	v_mfma_f32_16x16x32_bf16 v[44:47], v[146:149], v[206:209], v[44:47]
	v_mfma_f32_16x16x32_bf16 v[40:43], v[154:157], v[206:209], v[40:43]
	v_mfma_f32_16x16x32_bf16 v[28:31], v[146:149], v[214:217], v[28:31]
	v_mfma_f32_16x16x32_bf16 v[24:27], v[154:157], v[214:217], v[24:27]
	v_mfma_f32_16x16x32_bf16 v[12:15], v[146:149], v[242:245], v[12:15]
	v_mfma_f32_16x16x32_bf16 v[8:11], v[154:157], v[242:245], v[8:11]
	v_mfma_f32_16x16x32_bf16 v[60:63], v[150:153], v[202:205], v[60:63]
	v_mfma_f32_16x16x32_bf16 v[56:59], v[158:161], v[202:205], v[56:59]
	v_mfma_f32_16x16x32_bf16 v[44:47], v[150:153], v[210:213], v[44:47]
	v_mfma_f32_16x16x32_bf16 v[40:43], v[158:161], v[210:213], v[40:43]
	v_mfma_f32_16x16x32_bf16 v[28:31], v[150:153], v[218:221], v[28:31]
	v_mfma_f32_16x16x32_bf16 v[24:27], v[158:161], v[218:221], v[24:27]
	v_mfma_f32_16x16x32_bf16 v[12:15], v[150:153], v[246:249], v[12:15]
	v_mfma_f32_16x16x32_bf16 v[8:11], v[158:161], v[246:249], v[8:11]
	v_mfma_f32_16x16x32_bf16 v[52:55], v[162:165], v[198:201], v[52:55]
	v_mfma_f32_16x16x32_bf16 v[48:51], v[190:193], v[198:201], v[48:51]
	v_mfma_f32_16x16x32_bf16 v[36:39], v[162:165], v[206:209], v[36:39]
	v_mfma_f32_16x16x32_bf16 v[32:35], v[190:193], v[206:209], v[32:35]
	v_mfma_f32_16x16x32_bf16 v[20:23], v[162:165], v[214:217], v[20:23]
	v_mfma_f32_16x16x32_bf16 v[16:19], v[190:193], v[214:217], v[16:19]
	v_mfma_f32_16x16x32_bf16 v[0:3], v[162:165], v[242:245], v[0:3]
	v_mfma_f32_16x16x32_bf16 v[4:7], v[190:193], v[242:245], v[4:7]
	v_mfma_f32_16x16x32_bf16 v[52:55], v[186:189], v[202:205], v[52:55]
	v_mfma_f32_16x16x32_bf16 v[48:51], v[194:197], v[202:205], v[48:51]
	v_mfma_f32_16x16x32_bf16 v[36:39], v[186:189], v[210:213], v[36:39]
	v_mfma_f32_16x16x32_bf16 v[32:35], v[194:197], v[210:213], v[32:35]
	v_mfma_f32_16x16x32_bf16 v[20:23], v[186:189], v[218:221], v[20:23]
	v_mfma_f32_16x16x32_bf16 v[16:19], v[194:197], v[218:221], v[16:19]
	v_mfma_f32_16x16x32_bf16 v[0:3], v[186:189], v[246:249], v[0:3]
	v_mfma_f32_16x16x32_bf16 v[4:7], v[194:197], v[246:249], v[4:7]
	s_setprio 0
	s_barrier
	s_add_i32 s69, 0, 0x18000
	s_add_i32 s70, 0, 0x1c000
	v_add_u32_e32 v158, s69, v144
	v_add_u32_e32 v174, s70, v144
	ds_read_b128 v[146:149], v158
	ds_read_b128 v[150:153], v158 offset:1024
	ds_read_b128 v[154:157], v158 offset:2048
	ds_read_b128 v[158:161], v158 offset:3072
	ds_read_b128 v[162:165], v174
	ds_read_b128 v[186:189], v174 offset:1024
	ds_read_b128 v[190:193], v174 offset:2048
	ds_read_b128 v[194:197], v174 offset:3072
	s_add_u32 s20, s50, 0x40000
	s_addc_u32 s21, s51, 0
	s_mov_b32 m0, s57
	v_lshl_add_u64 v[234:235], s[20:21], 0, v[168:169]
	ds_read_b128 v[198:201], v145 offset:32768
	ds_read_b128 v[202:205], v145 offset:33792
	ds_read_b128 v[206:209], v145 offset:34816
	ds_read_b128 v[210:213], v145 offset:35840
	ds_read_b128 v[214:217], v145 offset:36864
	ds_read_b128 v[218:221], v145 offset:37888
	ds_read_b128 v[242:245], v145 offset:38912
	ds_read_b128 v[246:249], v145 offset:39936
	global_load_lds_dwordx4 v[234:235], off
	v_lshl_add_u64 v[234:235], s[20:21], 0, v[130:131]
	s_mov_b32 m0, s58
	s_nop 0
	global_load_lds_dwordx4 v[234:235], off
	s_waitcnt vmcnt(8)
	s_waitcnt lgkmcnt(0)
	s_barrier
	s_setprio 1
	s_waitcnt lgkmcnt(0)
	v_mfma_f32_16x16x32_bf16 v[124:127], v[146:149], v[198:201], v[124:127]
	v_mfma_f32_16x16x32_bf16 v[120:123], v[154:157], v[198:201], v[120:123]
	v_mfma_f32_16x16x32_bf16 v[108:111], v[146:149], v[206:209], v[108:111]
	v_mfma_f32_16x16x32_bf16 v[104:107], v[154:157], v[206:209], v[104:107]
	v_mfma_f32_16x16x32_bf16 v[92:95], v[146:149], v[214:217], v[92:95]
	v_mfma_f32_16x16x32_bf16 v[88:91], v[154:157], v[214:217], v[88:91]
	v_mfma_f32_16x16x32_bf16 v[76:79], v[146:149], v[242:245], v[76:79]
	v_mfma_f32_16x16x32_bf16 v[72:75], v[154:157], v[242:245], v[72:75]
	v_mfma_f32_16x16x32_bf16 v[124:127], v[150:153], v[202:205], v[124:127]
	v_mfma_f32_16x16x32_bf16 v[120:123], v[158:161], v[202:205], v[120:123]
	v_mfma_f32_16x16x32_bf16 v[108:111], v[150:153], v[210:213], v[108:111]
	v_mfma_f32_16x16x32_bf16 v[104:107], v[158:161], v[210:213], v[104:107]
	v_mfma_f32_16x16x32_bf16 v[92:95], v[150:153], v[218:221], v[92:95]
	v_mfma_f32_16x16x32_bf16 v[88:91], v[158:161], v[218:221], v[88:91]
	v_mfma_f32_16x16x32_bf16 v[76:79], v[150:153], v[246:249], v[76:79]
	v_mfma_f32_16x16x32_bf16 v[72:75], v[158:161], v[246:249], v[72:75]
	v_mfma_f32_16x16x32_bf16 v[116:119], v[162:165], v[198:201], v[116:119]
	v_mfma_f32_16x16x32_bf16 v[112:115], v[190:193], v[198:201], v[112:115]
	v_mfma_f32_16x16x32_bf16 v[100:103], v[162:165], v[206:209], v[100:103]
	v_mfma_f32_16x16x32_bf16 v[96:99], v[190:193], v[206:209], v[96:99]
	v_mfma_f32_16x16x32_bf16 v[84:87], v[162:165], v[214:217], v[84:87]
	v_mfma_f32_16x16x32_bf16 v[80:83], v[190:193], v[214:217], v[80:83]
	v_mfma_f32_16x16x32_bf16 v[68:71], v[162:165], v[242:245], v[68:71]
	v_mfma_f32_16x16x32_bf16 v[64:67], v[190:193], v[242:245], v[64:67]
	v_mfma_f32_16x16x32_bf16 v[116:119], v[186:189], v[202:205], v[116:119]
	v_mfma_f32_16x16x32_bf16 v[112:115], v[194:197], v[202:205], v[112:115]
	v_mfma_f32_16x16x32_bf16 v[100:103], v[186:189], v[210:213], v[100:103]
	v_mfma_f32_16x16x32_bf16 v[96:99], v[194:197], v[210:213], v[96:99]
	v_mfma_f32_16x16x32_bf16 v[84:87], v[186:189], v[218:221], v[84:87]
	v_mfma_f32_16x16x32_bf16 v[80:83], v[194:197], v[218:221], v[80:83]
	v_mfma_f32_16x16x32_bf16 v[68:71], v[186:189], v[246:249], v[68:71]
	v_mfma_f32_16x16x32_bf16 v[64:67], v[194:197], v[246:249], v[64:67]
	s_setprio 0
	s_barrier
	s_add_i32 s20, s69, s54
	v_lshl_add_u64 v[166:167], v[166:167], 0, s[28:29]
	s_mov_b32 m0, s20
	ds_read_b128 v[198:201], v145 offset:49152
	ds_read_b128 v[202:205], v145 offset:50176
	ds_read_b128 v[206:209], v145 offset:51200
	ds_read_b128 v[210:213], v145 offset:52224
	ds_read_b128 v[214:217], v145 offset:53248
	ds_read_b128 v[218:221], v145 offset:54272
	ds_read_b128 v[242:245], v145 offset:55296
	ds_read_b128 v[246:249], v145 offset:56320
	global_load_lds_dwordx4 v[166:167], off
	s_add_i32 m0, s20, 0x2000
	s_add_u32 s20, s26, 0x10080
	v_lshl_add_u64 v[166:167], v[222:223], 0, s[28:29]
	s_addc_u32 s21, s27, 0
	s_add_i32 s26, s70, s54
	global_load_lds_dwordx4 v[166:167], off
	v_lshl_add_u64 v[166:167], s[20:21], 0, v[128:129]
	s_mov_b32 m0, s26
	s_nop 0
	global_load_lds_dwordx4 v[166:167], off
	v_lshl_add_u64 v[166:167], s[20:21], 0, v[132:133]
	s_add_i32 m0, s26, 0x2000
	s_nop 0
	global_load_lds_dwordx4 v[166:167], off
	v_lshl_add_u64 v[166:167], v[236:237], 0, s[28:29]
	s_mov_b32 m0, s62
	s_nop 0
	global_load_lds_dwordx4 v[166:167], off
	v_lshl_add_u64 v[166:167], v[250:251], 0, s[28:29]
	s_mov_b32 m0, s63
	s_nop 0
	global_load_lds_dwordx4 v[166:167], off
	s_waitcnt vmcnt(8)
	s_waitcnt lgkmcnt(0)
	s_barrier
	s_setprio 1
	s_waitcnt lgkmcnt(0)
	v_mfma_f32_16x16x32_bf16 v[60:63], v[146:149], v[198:201], v[60:63]
	v_mfma_f32_16x16x32_bf16 v[56:59], v[154:157], v[198:201], v[56:59]
	v_mfma_f32_16x16x32_bf16 v[44:47], v[146:149], v[206:209], v[44:47]
	v_mfma_f32_16x16x32_bf16 v[40:43], v[154:157], v[206:209], v[40:43]
	v_mfma_f32_16x16x32_bf16 v[28:31], v[146:149], v[214:217], v[28:31]
	v_mfma_f32_16x16x32_bf16 v[24:27], v[154:157], v[214:217], v[24:27]
	v_mfma_f32_16x16x32_bf16 v[12:15], v[146:149], v[242:245], v[12:15]
	v_mfma_f32_16x16x32_bf16 v[8:11], v[154:157], v[242:245], v[8:11]
	v_mfma_f32_16x16x32_bf16 v[60:63], v[150:153], v[202:205], v[60:63]
	v_mfma_f32_16x16x32_bf16 v[56:59], v[158:161], v[202:205], v[56:59]
	v_mfma_f32_16x16x32_bf16 v[44:47], v[150:153], v[210:213], v[44:47]
	v_mfma_f32_16x16x32_bf16 v[40:43], v[158:161], v[210:213], v[40:43]
	v_mfma_f32_16x16x32_bf16 v[28:31], v[150:153], v[218:221], v[28:31]
	v_mfma_f32_16x16x32_bf16 v[24:27], v[158:161], v[218:221], v[24:27]
	v_mfma_f32_16x16x32_bf16 v[12:15], v[150:153], v[246:249], v[12:15]
	v_mfma_f32_16x16x32_bf16 v[8:11], v[158:161], v[246:249], v[8:11]
	v_mfma_f32_16x16x32_bf16 v[52:55], v[162:165], v[198:201], v[52:55]
	v_mfma_f32_16x16x32_bf16 v[48:51], v[190:193], v[198:201], v[48:51]
	v_mfma_f32_16x16x32_bf16 v[36:39], v[162:165], v[206:209], v[36:39]
	v_mfma_f32_16x16x32_bf16 v[32:35], v[190:193], v[206:209], v[32:35]
	v_mfma_f32_16x16x32_bf16 v[20:23], v[162:165], v[214:217], v[20:23]
	v_mfma_f32_16x16x32_bf16 v[16:19], v[190:193], v[214:217], v[16:19]
	v_mfma_f32_16x16x32_bf16 v[0:3], v[162:165], v[242:245], v[0:3]
	v_mfma_f32_16x16x32_bf16 v[4:7], v[190:193], v[242:245], v[4:7]
	v_mfma_f32_16x16x32_bf16 v[52:55], v[186:189], v[202:205], v[52:55]
	v_mfma_f32_16x16x32_bf16 v[48:51], v[194:197], v[202:205], v[48:51]
	v_mfma_f32_16x16x32_bf16 v[36:39], v[186:189], v[210:213], v[36:39]
	v_mfma_f32_16x16x32_bf16 v[32:35], v[194:197], v[210:213], v[32:35]
	v_mfma_f32_16x16x32_bf16 v[20:23], v[186:189], v[218:221], v[20:23]
	v_mfma_f32_16x16x32_bf16 v[16:19], v[194:197], v[218:221], v[16:19]
	v_mfma_f32_16x16x32_bf16 v[0:3], v[186:189], v[246:249], v[0:3]
	v_mfma_f32_16x16x32_bf16 v[4:7], v[194:197], v[246:249], v[4:7]
	s_setprio 0
	s_barrier
	s_cmp_ge_i32 s68, s59
	s_mov_b64 s[20:21], s[22:23]
	s_mov_b32 s26, s68
	s_cbranch_scc0 .LBB0_537
	v_readlane_b32 s78, v254, 17
	v_readlane_b32 s79, v254, 18

.LBB0_574:
	s_add_i32 s70, s26, 2
	s_add_u32 s27, s22, 0xfffe0080
	s_addc_u32 s50, s23, -1
	s_add_i32 s71, 0, 0x10000
	s_cmp_eq_u32 s64, s26
	s_cselect_b32 s51, s3, s50
	s_cselect_b32 s50, s21, s27
	s_cselect_b32 s27, s43, s69
	s_cselect_b32 s26, s45, s68
	s_add_i32 s74, 0, 0x14000
	v_add_u32_e32 v156, s71, v142
	v_add_u32_e32 v168, s74, v142
	ds_read_b128 v[144:147], v156
	ds_read_b128 v[148:151], v156 offset:1024
	ds_read_b128 v[152:155], v156 offset:2048
	ds_read_b128 v[156:159], v156 offset:3072
	ds_read_b128 v[160:163], v168
	ds_read_b128 v[164:167], v168 offset:1024
	ds_read_b128 v[186:189], v168 offset:2048
	ds_read_b128 v[190:193], v168 offset:3072
	v_lshl_add_u64 v[222:223], s[22:23], 0, v[136:137]
	s_add_i32 m0, s55, 0xc000
	ds_read_b128 v[194:197], v143
	ds_read_b128 v[198:201], v143 offset:1024
	ds_read_b128 v[202:205], v143 offset:2048
	ds_read_b128 v[206:209], v143 offset:3072
	ds_read_b128 v[210:213], v143 offset:4096
	ds_read_b128 v[214:217], v143 offset:5120
	ds_read_b128 v[218:221], v143 offset:6144
	ds_read_b128 v[242:245], v143 offset:7168
	global_load_lds_dwordx4 v[222:223], off
	v_lshl_add_u64 v[222:223], s[22:23], 0, v[138:139]
	s_add_i32 m0, s55, 0xe000
	s_nop 0
	global_load_lds_dwordx4 v[222:223], off
	s_waitcnt vmcnt(8)
	s_waitcnt lgkmcnt(0)
	s_barrier
	s_setprio 1
	s_waitcnt lgkmcnt(0)
	v_mfma_f32_16x16x32_bf16 v[124:127], v[144:147], v[194:197], v[124:127]
	v_mfma_f32_16x16x32_bf16 v[120:123], v[152:155], v[194:197], v[120:123]
	v_mfma_f32_16x16x32_bf16 v[108:111], v[144:147], v[202:205], v[108:111]
	v_mfma_f32_16x16x32_bf16 v[104:107], v[152:155], v[202:205], v[104:107]
	v_mfma_f32_16x16x32_bf16 v[92:95], v[144:147], v[210:213], v[92:95]
	v_mfma_f32_16x16x32_bf16 v[88:91], v[152:155], v[210:213], v[88:91]
	v_mfma_f32_16x16x32_bf16 v[76:79], v[144:147], v[218:221], v[76:79]
	v_mfma_f32_16x16x32_bf16 v[72:75], v[152:155], v[218:221], v[72:75]
	v_mfma_f32_16x16x32_bf16 v[124:127], v[148:151], v[198:201], v[124:127]
	v_mfma_f32_16x16x32_bf16 v[120:123], v[156:159], v[198:201], v[120:123]
	v_mfma_f32_16x16x32_bf16 v[108:111], v[148:151], v[206:209], v[108:111]
	v_mfma_f32_16x16x32_bf16 v[104:107], v[156:159], v[206:209], v[104:107]
	v_mfma_f32_16x16x32_bf16 v[92:95], v[148:151], v[214:217], v[92:95]
	v_mfma_f32_16x16x32_bf16 v[88:91], v[156:159], v[214:217], v[88:91]
	v_mfma_f32_16x16x32_bf16 v[76:79], v[148:151], v[242:245], v[76:79]
	v_mfma_f32_16x16x32_bf16 v[72:75], v[156:159], v[242:245], v[72:75]
	v_mfma_f32_16x16x32_bf16 v[116:119], v[160:163], v[194:197], v[116:119]
	v_mfma_f32_16x16x32_bf16 v[112:115], v[186:189], v[194:197], v[112:115]
	v_mfma_f32_16x16x32_bf16 v[100:103], v[160:163], v[202:205], v[100:103]
	v_mfma_f32_16x16x32_bf16 v[96:99], v[186:189], v[202:205], v[96:99]
	v_mfma_f32_16x16x32_bf16 v[84:87], v[160:163], v[210:213], v[84:87]
	v_mfma_f32_16x16x32_bf16 v[80:83], v[186:189], v[210:213], v[80:83]
	v_mfma_f32_16x16x32_bf16 v[68:71], v[160:163], v[218:221], v[68:71]
	v_mfma_f32_16x16x32_bf16 v[64:67], v[186:189], v[218:221], v[64:67]
	v_mfma_f32_16x16x32_bf16 v[116:119], v[164:167], v[198:201], v[116:119]
	v_mfma_f32_16x16x32_bf16 v[112:115], v[190:193], v[198:201], v[112:115]
	v_mfma_f32_16x16x32_bf16 v[100:103], v[164:167], v[206:209], v[100:103]
	v_mfma_f32_16x16x32_bf16 v[96:99], v[190:193], v[206:209], v[96:99]
	v_mfma_f32_16x16x32_bf16 v[84:87], v[164:167], v[214:217], v[84:87]
	v_mfma_f32_16x16x32_bf16 v[80:83], v[190:193], v[214:217], v[80:83]
	v_mfma_f32_16x16x32_bf16 v[68:71], v[164:167], v[242:245], v[68:71]
	v_mfma_f32_16x16x32_bf16 v[64:67], v[190:193], v[242:245], v[64:67]
	s_setprio 0
	s_barrier
	s_add_i32 s71, s71, s54
	v_lshl_add_u64 v[222:223], s[26:27], 0, v[130:131]
	s_mov_b32 m0, s71
	ds_read_b128 v[194:197], v143 offset:16384
	ds_read_b128 v[198:201], v143 offset:17408
	ds_read_b128 v[202:205], v143 offset:18432
	ds_read_b128 v[206:209], v143 offset:19456
	ds_read_b128 v[210:213], v143 offset:20480
	ds_read_b128 v[214:217], v143 offset:21504
	ds_read_b128 v[218:221], v143 offset:22528
	ds_read_b128 v[242:245], v143 offset:23552
	global_load_lds_dwordx4 v[222:223], off
	s_add_i32 m0, s71, 0x2000
	s_add_u32 s72, s26, 0x20000
	v_lshl_add_u64 v[236:237], s[26:27], 0, v[134:135]
	s_addc_u32 s73, s27, 0
	s_add_i32 s71, s74, s54
	global_load_lds_dwordx4 v[236:237], off
	v_lshl_add_u64 v[246:247], s[72:73], 0, v[130:131]
	s_mov_b32 m0, s71
	v_lshl_add_u64 v[248:249], s[50:51], 0, v[132:133]
	global_load_lds_dwordx4 v[246:247], off
	v_lshl_add_u64 v[246:247], s[72:73], 0, v[134:135]
	s_add_i32 m0, s71, 0x2000
	s_nop 0
	global_load_lds_dwordx4 v[246:247], off
	v_lshl_add_u64 v[246:247], s[50:51], 0, v[128:129]
	s_mov_b32 m0, s55
	s_nop 0
	global_load_lds_dwordx4 v[246:247], off
	s_mov_b32 m0, s56
	s_nop 0
	global_load_lds_dwordx4 v[248:249], off
	s_waitcnt vmcnt(8)
	s_waitcnt lgkmcnt(0)
	s_barrier
	s_setprio 1
	s_waitcnt lgkmcnt(0)
	v_mfma_f32_16x16x32_bf16 v[60:63], v[144:147], v[194:197], v[60:63]
	v_mfma_f32_16x16x32_bf16 v[56:59], v[152:155], v[194:197], v[56:59]
	v_mfma_f32_16x16x32_bf16 v[44:47], v[144:147], v[202:205], v[44:47]
	v_mfma_f32_16x16x32_bf16 v[40:43], v[152:155], v[202:205], v[40:43]
	v_mfma_f32_16x16x32_bf16 v[28:31], v[144:147], v[210:213], v[28:31]
	v_mfma_f32_16x16x32_bf16 v[24:27], v[152:155], v[210:213], v[24:27]
	v_mfma_f32_16x16x32_bf16 v[12:15], v[144:147], v[218:221], v[12:15]
	v_mfma_f32_16x16x32_bf16 v[8:11], v[152:155], v[218:221], v[8:11]
	v_mfma_f32_16x16x32_bf16 v[60:63], v[148:151], v[198:201], v[60:63]
	v_mfma_f32_16x16x32_bf16 v[56:59], v[156:159], v[198:201], v[56:59]
	v_mfma_f32_16x16x32_bf16 v[44:47], v[148:151], v[206:209], v[44:47]
	v_mfma_f32_16x16x32_bf16 v[40:43], v[156:159], v[206:209], v[40:43]
	v_mfma_f32_16x16x32_bf16 v[28:31], v[148:151], v[214:217], v[28:31]
	v_mfma_f32_16x16x32_bf16 v[24:27], v[156:159], v[214:217], v[24:27]
	v_mfma_f32_16x16x32_bf16 v[12:15], v[148:151], v[242:245], v[12:15]
	v_mfma_f32_16x16x32_bf16 v[8:11], v[156:159], v[242:245], v[8:11]
	v_mfma_f32_16x16x32_bf16 v[52:55], v[160:163], v[194:197], v[52:55]
	v_mfma_f32_16x16x32_bf16 v[48:51], v[186:189], v[194:197], v[48:51]
	v_mfma_f32_16x16x32_bf16 v[36:39], v[160:163], v[202:205], v[36:39]
	v_mfma_f32_16x16x32_bf16 v[32:35], v[186:189], v[202:205], v[32:35]
	v_mfma_f32_16x16x32_bf16 v[20:23], v[160:163], v[210:213], v[20:23]
	v_mfma_f32_16x16x32_bf16 v[16:19], v[186:189], v[210:213], v[16:19]
	v_mfma_f32_16x16x32_bf16 v[4:7], v[160:163], v[218:221], v[4:7]
	v_mfma_f32_16x16x32_bf16 v[0:3], v[186:189], v[218:221], v[0:3]
	v_mfma_f32_16x16x32_bf16 v[52:55], v[164:167], v[198:201], v[52:55]
	v_mfma_f32_16x16x32_bf16 v[48:51], v[190:193], v[198:201], v[48:51]
	v_mfma_f32_16x16x32_bf16 v[36:39], v[164:167], v[206:209], v[36:39]
	v_mfma_f32_16x16x32_bf16 v[32:35], v[190:193], v[206:209], v[32:35]
	v_mfma_f32_16x16x32_bf16 v[20:23], v[164:167], v[214:217], v[20:23]
	v_mfma_f32_16x16x32_bf16 v[16:19], v[190:193], v[214:217], v[16:19]
	v_mfma_f32_16x16x32_bf16 v[4:7], v[164:167], v[242:245], v[4:7]
	v_mfma_f32_16x16x32_bf16 v[0:3], v[190:193], v[242:245], v[0:3]
	s_setprio 0
	s_barrier
	s_add_i32 s71, 0, 0x18000
	s_add_i32 s72, 0, 0x1c000
	v_add_u32_e32 v156, s71, v142
	v_add_u32_e32 v168, s72, v142
	ds_read_b128 v[144:147], v156
	ds_read_b128 v[148:151], v156 offset:1024
	ds_read_b128 v[152:155], v156 offset:2048
	ds_read_b128 v[156:159], v156 offset:3072
	ds_read_b128 v[160:163], v168
	ds_read_b128 v[164:167], v168 offset:1024
	ds_read_b128 v[186:189], v168 offset:2048
	ds_read_b128 v[190:193], v168 offset:3072
	s_add_u32 s50, s50, 0x20000
	s_addc_u32 s51, s51, 0
	s_mov_b32 m0, s57
	v_lshl_add_u64 v[250:251], s[50:51], 0, v[128:129]
	ds_read_b128 v[194:197], v143 offset:32768
	ds_read_b128 v[198:201], v143 offset:33792
	ds_read_b128 v[202:205], v143 offset:34816
	ds_read_b128 v[206:209], v143 offset:35840
	ds_read_b128 v[210:213], v143 offset:36864
	ds_read_b128 v[214:217], v143 offset:37888
	ds_read_b128 v[218:221], v143 offset:38912
	ds_read_b128 v[242:245], v143 offset:39936
	global_load_lds_dwordx4 v[250:251], off
	v_lshl_add_u64 v[250:251], s[50:51], 0, v[132:133]
	s_mov_b32 m0, s58
	s_nop 0
	global_load_lds_dwordx4 v[250:251], off
	s_waitcnt vmcnt(8)
	s_waitcnt lgkmcnt(0)
	s_barrier
	s_setprio 1
	s_waitcnt lgkmcnt(0)
	v_mfma_f32_16x16x32_bf16 v[124:127], v[144:147], v[194:197], v[124:127]
	v_mfma_f32_16x16x32_bf16 v[120:123], v[152:155], v[194:197], v[120:123]
	v_mfma_f32_16x16x32_bf16 v[108:111], v[144:147], v[202:205], v[108:111]
	v_mfma_f32_16x16x32_bf16 v[104:107], v[152:155], v[202:205], v[104:107]
	v_mfma_f32_16x16x32_bf16 v[92:95], v[144:147], v[210:213], v[92:95]
	v_mfma_f32_16x16x32_bf16 v[88:91], v[152:155], v[210:213], v[88:91]
	v_mfma_f32_16x16x32_bf16 v[76:79], v[144:147], v[218:221], v[76:79]
	v_mfma_f32_16x16x32_bf16 v[72:75], v[152:155], v[218:221], v[72:75]
	v_mfma_f32_16x16x32_bf16 v[124:127], v[148:151], v[198:201], v[124:127]
	v_mfma_f32_16x16x32_bf16 v[120:123], v[156:159], v[198:201], v[120:123]
	v_mfma_f32_16x16x32_bf16 v[108:111], v[148:151], v[206:209], v[108:111]
	v_mfma_f32_16x16x32_bf16 v[104:107], v[156:159], v[206:209], v[104:107]
	v_mfma_f32_16x16x32_bf16 v[92:95], v[148:151], v[214:217], v[92:95]
	v_mfma_f32_16x16x32_bf16 v[88:91], v[156:159], v[214:217], v[88:91]
	v_mfma_f32_16x16x32_bf16 v[76:79], v[148:151], v[242:245], v[76:79]
	v_mfma_f32_16x16x32_bf16 v[72:75], v[156:159], v[242:245], v[72:75]
	v_mfma_f32_16x16x32_bf16 v[116:119], v[160:163], v[194:197], v[116:119]
	v_mfma_f32_16x16x32_bf16 v[112:115], v[186:189], v[194:197], v[112:115]
	v_mfma_f32_16x16x32_bf16 v[100:103], v[160:163], v[202:205], v[100:103]
	v_mfma_f32_16x16x32_bf16 v[96:99], v[186:189], v[202:205], v[96:99]
	v_mfma_f32_16x16x32_bf16 v[84:87], v[160:163], v[210:213], v[84:87]
	v_mfma_f32_16x16x32_bf16 v[80:83], v[186:189], v[210:213], v[80:83]
	v_mfma_f32_16x16x32_bf16 v[68:71], v[160:163], v[218:221], v[68:71]
	v_mfma_f32_16x16x32_bf16 v[64:67], v[186:189], v[218:221], v[64:67]
	v_mfma_f32_16x16x32_bf16 v[116:119], v[164:167], v[198:201], v[116:119]
	v_mfma_f32_16x16x32_bf16 v[112:115], v[190:193], v[198:201], v[112:115]
	v_mfma_f32_16x16x32_bf16 v[100:103], v[164:167], v[206:209], v[100:103]
	v_mfma_f32_16x16x32_bf16 v[96:99], v[190:193], v[206:209], v[96:99]
	v_mfma_f32_16x16x32_bf16 v[84:87], v[164:167], v[214:217], v[84:87]
	v_mfma_f32_16x16x32_bf16 v[80:83], v[190:193], v[214:217], v[80:83]
	v_mfma_f32_16x16x32_bf16 v[68:71], v[164:167], v[242:245], v[68:71]
	v_mfma_f32_16x16x32_bf16 v[64:67], v[190:193], v[242:245], v[64:67]
	s_setprio 0
	s_barrier
	s_add_i32 s50, s71, s54
	v_lshl_add_u64 v[222:223], v[222:223], 0, s[28:29]
	s_mov_b32 m0, s50
	ds_read_b128 v[194:197], v143 offset:49152
	ds_read_b128 v[198:201], v143 offset:50176
	ds_read_b128 v[202:205], v143 offset:51200
	ds_read_b128 v[206:209], v143 offset:52224
	ds_read_b128 v[210:213], v143 offset:53248
	ds_read_b128 v[214:217], v143 offset:54272
	ds_read_b128 v[218:221], v143 offset:55296
	ds_read_b128 v[242:245], v143 offset:56320
	global_load_lds_dwordx4 v[222:223], off
	s_add_i32 m0, s50, 0x2000
	s_add_u32 s26, s26, 0x20080
	v_lshl_add_u64 v[222:223], v[236:237], 0, s[28:29]
	s_addc_u32 s27, s27, 0
	s_add_i32 s50, s72, s54
	global_load_lds_dwordx4 v[222:223], off
	v_lshl_add_u64 v[222:223], s[26:27], 0, v[130:131]
	s_mov_b32 m0, s50
	s_nop 0
	global_load_lds_dwordx4 v[222:223], off
	v_lshl_add_u64 v[222:223], s[26:27], 0, v[134:135]
	s_add_i32 m0, s50, 0x2000
	s_nop 0
	global_load_lds_dwordx4 v[222:223], off
	v_lshl_add_u64 v[222:223], v[246:247], 0, s[28:29]
	s_mov_b32 m0, s62
	s_nop 0
	global_load_lds_dwordx4 v[222:223], off
	v_lshl_add_u64 v[222:223], v[248:249], 0, s[28:29]
	s_mov_b32 m0, s63
	s_nop 0
	global_load_lds_dwordx4 v[222:223], off
	s_waitcnt vmcnt(8)
	s_waitcnt lgkmcnt(0)
	s_barrier
	s_setprio 1
	s_waitcnt lgkmcnt(0)
	v_mfma_f32_16x16x32_bf16 v[60:63], v[144:147], v[194:197], v[60:63]
	v_mfma_f32_16x16x32_bf16 v[56:59], v[152:155], v[194:197], v[56:59]
	v_mfma_f32_16x16x32_bf16 v[44:47], v[144:147], v[202:205], v[44:47]
	v_mfma_f32_16x16x32_bf16 v[40:43], v[152:155], v[202:205], v[40:43]
	v_mfma_f32_16x16x32_bf16 v[28:31], v[144:147], v[210:213], v[28:31]
	v_mfma_f32_16x16x32_bf16 v[24:27], v[152:155], v[210:213], v[24:27]
	v_mfma_f32_16x16x32_bf16 v[12:15], v[144:147], v[218:221], v[12:15]
	v_mfma_f32_16x16x32_bf16 v[8:11], v[152:155], v[218:221], v[8:11]
	v_mfma_f32_16x16x32_bf16 v[60:63], v[148:151], v[198:201], v[60:63]
	v_mfma_f32_16x16x32_bf16 v[56:59], v[156:159], v[198:201], v[56:59]
	v_mfma_f32_16x16x32_bf16 v[44:47], v[148:151], v[206:209], v[44:47]
	v_mfma_f32_16x16x32_bf16 v[40:43], v[156:159], v[206:209], v[40:43]
	v_mfma_f32_16x16x32_bf16 v[28:31], v[148:151], v[214:217], v[28:31]
	v_mfma_f32_16x16x32_bf16 v[24:27], v[156:159], v[214:217], v[24:27]
	v_mfma_f32_16x16x32_bf16 v[12:15], v[148:151], v[242:245], v[12:15]
	v_mfma_f32_16x16x32_bf16 v[8:11], v[156:159], v[242:245], v[8:11]
	v_mfma_f32_16x16x32_bf16 v[52:55], v[160:163], v[194:197], v[52:55]
	v_mfma_f32_16x16x32_bf16 v[48:51], v[186:189], v[194:197], v[48:51]
	v_mfma_f32_16x16x32_bf16 v[36:39], v[160:163], v[202:205], v[36:39]
	v_mfma_f32_16x16x32_bf16 v[32:35], v[186:189], v[202:205], v[32:35]
	v_mfma_f32_16x16x32_bf16 v[20:23], v[160:163], v[210:213], v[20:23]
	v_mfma_f32_16x16x32_bf16 v[16:19], v[186:189], v[210:213], v[16:19]
	v_mfma_f32_16x16x32_bf16 v[4:7], v[160:163], v[218:221], v[4:7]
	v_mfma_f32_16x16x32_bf16 v[0:3], v[186:189], v[218:221], v[0:3]
	v_mfma_f32_16x16x32_bf16 v[52:55], v[164:167], v[198:201], v[52:55]
	v_mfma_f32_16x16x32_bf16 v[48:51], v[190:193], v[198:201], v[48:51]
	v_mfma_f32_16x16x32_bf16 v[36:39], v[164:167], v[206:209], v[36:39]
	v_mfma_f32_16x16x32_bf16 v[32:35], v[190:193], v[206:209], v[32:35]
	v_mfma_f32_16x16x32_bf16 v[20:23], v[164:167], v[214:217], v[20:23]
	v_mfma_f32_16x16x32_bf16 v[16:19], v[190:193], v[214:217], v[16:19]
	v_mfma_f32_16x16x32_bf16 v[4:7], v[164:167], v[242:245], v[4:7]
	v_mfma_f32_16x16x32_bf16 v[0:3], v[190:193], v[242:245], v[0:3]
	s_setprio 0
	s_barrier
	s_add_u32 s22, s22, 0x100
	s_addc_u32 s23, s23, 0
	s_add_u32 s68, s68, 0x100
	s_addc_u32 s69, s69, 0
	s_cmp_ge_i32 s70, s59
	s_mov_b32 s26, s70
	s_cbranch_scc0 .LBB0_574

.LBB0_630:
	s_add_i32 s70, s41, 2
	s_add_u32 s48, s0, 0xfffe0080
	s_addc_u32 s49, s1, -1
	s_add_i32 s71, 0, 0x10000
	s_cmp_eq_u32 s64, s41
	s_cselect_b32 s51, s43, s49
	s_cselect_b32 s50, s42, s48
	s_cselect_b32 s49, s45, s27
	s_cselect_b32 s48, s44, s3
	s_add_i32 s41, 0, 0x14000
	v_add_u32_e32 v154, s71, v148
	v_add_u32_e32 v166, s41, v148
	ds_read_b128 v[138:141], v154
	ds_read_b128 v[142:145], v154 offset:1024
	ds_read_b128 v[150:153], v154 offset:2048
	ds_read_b128 v[154:157], v154 offset:3072
	ds_read_b128 v[158:161], v166
	ds_read_b128 v[162:165], v166 offset:1024
	ds_read_b128 v[186:189], v166 offset:2048
	ds_read_b128 v[190:193], v166 offset:3072
	v_lshl_add_u64 v[166:167], s[0:1], 0, v[134:135]
	s_add_i32 m0, s47, 0xc000
	ds_read_b128 v[194:197], v149
	ds_read_b128 v[198:201], v149 offset:1024
	ds_read_b128 v[202:205], v149 offset:2048
	ds_read_b128 v[206:209], v149 offset:3072
	ds_read_b128 v[210:213], v149 offset:4096
	ds_read_b128 v[214:217], v149 offset:5120
	ds_read_b128 v[218:221], v149 offset:6144
	ds_read_b128 v[242:245], v149 offset:7168
	global_load_lds_dwordx4 v[166:167], off
	v_lshl_add_u64 v[166:167], s[0:1], 0, v[136:137]
	s_add_i32 m0, s47, 0xe000
	s_nop 0
	global_load_lds_dwordx4 v[166:167], off
	s_waitcnt vmcnt(8)
	s_waitcnt lgkmcnt(0)
	s_barrier
	s_setprio 1
	s_waitcnt lgkmcnt(0)
	v_mfma_f32_16x16x32_bf16 v[124:127], v[138:141], v[194:197], v[124:127]
	v_mfma_f32_16x16x32_bf16 v[120:123], v[150:153], v[194:197], v[120:123]
	v_mfma_f32_16x16x32_bf16 v[108:111], v[138:141], v[202:205], v[108:111]
	v_mfma_f32_16x16x32_bf16 v[104:107], v[150:153], v[202:205], v[104:107]
	v_mfma_f32_16x16x32_bf16 v[92:95], v[138:141], v[210:213], v[92:95]
	v_mfma_f32_16x16x32_bf16 v[88:91], v[150:153], v[210:213], v[88:91]
	v_mfma_f32_16x16x32_bf16 v[76:79], v[138:141], v[218:221], v[76:79]
	v_mfma_f32_16x16x32_bf16 v[72:75], v[150:153], v[218:221], v[72:75]
	v_mfma_f32_16x16x32_bf16 v[124:127], v[142:145], v[198:201], v[124:127]
	v_mfma_f32_16x16x32_bf16 v[120:123], v[154:157], v[198:201], v[120:123]
	v_mfma_f32_16x16x32_bf16 v[108:111], v[142:145], v[206:209], v[108:111]
	v_mfma_f32_16x16x32_bf16 v[104:107], v[154:157], v[206:209], v[104:107]
	v_mfma_f32_16x16x32_bf16 v[92:95], v[142:145], v[214:217], v[92:95]
	v_mfma_f32_16x16x32_bf16 v[88:91], v[154:157], v[214:217], v[88:91]
	v_mfma_f32_16x16x32_bf16 v[76:79], v[142:145], v[242:245], v[76:79]
	v_mfma_f32_16x16x32_bf16 v[72:75], v[154:157], v[242:245], v[72:75]
	v_mfma_f32_16x16x32_bf16 v[116:119], v[158:161], v[194:197], v[116:119]
	v_mfma_f32_16x16x32_bf16 v[112:115], v[186:189], v[194:197], v[112:115]
	v_mfma_f32_16x16x32_bf16 v[100:103], v[158:161], v[202:205], v[100:103]
	v_mfma_f32_16x16x32_bf16 v[96:99], v[186:189], v[202:205], v[96:99]
	v_mfma_f32_16x16x32_bf16 v[84:87], v[158:161], v[210:213], v[84:87]
	v_mfma_f32_16x16x32_bf16 v[80:83], v[186:189], v[210:213], v[80:83]
	v_mfma_f32_16x16x32_bf16 v[68:71], v[158:161], v[218:221], v[68:71]
	v_mfma_f32_16x16x32_bf16 v[64:67], v[186:189], v[218:221], v[64:67]
	v_mfma_f32_16x16x32_bf16 v[116:119], v[162:165], v[198:201], v[116:119]
	v_mfma_f32_16x16x32_bf16 v[112:115], v[190:193], v[198:201], v[112:115]
	v_mfma_f32_16x16x32_bf16 v[100:103], v[162:165], v[206:209], v[100:103]
	v_mfma_f32_16x16x32_bf16 v[96:99], v[190:193], v[206:209], v[96:99]
	v_mfma_f32_16x16x32_bf16 v[84:87], v[162:165], v[214:217], v[84:87]
	v_mfma_f32_16x16x32_bf16 v[80:83], v[190:193], v[214:217], v[80:83]
	v_mfma_f32_16x16x32_bf16 v[68:71], v[162:165], v[242:245], v[68:71]
	v_mfma_f32_16x16x32_bf16 v[64:67], v[190:193], v[242:245], v[64:67]
	s_setprio 0
	s_barrier
	s_add_i32 s71, s71, s53
	v_lshl_add_u64 v[166:167], s[48:49], 0, v[168:169]
	s_mov_b32 m0, s71
	ds_read_b128 v[194:197], v149 offset:16384
	ds_read_b128 v[198:201], v149 offset:17408
	ds_read_b128 v[202:205], v149 offset:18432
	ds_read_b128 v[206:209], v149 offset:19456
	ds_read_b128 v[210:213], v149 offset:20480
	ds_read_b128 v[214:217], v149 offset:21504
	ds_read_b128 v[218:221], v149 offset:22528
	ds_read_b128 v[242:245], v149 offset:23552
	global_load_lds_dwordx4 v[166:167], off
	s_add_i32 m0, s71, 0x2000
	s_add_u32 s72, s48, 0x10000
	v_lshl_add_u64 v[222:223], s[48:49], 0, v[132:133]
	s_addc_u32 s73, s49, 0
	s_add_i32 s41, s41, s53
	global_load_lds_dwordx4 v[222:223], off
	v_lshl_add_u64 v[236:237], s[72:73], 0, v[168:169]
	s_mov_b32 m0, s41
	v_lshl_add_u64 v[246:247], s[50:51], 0, v[130:131]
	global_load_lds_dwordx4 v[236:237], off
	v_lshl_add_u64 v[236:237], s[72:73], 0, v[132:133]
	s_add_i32 m0, s41, 0x2000
	s_nop 0
	global_load_lds_dwordx4 v[236:237], off
	v_lshl_add_u64 v[236:237], s[50:51], 0, v[128:129]
	s_mov_b32 m0, s47
	s_nop 0
	global_load_lds_dwordx4 v[236:237], off
	s_mov_b32 m0, s54
	s_nop 0
	global_load_lds_dwordx4 v[246:247], off
	s_waitcnt vmcnt(8)
	s_waitcnt lgkmcnt(0)
	s_barrier
	s_setprio 1
	s_waitcnt lgkmcnt(0)
	v_mfma_f32_16x16x32_bf16 v[60:63], v[138:141], v[194:197], v[60:63]
	v_mfma_f32_16x16x32_bf16 v[56:59], v[150:153], v[194:197], v[56:59]
	v_mfma_f32_16x16x32_bf16 v[44:47], v[138:141], v[202:205], v[44:47]
	v_mfma_f32_16x16x32_bf16 v[40:43], v[150:153], v[202:205], v[40:43]
	v_mfma_f32_16x16x32_bf16 v[28:31], v[138:141], v[210:213], v[28:31]
	v_mfma_f32_16x16x32_bf16 v[24:27], v[150:153], v[210:213], v[24:27]
	v_mfma_f32_16x16x32_bf16 v[12:15], v[138:141], v[218:221], v[12:15]
	v_mfma_f32_16x16x32_bf16 v[8:11], v[150:153], v[218:221], v[8:11]
	v_mfma_f32_16x16x32_bf16 v[60:63], v[142:145], v[198:201], v[60:63]
	v_mfma_f32_16x16x32_bf16 v[56:59], v[154:157], v[198:201], v[56:59]
	v_mfma_f32_16x16x32_bf16 v[44:47], v[142:145], v[206:209], v[44:47]
	v_mfma_f32_16x16x32_bf16 v[40:43], v[154:157], v[206:209], v[40:43]
	v_mfma_f32_16x16x32_bf16 v[28:31], v[142:145], v[214:217], v[28:31]
	v_mfma_f32_16x16x32_bf16 v[24:27], v[154:157], v[214:217], v[24:27]
	v_mfma_f32_16x16x32_bf16 v[12:15], v[142:145], v[242:245], v[12:15]
	v_mfma_f32_16x16x32_bf16 v[8:11], v[154:157], v[242:245], v[8:11]
	v_mfma_f32_16x16x32_bf16 v[52:55], v[158:161], v[194:197], v[52:55]
	v_mfma_f32_16x16x32_bf16 v[48:51], v[186:189], v[194:197], v[48:51]
	v_mfma_f32_16x16x32_bf16 v[36:39], v[158:161], v[202:205], v[36:39]
	v_mfma_f32_16x16x32_bf16 v[32:35], v[186:189], v[202:205], v[32:35]
	v_mfma_f32_16x16x32_bf16 v[20:23], v[158:161], v[210:213], v[20:23]
	v_mfma_f32_16x16x32_bf16 v[16:19], v[186:189], v[210:213], v[16:19]
	v_mfma_f32_16x16x32_bf16 v[4:7], v[158:161], v[218:221], v[4:7]
	v_mfma_f32_16x16x32_bf16 v[0:3], v[186:189], v[218:221], v[0:3]
	v_mfma_f32_16x16x32_bf16 v[52:55], v[162:165], v[198:201], v[52:55]
	v_mfma_f32_16x16x32_bf16 v[48:51], v[190:193], v[198:201], v[48:51]
	v_mfma_f32_16x16x32_bf16 v[36:39], v[162:165], v[206:209], v[36:39]
	v_mfma_f32_16x16x32_bf16 v[32:35], v[190:193], v[206:209], v[32:35]
	v_mfma_f32_16x16x32_bf16 v[20:23], v[162:165], v[214:217], v[20:23]
	v_mfma_f32_16x16x32_bf16 v[16:19], v[190:193], v[214:217], v[16:19]
	v_mfma_f32_16x16x32_bf16 v[4:7], v[162:165], v[242:245], v[4:7]
	v_mfma_f32_16x16x32_bf16 v[0:3], v[190:193], v[242:245], v[0:3]
	s_setprio 0
	s_barrier
	s_add_i32 s41, 0, 0x18000
	s_add_i32 s71, 0, 0x1c000
	v_add_u32_e32 v154, s41, v148
	v_add_u32_e32 v179, s71, v148
	ds_read_b128 v[138:141], v154
	ds_read_b128 v[142:145], v154 offset:1024
	ds_read_b128 v[150:153], v154 offset:2048
	ds_read_b128 v[154:157], v154 offset:3072
	ds_read_b128 v[158:161], v179
	ds_read_b128 v[162:165], v179 offset:1024
	ds_read_b128 v[186:189], v179 offset:2048
	ds_read_b128 v[190:193], v179 offset:3072
	s_add_u32 s50, s50, 0x20000
	s_addc_u32 s51, s51, 0
	s_mov_b32 m0, s55
	v_lshl_add_u64 v[248:249], s[50:51], 0, v[128:129]
	ds_read_b128 v[194:197], v149 offset:32768
	ds_read_b128 v[198:201], v149 offset:33792
	ds_read_b128 v[202:205], v149 offset:34816
	ds_read_b128 v[206:209], v149 offset:35840
	ds_read_b128 v[210:213], v149 offset:36864
	ds_read_b128 v[214:217], v149 offset:37888
	ds_read_b128 v[218:221], v149 offset:38912
	ds_read_b128 v[242:245], v149 offset:39936
	global_load_lds_dwordx4 v[248:249], off
	v_lshl_add_u64 v[248:249], s[50:51], 0, v[130:131]
	s_mov_b32 m0, s56
	s_nop 0
	global_load_lds_dwordx4 v[248:249], off
	s_waitcnt vmcnt(8)
	s_waitcnt lgkmcnt(0)
	s_barrier
	s_setprio 1
	s_waitcnt lgkmcnt(0)
	v_mfma_f32_16x16x32_bf16 v[124:127], v[138:141], v[194:197], v[124:127]
	v_mfma_f32_16x16x32_bf16 v[120:123], v[150:153], v[194:197], v[120:123]
	v_mfma_f32_16x16x32_bf16 v[108:111], v[138:141], v[202:205], v[108:111]
	v_mfma_f32_16x16x32_bf16 v[104:107], v[150:153], v[202:205], v[104:107]
	v_mfma_f32_16x16x32_bf16 v[92:95], v[138:141], v[210:213], v[92:95]
	v_mfma_f32_16x16x32_bf16 v[88:91], v[150:153], v[210:213], v[88:91]
	v_mfma_f32_16x16x32_bf16 v[76:79], v[138:141], v[218:221], v[76:79]
	v_mfma_f32_16x16x32_bf16 v[72:75], v[150:153], v[218:221], v[72:75]
	v_mfma_f32_16x16x32_bf16 v[124:127], v[142:145], v[198:201], v[124:127]
	v_mfma_f32_16x16x32_bf16 v[120:123], v[154:157], v[198:201], v[120:123]
	v_mfma_f32_16x16x32_bf16 v[108:111], v[142:145], v[206:209], v[108:111]
	v_mfma_f32_16x16x32_bf16 v[104:107], v[154:157], v[206:209], v[104:107]
	v_mfma_f32_16x16x32_bf16 v[92:95], v[142:145], v[214:217], v[92:95]
	v_mfma_f32_16x16x32_bf16 v[88:91], v[154:157], v[214:217], v[88:91]
	v_mfma_f32_16x16x32_bf16 v[76:79], v[142:145], v[242:245], v[76:79]
	v_mfma_f32_16x16x32_bf16 v[72:75], v[154:157], v[242:245], v[72:75]
	v_mfma_f32_16x16x32_bf16 v[116:119], v[158:161], v[194:197], v[116:119]
	v_mfma_f32_16x16x32_bf16 v[112:115], v[186:189], v[194:197], v[112:115]
	v_mfma_f32_16x16x32_bf16 v[100:103], v[158:161], v[202:205], v[100:103]
	v_mfma_f32_16x16x32_bf16 v[96:99], v[186:189], v[202:205], v[96:99]
	v_mfma_f32_16x16x32_bf16 v[84:87], v[158:161], v[210:213], v[84:87]
	v_mfma_f32_16x16x32_bf16 v[80:83], v[186:189], v[210:213], v[80:83]
	v_mfma_f32_16x16x32_bf16 v[68:71], v[158:161], v[218:221], v[68:71]
	v_mfma_f32_16x16x32_bf16 v[64:67], v[186:189], v[218:221], v[64:67]
	v_mfma_f32_16x16x32_bf16 v[116:119], v[162:165], v[198:201], v[116:119]
	v_mfma_f32_16x16x32_bf16 v[112:115], v[190:193], v[198:201], v[112:115]
	v_mfma_f32_16x16x32_bf16 v[100:103], v[162:165], v[206:209], v[100:103]
	v_mfma_f32_16x16x32_bf16 v[96:99], v[190:193], v[206:209], v[96:99]
	v_mfma_f32_16x16x32_bf16 v[84:87], v[162:165], v[214:217], v[84:87]
	v_mfma_f32_16x16x32_bf16 v[80:83], v[190:193], v[214:217], v[80:83]
	v_mfma_f32_16x16x32_bf16 v[68:71], v[162:165], v[242:245], v[68:71]
	v_mfma_f32_16x16x32_bf16 v[64:67], v[190:193], v[242:245], v[64:67]
	s_setprio 0
	s_barrier
	s_add_i32 s41, s41, s53
	v_lshl_add_u64 v[166:167], v[166:167], 0, s[28:29]
	s_mov_b32 m0, s41
	ds_read_b128 v[194:197], v149 offset:49152
	ds_read_b128 v[198:201], v149 offset:50176
	ds_read_b128 v[202:205], v149 offset:51200
	ds_read_b128 v[206:209], v149 offset:52224
	ds_read_b128 v[210:213], v149 offset:53248
	ds_read_b128 v[214:217], v149 offset:54272
	ds_read_b128 v[218:221], v149 offset:55296
	ds_read_b128 v[242:245], v149 offset:56320
	global_load_lds_dwordx4 v[166:167], off
	s_add_i32 m0, s41, 0x2000
	s_add_u32 s48, s48, 0x10080
	v_lshl_add_u64 v[166:167], v[222:223], 0, s[28:29]
	s_addc_u32 s49, s49, 0
	s_add_i32 s41, s71, s53
	global_load_lds_dwordx4 v[166:167], off
	v_lshl_add_u64 v[166:167], s[48:49], 0, v[168:169]
	s_mov_b32 m0, s41
	s_nop 0
	global_load_lds_dwordx4 v[166:167], off
	v_lshl_add_u64 v[166:167], s[48:49], 0, v[132:133]
	s_add_i32 m0, s41, 0x2000
	s_nop 0
	global_load_lds_dwordx4 v[166:167], off
	v_lshl_add_u64 v[166:167], v[236:237], 0, s[28:29]
	s_mov_b32 m0, s62
	s_nop 0
	global_load_lds_dwordx4 v[166:167], off
	v_lshl_add_u64 v[166:167], v[246:247], 0, s[28:29]
	s_mov_b32 m0, s63
	s_nop 0
	global_load_lds_dwordx4 v[166:167], off
	s_waitcnt vmcnt(8)
	s_waitcnt lgkmcnt(0)
	s_barrier
	s_setprio 1
	s_waitcnt lgkmcnt(0)
	v_mfma_f32_16x16x32_bf16 v[60:63], v[138:141], v[194:197], v[60:63]
	v_mfma_f32_16x16x32_bf16 v[56:59], v[150:153], v[194:197], v[56:59]
	v_mfma_f32_16x16x32_bf16 v[44:47], v[138:141], v[202:205], v[44:47]
	v_mfma_f32_16x16x32_bf16 v[40:43], v[150:153], v[202:205], v[40:43]
	v_mfma_f32_16x16x32_bf16 v[28:31], v[138:141], v[210:213], v[28:31]
	v_mfma_f32_16x16x32_bf16 v[24:27], v[150:153], v[210:213], v[24:27]
	v_mfma_f32_16x16x32_bf16 v[12:15], v[138:141], v[218:221], v[12:15]
	v_mfma_f32_16x16x32_bf16 v[8:11], v[150:153], v[218:221], v[8:11]
	v_mfma_f32_16x16x32_bf16 v[60:63], v[142:145], v[198:201], v[60:63]
	v_mfma_f32_16x16x32_bf16 v[56:59], v[154:157], v[198:201], v[56:59]
	v_mfma_f32_16x16x32_bf16 v[44:47], v[142:145], v[206:209], v[44:47]
	v_mfma_f32_16x16x32_bf16 v[40:43], v[154:157], v[206:209], v[40:43]
	v_mfma_f32_16x16x32_bf16 v[28:31], v[142:145], v[214:217], v[28:31]
	v_mfma_f32_16x16x32_bf16 v[24:27], v[154:157], v[214:217], v[24:27]
	v_mfma_f32_16x16x32_bf16 v[12:15], v[142:145], v[242:245], v[12:15]
	v_mfma_f32_16x16x32_bf16 v[8:11], v[154:157], v[242:245], v[8:11]
	v_mfma_f32_16x16x32_bf16 v[52:55], v[158:161], v[194:197], v[52:55]
	v_mfma_f32_16x16x32_bf16 v[48:51], v[186:189], v[194:197], v[48:51]
	v_mfma_f32_16x16x32_bf16 v[36:39], v[158:161], v[202:205], v[36:39]
	v_mfma_f32_16x16x32_bf16 v[32:35], v[186:189], v[202:205], v[32:35]
	v_mfma_f32_16x16x32_bf16 v[20:23], v[158:161], v[210:213], v[20:23]
	v_mfma_f32_16x16x32_bf16 v[16:19], v[186:189], v[210:213], v[16:19]
	v_mfma_f32_16x16x32_bf16 v[4:7], v[158:161], v[218:221], v[4:7]
	v_mfma_f32_16x16x32_bf16 v[0:3], v[186:189], v[218:221], v[0:3]
	v_mfma_f32_16x16x32_bf16 v[52:55], v[162:165], v[198:201], v[52:55]
	v_mfma_f32_16x16x32_bf16 v[48:51], v[190:193], v[198:201], v[48:51]
	v_mfma_f32_16x16x32_bf16 v[36:39], v[162:165], v[206:209], v[36:39]
	v_mfma_f32_16x16x32_bf16 v[32:35], v[190:193], v[206:209], v[32:35]
	v_mfma_f32_16x16x32_bf16 v[20:23], v[162:165], v[214:217], v[20:23]
	v_mfma_f32_16x16x32_bf16 v[16:19], v[190:193], v[214:217], v[16:19]
	v_mfma_f32_16x16x32_bf16 v[4:7], v[162:165], v[242:245], v[4:7]
	v_mfma_f32_16x16x32_bf16 v[0:3], v[190:193], v[242:245], v[0:3]
	s_setprio 0
	s_barrier
	s_add_u32 s0, s0, 0x100
	s_addc_u32 s1, s1, 0
	s_add_u32 s3, s3, 0x100
	s_addc_u32 s27, s27, 0
	s_cmp_ge_i32 s70, s59
	s_mov_b32 s41, s70
	s_cbranch_scc0 .LBB0_630

.LBB0_853:
	s_add_i32 s72, s22, 2
	s_add_u32 s23, s20, 0xfffc0080
	s_addc_u32 s26, s21, -1
	s_add_i32 s73, 0, 0x10000
	s_cmp_eq_u32 s68, s22
	s_cselect_b32 s27, s1, s26
	s_cselect_b32 s26, s40, s23
	s_cselect_b32 s23, s41, s71
	s_cselect_b32 s22, s53, s55
	s_add_i32 s76, 0, 0x14000
	v_add_u32_e32 v92, s73, v211
	v_add_u32_e32 v108, s76, v211
	ds_read_b128 v[80:83], v92
	ds_read_b128 v[84:87], v92 offset:1024
	ds_read_b128 v[88:91], v92 offset:2048
	ds_read_b128 v[92:95], v92 offset:3072
	ds_read_b128 v[96:99], v108
	ds_read_b128 v[100:103], v108 offset:1024
	ds_read_b128 v[104:107], v108 offset:2048
	ds_read_b128 v[108:111], v108 offset:3072
	v_lshl_add_u64 v[208:209], s[20:21], 0, v[192:193]
	s_add_i32 m0, s3, 0xc000
	ds_read_b128 v[160:163], v212
	ds_read_b128 v[164:167], v212 offset:1024
	ds_read_b128 v[196:199], v212 offset:2048
	ds_read_b128 v[200:203], v212 offset:3072
	ds_read_b128 v[204:207], v212 offset:4096
	ds_read_b128 v[214:217], v212 offset:5120
	ds_read_b128 v[218:221], v212 offset:6144
	ds_read_b128 v[242:245], v212 offset:7168
	global_load_lds_dwordx4 v[208:209], off
	v_lshl_add_u64 v[208:209], s[20:21], 0, v[194:195]
	s_add_i32 m0, s3, 0xe000
	s_nop 0
	global_load_lds_dwordx4 v[208:209], off
	s_waitcnt vmcnt(8)
	s_waitcnt lgkmcnt(0)
	s_barrier
	s_setprio 1
	s_waitcnt lgkmcnt(0)
	v_mfma_f32_16x16x32_bf16 v[156:159], v[80:83], v[160:163], v[156:159]
	v_mfma_f32_16x16x32_bf16 v[152:155], v[88:91], v[160:163], v[152:155]
	v_mfma_f32_16x16x32_bf16 v[140:143], v[80:83], v[196:199], v[140:143]
	v_mfma_f32_16x16x32_bf16 v[136:139], v[88:91], v[196:199], v[136:139]
	v_mfma_f32_16x16x32_bf16 v[124:127], v[80:83], v[204:207], v[124:127]
	v_mfma_f32_16x16x32_bf16 v[120:123], v[88:91], v[204:207], v[120:123]
	v_mfma_f32_16x16x32_bf16 v[76:79], v[80:83], v[218:221], v[76:79]
	v_mfma_f32_16x16x32_bf16 v[72:75], v[88:91], v[218:221], v[72:75]
	v_mfma_f32_16x16x32_bf16 v[156:159], v[84:87], v[164:167], v[156:159]
	v_mfma_f32_16x16x32_bf16 v[152:155], v[92:95], v[164:167], v[152:155]
	v_mfma_f32_16x16x32_bf16 v[140:143], v[84:87], v[200:203], v[140:143]
	v_mfma_f32_16x16x32_bf16 v[136:139], v[92:95], v[200:203], v[136:139]
	v_mfma_f32_16x16x32_bf16 v[124:127], v[84:87], v[214:217], v[124:127]
	v_mfma_f32_16x16x32_bf16 v[120:123], v[92:95], v[214:217], v[120:123]
	v_mfma_f32_16x16x32_bf16 v[76:79], v[84:87], v[242:245], v[76:79]
	v_mfma_f32_16x16x32_bf16 v[72:75], v[92:95], v[242:245], v[72:75]
	v_mfma_f32_16x16x32_bf16 v[148:151], v[96:99], v[160:163], v[148:151]
	v_mfma_f32_16x16x32_bf16 v[144:147], v[104:107], v[160:163], v[144:147]
	v_mfma_f32_16x16x32_bf16 v[132:135], v[96:99], v[196:199], v[132:135]
	v_mfma_f32_16x16x32_bf16 v[128:131], v[104:107], v[196:199], v[128:131]
	v_mfma_f32_16x16x32_bf16 v[116:119], v[96:99], v[204:207], v[116:119]
	v_mfma_f32_16x16x32_bf16 v[112:115], v[104:107], v[204:207], v[112:115]
	v_mfma_f32_16x16x32_bf16 v[68:71], v[96:99], v[218:221], v[68:71]
	v_mfma_f32_16x16x32_bf16 v[64:67], v[104:107], v[218:221], v[64:67]
	v_mfma_f32_16x16x32_bf16 v[148:151], v[100:103], v[164:167], v[148:151]
	v_mfma_f32_16x16x32_bf16 v[144:147], v[108:111], v[164:167], v[144:147]
	v_mfma_f32_16x16x32_bf16 v[132:135], v[100:103], v[200:203], v[132:135]
	v_mfma_f32_16x16x32_bf16 v[128:131], v[108:111], v[200:203], v[128:131]
	v_mfma_f32_16x16x32_bf16 v[116:119], v[100:103], v[214:217], v[116:119]
	v_mfma_f32_16x16x32_bf16 v[112:115], v[108:111], v[214:217], v[112:115]
	v_mfma_f32_16x16x32_bf16 v[68:71], v[100:103], v[242:245], v[68:71]
	v_mfma_f32_16x16x32_bf16 v[64:67], v[108:111], v[242:245], v[64:67]
	s_setprio 0
	s_barrier
	s_add_i32 s73, s73, s34
	v_lshl_add_u64 v[208:209], s[22:23], 0, v[168:169]
	s_mov_b32 m0, s73
	ds_read_b128 v[160:163], v212 offset:16384
	ds_read_b128 v[164:167], v212 offset:17408
	ds_read_b128 v[196:199], v212 offset:18432
	ds_read_b128 v[200:203], v212 offset:19456
	ds_read_b128 v[204:207], v212 offset:20480
	ds_read_b128 v[214:217], v212 offset:21504
	ds_read_b128 v[218:221], v212 offset:22528
	ds_read_b128 v[242:245], v212 offset:23552
	global_load_lds_dwordx4 v[208:209], off
	s_add_i32 m0, s73, 0x2000
	s_add_u32 s74, s22, 0x40000
	v_lshl_add_u64 v[222:223], s[22:23], 0, v[190:191]
	s_addc_u32 s75, s23, 0
	s_add_i32 s73, s76, s34
	global_load_lds_dwordx4 v[222:223], off
	v_lshl_add_u64 v[236:237], s[74:75], 0, v[168:169]
	s_mov_b32 m0, s73
	v_lshl_add_u64 v[246:247], s[26:27], 0, v[188:189]
	global_load_lds_dwordx4 v[236:237], off
	v_lshl_add_u64 v[236:237], s[74:75], 0, v[190:191]
	s_add_i32 m0, s73, 0x2000
	s_nop 0
	global_load_lds_dwordx4 v[236:237], off
	v_lshl_add_u64 v[236:237], s[26:27], 0, v[186:187]
	s_mov_b32 m0, s3
	s_nop 0
	global_load_lds_dwordx4 v[236:237], off
	s_mov_b32 m0, s60
	s_nop 0
	global_load_lds_dwordx4 v[246:247], off
	s_waitcnt vmcnt(8)
	s_waitcnt lgkmcnt(0)
	s_barrier
	s_setprio 1
	s_waitcnt lgkmcnt(0)
	v_mfma_f32_16x16x32_bf16 v[60:63], v[80:83], v[160:163], v[60:63]
	v_mfma_f32_16x16x32_bf16 v[56:59], v[88:91], v[160:163], v[56:59]
	v_mfma_f32_16x16x32_bf16 v[44:47], v[80:83], v[196:199], v[44:47]
	v_mfma_f32_16x16x32_bf16 v[40:43], v[88:91], v[196:199], v[40:43]
	v_mfma_f32_16x16x32_bf16 v[28:31], v[80:83], v[204:207], v[28:31]
	v_mfma_f32_16x16x32_bf16 v[24:27], v[88:91], v[204:207], v[24:27]
	v_mfma_f32_16x16x32_bf16 v[12:15], v[80:83], v[218:221], v[12:15]
	v_mfma_f32_16x16x32_bf16 v[8:11], v[88:91], v[218:221], v[8:11]
	v_mfma_f32_16x16x32_bf16 v[60:63], v[84:87], v[164:167], v[60:63]
	v_mfma_f32_16x16x32_bf16 v[56:59], v[92:95], v[164:167], v[56:59]
	v_mfma_f32_16x16x32_bf16 v[44:47], v[84:87], v[200:203], v[44:47]
	v_mfma_f32_16x16x32_bf16 v[40:43], v[92:95], v[200:203], v[40:43]
	v_mfma_f32_16x16x32_bf16 v[28:31], v[84:87], v[214:217], v[28:31]
	v_mfma_f32_16x16x32_bf16 v[24:27], v[92:95], v[214:217], v[24:27]
	v_mfma_f32_16x16x32_bf16 v[12:15], v[84:87], v[242:245], v[12:15]
	v_mfma_f32_16x16x32_bf16 v[8:11], v[92:95], v[242:245], v[8:11]
	v_mfma_f32_16x16x32_bf16 v[52:55], v[96:99], v[160:163], v[52:55]
	v_mfma_f32_16x16x32_bf16 v[48:51], v[104:107], v[160:163], v[48:51]
	v_mfma_f32_16x16x32_bf16 v[36:39], v[96:99], v[196:199], v[36:39]
	v_mfma_f32_16x16x32_bf16 v[32:35], v[104:107], v[196:199], v[32:35]
	v_mfma_f32_16x16x32_bf16 v[20:23], v[96:99], v[204:207], v[20:23]
	v_mfma_f32_16x16x32_bf16 v[16:19], v[104:107], v[204:207], v[16:19]
	v_mfma_f32_16x16x32_bf16 v[4:7], v[96:99], v[218:221], v[4:7]
	v_mfma_f32_16x16x32_bf16 v[0:3], v[104:107], v[218:221], v[0:3]
	v_mfma_f32_16x16x32_bf16 v[52:55], v[100:103], v[164:167], v[52:55]
	v_mfma_f32_16x16x32_bf16 v[48:51], v[108:111], v[164:167], v[48:51]
	v_mfma_f32_16x16x32_bf16 v[36:39], v[100:103], v[200:203], v[36:39]
	v_mfma_f32_16x16x32_bf16 v[32:35], v[108:111], v[200:203], v[32:35]
	v_mfma_f32_16x16x32_bf16 v[20:23], v[100:103], v[214:217], v[20:23]
	v_mfma_f32_16x16x32_bf16 v[16:19], v[108:111], v[214:217], v[16:19]
	v_mfma_f32_16x16x32_bf16 v[4:7], v[100:103], v[242:245], v[4:7]
	v_mfma_f32_16x16x32_bf16 v[0:3], v[108:111], v[242:245], v[0:3]
	s_setprio 0
	s_barrier
	s_add_i32 s73, 0, 0x18000
	s_add_i32 s74, 0, 0x1c000
	v_add_u32_e32 v92, s73, v211
	v_add_u32_e32 v108, s74, v211
	ds_read_b128 v[80:83], v92
	ds_read_b128 v[84:87], v92 offset:1024
	ds_read_b128 v[88:91], v92 offset:2048
	ds_read_b128 v[92:95], v92 offset:3072
	ds_read_b128 v[96:99], v108
	ds_read_b128 v[100:103], v108 offset:1024
	ds_read_b128 v[104:107], v108 offset:2048
	ds_read_b128 v[108:111], v108 offset:3072
	s_add_u32 s26, s26, 0x40000
	s_addc_u32 s27, s27, 0
	s_mov_b32 m0, s61
	v_lshl_add_u64 v[248:249], s[26:27], 0, v[186:187]
	ds_read_b128 v[160:163], v212 offset:32768
	ds_read_b128 v[164:167], v212 offset:33792
	ds_read_b128 v[196:199], v212 offset:34816
	ds_read_b128 v[200:203], v212 offset:35840
	ds_read_b128 v[204:207], v212 offset:36864
	ds_read_b128 v[214:217], v212 offset:37888
	ds_read_b128 v[218:221], v212 offset:38912
	ds_read_b128 v[242:245], v212 offset:39936
	global_load_lds_dwordx4 v[248:249], off
	v_lshl_add_u64 v[248:249], s[26:27], 0, v[188:189]
	s_mov_b32 m0, s62
	s_nop 0
	global_load_lds_dwordx4 v[248:249], off
	s_waitcnt vmcnt(8)
	s_waitcnt lgkmcnt(0)
	s_barrier
	s_setprio 1
	s_waitcnt lgkmcnt(0)
	v_mfma_f32_16x16x32_bf16 v[156:159], v[80:83], v[160:163], v[156:159]
	v_mfma_f32_16x16x32_bf16 v[152:155], v[88:91], v[160:163], v[152:155]
	v_mfma_f32_16x16x32_bf16 v[140:143], v[80:83], v[196:199], v[140:143]
	v_mfma_f32_16x16x32_bf16 v[136:139], v[88:91], v[196:199], v[136:139]
	v_mfma_f32_16x16x32_bf16 v[124:127], v[80:83], v[204:207], v[124:127]
	v_mfma_f32_16x16x32_bf16 v[120:123], v[88:91], v[204:207], v[120:123]
	v_mfma_f32_16x16x32_bf16 v[76:79], v[80:83], v[218:221], v[76:79]
	v_mfma_f32_16x16x32_bf16 v[72:75], v[88:91], v[218:221], v[72:75]
	v_mfma_f32_16x16x32_bf16 v[156:159], v[84:87], v[164:167], v[156:159]
	v_mfma_f32_16x16x32_bf16 v[152:155], v[92:95], v[164:167], v[152:155]
	v_mfma_f32_16x16x32_bf16 v[140:143], v[84:87], v[200:203], v[140:143]
	v_mfma_f32_16x16x32_bf16 v[136:139], v[92:95], v[200:203], v[136:139]
	v_mfma_f32_16x16x32_bf16 v[124:127], v[84:87], v[214:217], v[124:127]
	v_mfma_f32_16x16x32_bf16 v[120:123], v[92:95], v[214:217], v[120:123]
	v_mfma_f32_16x16x32_bf16 v[76:79], v[84:87], v[242:245], v[76:79]
	v_mfma_f32_16x16x32_bf16 v[72:75], v[92:95], v[242:245], v[72:75]
	v_mfma_f32_16x16x32_bf16 v[148:151], v[96:99], v[160:163], v[148:151]
	v_mfma_f32_16x16x32_bf16 v[144:147], v[104:107], v[160:163], v[144:147]
	v_mfma_f32_16x16x32_bf16 v[132:135], v[96:99], v[196:199], v[132:135]
	v_mfma_f32_16x16x32_bf16 v[128:131], v[104:107], v[196:199], v[128:131]
	v_mfma_f32_16x16x32_bf16 v[116:119], v[96:99], v[204:207], v[116:119]
	v_mfma_f32_16x16x32_bf16 v[112:115], v[104:107], v[204:207], v[112:115]
	v_mfma_f32_16x16x32_bf16 v[68:71], v[96:99], v[218:221], v[68:71]
	v_mfma_f32_16x16x32_bf16 v[64:67], v[104:107], v[218:221], v[64:67]
	v_mfma_f32_16x16x32_bf16 v[148:151], v[100:103], v[164:167], v[148:151]
	v_mfma_f32_16x16x32_bf16 v[144:147], v[108:111], v[164:167], v[144:147]
	v_mfma_f32_16x16x32_bf16 v[132:135], v[100:103], v[200:203], v[132:135]
	v_mfma_f32_16x16x32_bf16 v[128:131], v[108:111], v[200:203], v[128:131]
	v_mfma_f32_16x16x32_bf16 v[116:119], v[100:103], v[214:217], v[116:119]
	v_mfma_f32_16x16x32_bf16 v[112:115], v[108:111], v[214:217], v[112:115]
	v_mfma_f32_16x16x32_bf16 v[68:71], v[100:103], v[242:245], v[68:71]
	v_mfma_f32_16x16x32_bf16 v[64:67], v[108:111], v[242:245], v[64:67]
	s_setprio 0
	s_barrier
	s_add_i32 s26, s73, s34
	v_lshl_add_u64 v[208:209], v[208:209], 0, s[28:29]
	s_mov_b32 m0, s26
	ds_read_b128 v[160:163], v212 offset:49152
	ds_read_b128 v[164:167], v212 offset:50176
	ds_read_b128 v[196:199], v212 offset:51200
	ds_read_b128 v[200:203], v212 offset:52224
	ds_read_b128 v[204:207], v212 offset:53248
	ds_read_b128 v[214:217], v212 offset:54272
	ds_read_b128 v[218:221], v212 offset:55296
	ds_read_b128 v[242:245], v212 offset:56320
	global_load_lds_dwordx4 v[208:209], off
	s_add_i32 m0, s26, 0x2000
	s_add_u32 s22, s22, 0x40080
	v_lshl_add_u64 v[208:209], v[222:223], 0, s[28:29]
	s_addc_u32 s23, s23, 0
	s_add_i32 s26, s74, s34
	global_load_lds_dwordx4 v[208:209], off
	v_lshl_add_u64 v[208:209], s[22:23], 0, v[168:169]
	s_mov_b32 m0, s26
	s_nop 0
	global_load_lds_dwordx4 v[208:209], off
	v_lshl_add_u64 v[208:209], s[22:23], 0, v[190:191]
	s_add_i32 m0, s26, 0x2000
	s_nop 0
	global_load_lds_dwordx4 v[208:209], off
	v_lshl_add_u64 v[208:209], v[236:237], 0, s[28:29]
	s_mov_b32 m0, s66
	s_nop 0
	global_load_lds_dwordx4 v[208:209], off
	v_lshl_add_u64 v[208:209], v[246:247], 0, s[28:29]
	s_mov_b32 m0, s67
	s_nop 0
	global_load_lds_dwordx4 v[208:209], off
	s_waitcnt vmcnt(8)
	s_waitcnt lgkmcnt(0)
	s_barrier
	s_setprio 1
	s_waitcnt lgkmcnt(0)
	v_mfma_f32_16x16x32_bf16 v[60:63], v[80:83], v[160:163], v[60:63]
	v_mfma_f32_16x16x32_bf16 v[56:59], v[88:91], v[160:163], v[56:59]
	v_mfma_f32_16x16x32_bf16 v[44:47], v[80:83], v[196:199], v[44:47]
	v_mfma_f32_16x16x32_bf16 v[40:43], v[88:91], v[196:199], v[40:43]
	v_mfma_f32_16x16x32_bf16 v[28:31], v[80:83], v[204:207], v[28:31]
	v_mfma_f32_16x16x32_bf16 v[24:27], v[88:91], v[204:207], v[24:27]
	v_mfma_f32_16x16x32_bf16 v[12:15], v[80:83], v[218:221], v[12:15]
	v_mfma_f32_16x16x32_bf16 v[8:11], v[88:91], v[218:221], v[8:11]
	v_mfma_f32_16x16x32_bf16 v[60:63], v[84:87], v[164:167], v[60:63]
	v_mfma_f32_16x16x32_bf16 v[56:59], v[92:95], v[164:167], v[56:59]
	v_mfma_f32_16x16x32_bf16 v[44:47], v[84:87], v[200:203], v[44:47]
	v_mfma_f32_16x16x32_bf16 v[40:43], v[92:95], v[200:203], v[40:43]
	v_mfma_f32_16x16x32_bf16 v[28:31], v[84:87], v[214:217], v[28:31]
	v_mfma_f32_16x16x32_bf16 v[24:27], v[92:95], v[214:217], v[24:27]
	v_mfma_f32_16x16x32_bf16 v[12:15], v[84:87], v[242:245], v[12:15]
	v_mfma_f32_16x16x32_bf16 v[8:11], v[92:95], v[242:245], v[8:11]
	v_mfma_f32_16x16x32_bf16 v[52:55], v[96:99], v[160:163], v[52:55]
	v_mfma_f32_16x16x32_bf16 v[48:51], v[104:107], v[160:163], v[48:51]
	v_mfma_f32_16x16x32_bf16 v[36:39], v[96:99], v[196:199], v[36:39]
	v_mfma_f32_16x16x32_bf16 v[32:35], v[104:107], v[196:199], v[32:35]
	v_mfma_f32_16x16x32_bf16 v[20:23], v[96:99], v[204:207], v[20:23]
	v_mfma_f32_16x16x32_bf16 v[16:19], v[104:107], v[204:207], v[16:19]
	v_mfma_f32_16x16x32_bf16 v[4:7], v[96:99], v[218:221], v[4:7]
	v_mfma_f32_16x16x32_bf16 v[0:3], v[104:107], v[218:221], v[0:3]
	v_mfma_f32_16x16x32_bf16 v[52:55], v[100:103], v[164:167], v[52:55]
	v_mfma_f32_16x16x32_bf16 v[48:51], v[108:111], v[164:167], v[48:51]
	v_mfma_f32_16x16x32_bf16 v[36:39], v[100:103], v[200:203], v[36:39]
	v_mfma_f32_16x16x32_bf16 v[32:35], v[108:111], v[200:203], v[32:35]
	v_mfma_f32_16x16x32_bf16 v[20:23], v[100:103], v[214:217], v[20:23]
	v_mfma_f32_16x16x32_bf16 v[16:19], v[108:111], v[214:217], v[16:19]
	v_mfma_f32_16x16x32_bf16 v[4:7], v[100:103], v[242:245], v[4:7]
	v_mfma_f32_16x16x32_bf16 v[0:3], v[108:111], v[242:245], v[0:3]
	s_setprio 0
	s_barrier
	s_add_u32 s20, s20, 0x100
	s_addc_u32 s21, s21, 0
	s_add_u32 s55, s55, 0x100
	s_addc_u32 s71, s71, 0
	s_cmp_ge_i32 s72, s63
	s_mov_b32 s22, s72
	s_cbranch_scc0 .LBB0_853

.LBB0_916:
	s_add_i32 s76, s47, 2
	s_add_u32 s56, s54, 0xfffc0080
	s_addc_u32 s57, s55, -1
	s_add_i32 s77, 0, 0x10000
	s_cmp_eq_u32 s72, s47
	s_cselect_b32 s59, s1, s57
	s_cselect_b32 s58, s3, s56
	s_cselect_b32 s57, s49, s45
	s_cselect_b32 s56, s48, s43
	s_add_i32 s47, 0, 0x14000
	v_add_u32_e32 v154, s77, v148
	v_add_u32_e32 v166, s47, v148
	ds_read_b128 v[138:141], v154
	ds_read_b128 v[142:145], v154 offset:1024
	ds_read_b128 v[150:153], v154 offset:2048
	ds_read_b128 v[154:157], v154 offset:3072
	ds_read_b128 v[158:161], v166
	ds_read_b128 v[162:165], v166 offset:1024
	ds_read_b128 v[186:189], v166 offset:2048
	ds_read_b128 v[190:193], v166 offset:3072
	v_lshl_add_u64 v[166:167], s[54:55], 0, v[134:135]
	s_add_i32 m0, s53, 0xc000
	ds_read_b128 v[194:197], v149
	ds_read_b128 v[198:201], v149 offset:1024
	ds_read_b128 v[202:205], v149 offset:2048
	ds_read_b128 v[206:209], v149 offset:3072
	ds_read_b128 v[210:213], v149 offset:4096
	ds_read_b128 v[214:217], v149 offset:5120
	ds_read_b128 v[218:221], v149 offset:6144
	ds_read_b128 v[242:245], v149 offset:7168
	global_load_lds_dwordx4 v[166:167], off
	v_lshl_add_u64 v[166:167], s[54:55], 0, v[136:137]
	s_add_i32 m0, s53, 0xe000
	s_nop 0
	global_load_lds_dwordx4 v[166:167], off
	s_waitcnt vmcnt(8)
	s_waitcnt lgkmcnt(0)
	s_barrier
	s_setprio 1
	s_waitcnt lgkmcnt(0)
	v_mfma_f32_16x16x32_bf16 v[124:127], v[138:141], v[194:197], v[124:127]
	v_mfma_f32_16x16x32_bf16 v[120:123], v[150:153], v[194:197], v[120:123]
	v_mfma_f32_16x16x32_bf16 v[108:111], v[138:141], v[202:205], v[108:111]
	v_mfma_f32_16x16x32_bf16 v[104:107], v[150:153], v[202:205], v[104:107]
	v_mfma_f32_16x16x32_bf16 v[92:95], v[138:141], v[210:213], v[92:95]
	v_mfma_f32_16x16x32_bf16 v[88:91], v[150:153], v[210:213], v[88:91]
	v_mfma_f32_16x16x32_bf16 v[76:79], v[138:141], v[218:221], v[76:79]
	v_mfma_f32_16x16x32_bf16 v[72:75], v[150:153], v[218:221], v[72:75]
	v_mfma_f32_16x16x32_bf16 v[124:127], v[142:145], v[198:201], v[124:127]
	v_mfma_f32_16x16x32_bf16 v[120:123], v[154:157], v[198:201], v[120:123]
	v_mfma_f32_16x16x32_bf16 v[108:111], v[142:145], v[206:209], v[108:111]
	v_mfma_f32_16x16x32_bf16 v[104:107], v[154:157], v[206:209], v[104:107]
	v_mfma_f32_16x16x32_bf16 v[92:95], v[142:145], v[214:217], v[92:95]
	v_mfma_f32_16x16x32_bf16 v[88:91], v[154:157], v[214:217], v[88:91]
	v_mfma_f32_16x16x32_bf16 v[76:79], v[142:145], v[242:245], v[76:79]
	v_mfma_f32_16x16x32_bf16 v[72:75], v[154:157], v[242:245], v[72:75]
	v_mfma_f32_16x16x32_bf16 v[116:119], v[158:161], v[194:197], v[116:119]
	v_mfma_f32_16x16x32_bf16 v[112:115], v[186:189], v[194:197], v[112:115]
	v_mfma_f32_16x16x32_bf16 v[100:103], v[158:161], v[202:205], v[100:103]
	v_mfma_f32_16x16x32_bf16 v[96:99], v[186:189], v[202:205], v[96:99]
	v_mfma_f32_16x16x32_bf16 v[84:87], v[158:161], v[210:213], v[84:87]
	v_mfma_f32_16x16x32_bf16 v[80:83], v[186:189], v[210:213], v[80:83]
	v_mfma_f32_16x16x32_bf16 v[68:71], v[158:161], v[218:221], v[68:71]
	v_mfma_f32_16x16x32_bf16 v[64:67], v[186:189], v[218:221], v[64:67]
	v_mfma_f32_16x16x32_bf16 v[116:119], v[162:165], v[198:201], v[116:119]
	v_mfma_f32_16x16x32_bf16 v[112:115], v[190:193], v[198:201], v[112:115]
	v_mfma_f32_16x16x32_bf16 v[100:103], v[162:165], v[206:209], v[100:103]
	v_mfma_f32_16x16x32_bf16 v[96:99], v[190:193], v[206:209], v[96:99]
	v_mfma_f32_16x16x32_bf16 v[84:87], v[162:165], v[214:217], v[84:87]
	v_mfma_f32_16x16x32_bf16 v[80:83], v[190:193], v[214:217], v[80:83]
	v_mfma_f32_16x16x32_bf16 v[68:71], v[162:165], v[242:245], v[68:71]
	v_mfma_f32_16x16x32_bf16 v[64:67], v[190:193], v[242:245], v[64:67]
	s_setprio 0
	s_barrier
	s_add_i32 s77, s77, s63
	v_lshl_add_u64 v[166:167], s[56:57], 0, v[168:169]
	s_mov_b32 m0, s77
	ds_read_b128 v[194:197], v149 offset:16384
	ds_read_b128 v[198:201], v149 offset:17408
	ds_read_b128 v[202:205], v149 offset:18432
	ds_read_b128 v[206:209], v149 offset:19456
	ds_read_b128 v[210:213], v149 offset:20480
	ds_read_b128 v[214:217], v149 offset:21504
	ds_read_b128 v[218:221], v149 offset:22528
	ds_read_b128 v[242:245], v149 offset:23552
	global_load_lds_dwordx4 v[166:167], off
	s_add_i32 m0, s77, 0x2000
	s_add_u32 s78, s56, 0x40000
	v_lshl_add_u64 v[222:223], s[56:57], 0, v[132:133]
	s_addc_u32 s79, s57, 0
	s_add_i32 s47, s47, s63
	global_load_lds_dwordx4 v[222:223], off
	v_lshl_add_u64 v[236:237], s[78:79], 0, v[168:169]
	s_mov_b32 m0, s47
	v_lshl_add_u64 v[246:247], s[58:59], 0, v[130:131]
	global_load_lds_dwordx4 v[236:237], off
	v_lshl_add_u64 v[236:237], s[78:79], 0, v[132:133]
	s_add_i32 m0, s47, 0x2000
	s_nop 0
	global_load_lds_dwordx4 v[236:237], off
	v_lshl_add_u64 v[236:237], s[58:59], 0, v[128:129]
	s_mov_b32 m0, s53
	s_nop 0
	global_load_lds_dwordx4 v[236:237], off
	s_mov_b32 m0, s64
	s_nop 0
	global_load_lds_dwordx4 v[246:247], off
	s_waitcnt vmcnt(8)
	s_waitcnt lgkmcnt(0)
	s_barrier
	s_setprio 1
	s_waitcnt lgkmcnt(0)
	v_mfma_f32_16x16x32_bf16 v[60:63], v[138:141], v[194:197], v[60:63]
	v_mfma_f32_16x16x32_bf16 v[56:59], v[150:153], v[194:197], v[56:59]
	v_mfma_f32_16x16x32_bf16 v[44:47], v[138:141], v[202:205], v[44:47]
	v_mfma_f32_16x16x32_bf16 v[40:43], v[150:153], v[202:205], v[40:43]
	v_mfma_f32_16x16x32_bf16 v[28:31], v[138:141], v[210:213], v[28:31]
	v_mfma_f32_16x16x32_bf16 v[24:27], v[150:153], v[210:213], v[24:27]
	v_mfma_f32_16x16x32_bf16 v[12:15], v[138:141], v[218:221], v[12:15]
	v_mfma_f32_16x16x32_bf16 v[8:11], v[150:153], v[218:221], v[8:11]
	v_mfma_f32_16x16x32_bf16 v[60:63], v[142:145], v[198:201], v[60:63]
	v_mfma_f32_16x16x32_bf16 v[56:59], v[154:157], v[198:201], v[56:59]
	v_mfma_f32_16x16x32_bf16 v[44:47], v[142:145], v[206:209], v[44:47]
	v_mfma_f32_16x16x32_bf16 v[40:43], v[154:157], v[206:209], v[40:43]
	v_mfma_f32_16x16x32_bf16 v[28:31], v[142:145], v[214:217], v[28:31]
	v_mfma_f32_16x16x32_bf16 v[24:27], v[154:157], v[214:217], v[24:27]
	v_mfma_f32_16x16x32_bf16 v[12:15], v[142:145], v[242:245], v[12:15]
	v_mfma_f32_16x16x32_bf16 v[8:11], v[154:157], v[242:245], v[8:11]
	v_mfma_f32_16x16x32_bf16 v[52:55], v[158:161], v[194:197], v[52:55]
	v_mfma_f32_16x16x32_bf16 v[48:51], v[186:189], v[194:197], v[48:51]
	v_mfma_f32_16x16x32_bf16 v[36:39], v[158:161], v[202:205], v[36:39]
	v_mfma_f32_16x16x32_bf16 v[32:35], v[186:189], v[202:205], v[32:35]
	v_mfma_f32_16x16x32_bf16 v[20:23], v[158:161], v[210:213], v[20:23]
	v_mfma_f32_16x16x32_bf16 v[16:19], v[186:189], v[210:213], v[16:19]
	v_mfma_f32_16x16x32_bf16 v[4:7], v[158:161], v[218:221], v[4:7]
	v_mfma_f32_16x16x32_bf16 v[0:3], v[186:189], v[218:221], v[0:3]
	v_mfma_f32_16x16x32_bf16 v[52:55], v[162:165], v[198:201], v[52:55]
	v_mfma_f32_16x16x32_bf16 v[48:51], v[190:193], v[198:201], v[48:51]
	v_mfma_f32_16x16x32_bf16 v[36:39], v[162:165], v[206:209], v[36:39]
	v_mfma_f32_16x16x32_bf16 v[32:35], v[190:193], v[206:209], v[32:35]
	v_mfma_f32_16x16x32_bf16 v[20:23], v[162:165], v[214:217], v[20:23]
	v_mfma_f32_16x16x32_bf16 v[16:19], v[190:193], v[214:217], v[16:19]
	v_mfma_f32_16x16x32_bf16 v[4:7], v[162:165], v[242:245], v[4:7]
	v_mfma_f32_16x16x32_bf16 v[0:3], v[190:193], v[242:245], v[0:3]
	s_setprio 0
	s_barrier
	s_add_i32 s47, 0, 0x18000
	s_add_i32 s77, 0, 0x1c000
	v_add_u32_e32 v154, s47, v148
	v_add_u32_e32 v179, s77, v148
	ds_read_b128 v[138:141], v154
	ds_read_b128 v[142:145], v154 offset:1024
	ds_read_b128 v[150:153], v154 offset:2048
	ds_read_b128 v[154:157], v154 offset:3072
	ds_read_b128 v[158:161], v179
	ds_read_b128 v[162:165], v179 offset:1024
	ds_read_b128 v[186:189], v179 offset:2048
	ds_read_b128 v[190:193], v179 offset:3072
	s_add_u32 s58, s58, 0x40000
	s_addc_u32 s59, s59, 0
	s_mov_b32 m0, s65
	v_lshl_add_u64 v[248:249], s[58:59], 0, v[128:129]
	ds_read_b128 v[194:197], v149 offset:32768
	ds_read_b128 v[198:201], v149 offset:33792
	ds_read_b128 v[202:205], v149 offset:34816
	ds_read_b128 v[206:209], v149 offset:35840
	ds_read_b128 v[210:213], v149 offset:36864
	ds_read_b128 v[214:217], v149 offset:37888
	ds_read_b128 v[218:221], v149 offset:38912
	ds_read_b128 v[242:245], v149 offset:39936
	global_load_lds_dwordx4 v[248:249], off
	v_lshl_add_u64 v[248:249], s[58:59], 0, v[130:131]
	s_mov_b32 m0, s66
	s_nop 0
	global_load_lds_dwordx4 v[248:249], off
	s_waitcnt vmcnt(8)
	s_waitcnt lgkmcnt(0)
	s_barrier
	s_setprio 1
	s_waitcnt lgkmcnt(0)
	v_mfma_f32_16x16x32_bf16 v[124:127], v[138:141], v[194:197], v[124:127]
	v_mfma_f32_16x16x32_bf16 v[120:123], v[150:153], v[194:197], v[120:123]
	v_mfma_f32_16x16x32_bf16 v[108:111], v[138:141], v[202:205], v[108:111]
	v_mfma_f32_16x16x32_bf16 v[104:107], v[150:153], v[202:205], v[104:107]
	v_mfma_f32_16x16x32_bf16 v[92:95], v[138:141], v[210:213], v[92:95]
	v_mfma_f32_16x16x32_bf16 v[88:91], v[150:153], v[210:213], v[88:91]
	v_mfma_f32_16x16x32_bf16 v[76:79], v[138:141], v[218:221], v[76:79]
	v_mfma_f32_16x16x32_bf16 v[72:75], v[150:153], v[218:221], v[72:75]
	v_mfma_f32_16x16x32_bf16 v[124:127], v[142:145], v[198:201], v[124:127]
	v_mfma_f32_16x16x32_bf16 v[120:123], v[154:157], v[198:201], v[120:123]
	v_mfma_f32_16x16x32_bf16 v[108:111], v[142:145], v[206:209], v[108:111]
	v_mfma_f32_16x16x32_bf16 v[104:107], v[154:157], v[206:209], v[104:107]
	v_mfma_f32_16x16x32_bf16 v[92:95], v[142:145], v[214:217], v[92:95]
	v_mfma_f32_16x16x32_bf16 v[88:91], v[154:157], v[214:217], v[88:91]
	v_mfma_f32_16x16x32_bf16 v[76:79], v[142:145], v[242:245], v[76:79]
	v_mfma_f32_16x16x32_bf16 v[72:75], v[154:157], v[242:245], v[72:75]
	v_mfma_f32_16x16x32_bf16 v[116:119], v[158:161], v[194:197], v[116:119]
	v_mfma_f32_16x16x32_bf16 v[112:115], v[186:189], v[194:197], v[112:115]
	v_mfma_f32_16x16x32_bf16 v[100:103], v[158:161], v[202:205], v[100:103]
	v_mfma_f32_16x16x32_bf16 v[96:99], v[186:189], v[202:205], v[96:99]
	v_mfma_f32_16x16x32_bf16 v[84:87], v[158:161], v[210:213], v[84:87]
	v_mfma_f32_16x16x32_bf16 v[80:83], v[186:189], v[210:213], v[80:83]
	v_mfma_f32_16x16x32_bf16 v[68:71], v[158:161], v[218:221], v[68:71]
	v_mfma_f32_16x16x32_bf16 v[64:67], v[186:189], v[218:221], v[64:67]
	v_mfma_f32_16x16x32_bf16 v[116:119], v[162:165], v[198:201], v[116:119]
	v_mfma_f32_16x16x32_bf16 v[112:115], v[190:193], v[198:201], v[112:115]
	v_mfma_f32_16x16x32_bf16 v[100:103], v[162:165], v[206:209], v[100:103]
	v_mfma_f32_16x16x32_bf16 v[96:99], v[190:193], v[206:209], v[96:99]
	v_mfma_f32_16x16x32_bf16 v[84:87], v[162:165], v[214:217], v[84:87]
	v_mfma_f32_16x16x32_bf16 v[80:83], v[190:193], v[214:217], v[80:83]
	v_mfma_f32_16x16x32_bf16 v[68:71], v[162:165], v[242:245], v[68:71]
	v_mfma_f32_16x16x32_bf16 v[64:67], v[190:193], v[242:245], v[64:67]
	s_setprio 0
	s_barrier
	s_add_i32 s47, s47, s63
	v_lshl_add_u64 v[166:167], v[166:167], 0, s[28:29]
	s_mov_b32 m0, s47
	ds_read_b128 v[194:197], v149 offset:49152
	ds_read_b128 v[198:201], v149 offset:50176
	ds_read_b128 v[202:205], v149 offset:51200
	ds_read_b128 v[206:209], v149 offset:52224
	ds_read_b128 v[210:213], v149 offset:53248
	ds_read_b128 v[214:217], v149 offset:54272
	ds_read_b128 v[218:221], v149 offset:55296
	ds_read_b128 v[242:245], v149 offset:56320
	global_load_lds_dwordx4 v[166:167], off
	s_add_i32 m0, s47, 0x2000
	s_add_u32 s56, s56, 0x40080
	v_lshl_add_u64 v[166:167], v[222:223], 0, s[28:29]
	s_addc_u32 s57, s57, 0
	s_add_i32 s47, s77, s63
	global_load_lds_dwordx4 v[166:167], off
	v_lshl_add_u64 v[166:167], s[56:57], 0, v[168:169]
	s_mov_b32 m0, s47
	s_nop 0
	global_load_lds_dwordx4 v[166:167], off
	v_lshl_add_u64 v[166:167], s[56:57], 0, v[132:133]
	s_add_i32 m0, s47, 0x2000
	s_nop 0
	global_load_lds_dwordx4 v[166:167], off
	v_lshl_add_u64 v[166:167], v[236:237], 0, s[28:29]
	s_mov_b32 m0, s70
	s_nop 0
	global_load_lds_dwordx4 v[166:167], off
	v_lshl_add_u64 v[166:167], v[246:247], 0, s[28:29]
	s_mov_b32 m0, s71
	s_nop 0
	global_load_lds_dwordx4 v[166:167], off
	s_waitcnt vmcnt(8)
	s_waitcnt lgkmcnt(0)
	s_barrier
	s_setprio 1
	s_waitcnt lgkmcnt(0)
	v_mfma_f32_16x16x32_bf16 v[60:63], v[138:141], v[194:197], v[60:63]
	v_mfma_f32_16x16x32_bf16 v[56:59], v[150:153], v[194:197], v[56:59]
	v_mfma_f32_16x16x32_bf16 v[44:47], v[138:141], v[202:205], v[44:47]
	v_mfma_f32_16x16x32_bf16 v[40:43], v[150:153], v[202:205], v[40:43]
	v_mfma_f32_16x16x32_bf16 v[28:31], v[138:141], v[210:213], v[28:31]
	v_mfma_f32_16x16x32_bf16 v[24:27], v[150:153], v[210:213], v[24:27]
	v_mfma_f32_16x16x32_bf16 v[12:15], v[138:141], v[218:221], v[12:15]
	v_mfma_f32_16x16x32_bf16 v[8:11], v[150:153], v[218:221], v[8:11]
	v_mfma_f32_16x16x32_bf16 v[60:63], v[142:145], v[198:201], v[60:63]
	v_mfma_f32_16x16x32_bf16 v[56:59], v[154:157], v[198:201], v[56:59]
	v_mfma_f32_16x16x32_bf16 v[44:47], v[142:145], v[206:209], v[44:47]
	v_mfma_f32_16x16x32_bf16 v[40:43], v[154:157], v[206:209], v[40:43]
	v_mfma_f32_16x16x32_bf16 v[28:31], v[142:145], v[214:217], v[28:31]
	v_mfma_f32_16x16x32_bf16 v[24:27], v[154:157], v[214:217], v[24:27]
	v_mfma_f32_16x16x32_bf16 v[12:15], v[142:145], v[242:245], v[12:15]
	v_mfma_f32_16x16x32_bf16 v[8:11], v[154:157], v[242:245], v[8:11]
	v_mfma_f32_16x16x32_bf16 v[52:55], v[158:161], v[194:197], v[52:55]
	v_mfma_f32_16x16x32_bf16 v[48:51], v[186:189], v[194:197], v[48:51]
	v_mfma_f32_16x16x32_bf16 v[36:39], v[158:161], v[202:205], v[36:39]
	v_mfma_f32_16x16x32_bf16 v[32:35], v[186:189], v[202:205], v[32:35]
	v_mfma_f32_16x16x32_bf16 v[20:23], v[158:161], v[210:213], v[20:23]
	v_mfma_f32_16x16x32_bf16 v[16:19], v[186:189], v[210:213], v[16:19]
	v_mfma_f32_16x16x32_bf16 v[4:7], v[158:161], v[218:221], v[4:7]
	v_mfma_f32_16x16x32_bf16 v[0:3], v[186:189], v[218:221], v[0:3]
	v_mfma_f32_16x16x32_bf16 v[52:55], v[162:165], v[198:201], v[52:55]
	v_mfma_f32_16x16x32_bf16 v[48:51], v[190:193], v[198:201], v[48:51]
	v_mfma_f32_16x16x32_bf16 v[36:39], v[162:165], v[206:209], v[36:39]
	v_mfma_f32_16x16x32_bf16 v[32:35], v[190:193], v[206:209], v[32:35]
	v_mfma_f32_16x16x32_bf16 v[20:23], v[162:165], v[214:217], v[20:23]
	v_mfma_f32_16x16x32_bf16 v[16:19], v[190:193], v[214:217], v[16:19]
	v_mfma_f32_16x16x32_bf16 v[4:7], v[162:165], v[242:245], v[4:7]
	v_mfma_f32_16x16x32_bf16 v[0:3], v[190:193], v[242:245], v[0:3]
	s_setprio 0
	s_barrier
	s_add_u32 s54, s54, 0x100
	s_addc_u32 s55, s55, 0
	s_add_u32 s43, s43, 0x100
	s_addc_u32 s45, s45, 0
	s_cmp_ge_i32 s76, s67
	s_mov_b32 s47, s76
	s_cbranch_scc0 .LBB0_916
	s_mov_b32 s76, 0x3fffff80
	v_readlane_b32 s77, v254, 56

.LBB0_980:
	s_add_i32 s43, s41, 2
	s_add_u32 s49, s50, 0xfffc0080
	s_addc_u32 s52, s51, -1
	s_add_i32 s76, 0, 0x10000
	s_cmp_eq_u32 s69, s41
	s_cselect_b32 s55, s45, s52
	s_cselect_b32 s54, s44, s49
	s_cselect_b32 s53, s47, s3
	s_cselect_b32 s52, s46, s1
	s_add_i32 s41, 0, 0x14000
	v_add_u32_e32 v154, s76, v148
	v_add_u32_e32 v166, s41, v148
	ds_read_b128 v[138:141], v154
	ds_read_b128 v[142:145], v154 offset:1024
	ds_read_b128 v[150:153], v154 offset:2048
	ds_read_b128 v[154:157], v154 offset:3072
	ds_read_b128 v[158:161], v166
	ds_read_b128 v[162:165], v166 offset:1024
	ds_read_b128 v[186:189], v166 offset:2048
	ds_read_b128 v[190:193], v166 offset:3072
	v_lshl_add_u64 v[166:167], s[50:51], 0, v[134:135]
	s_add_i32 m0, s59, 0xc000
	ds_read_b128 v[194:197], v149
	ds_read_b128 v[198:201], v149 offset:1024
	ds_read_b128 v[202:205], v149 offset:2048
	ds_read_b128 v[206:209], v149 offset:3072
	ds_read_b128 v[210:213], v149 offset:4096
	ds_read_b128 v[214:217], v149 offset:5120
	ds_read_b128 v[218:221], v149 offset:6144
	ds_read_b128 v[242:245], v149 offset:7168
	global_load_lds_dwordx4 v[166:167], off
	v_lshl_add_u64 v[166:167], s[50:51], 0, v[136:137]
	s_add_i32 m0, s59, 0xe000
	s_nop 0
	global_load_lds_dwordx4 v[166:167], off
	s_waitcnt vmcnt(8)
	s_waitcnt lgkmcnt(0)
	s_barrier
	s_setprio 1
	s_waitcnt lgkmcnt(0)
	v_mfma_f32_16x16x32_bf16 v[124:127], v[138:141], v[194:197], v[124:127]
	v_mfma_f32_16x16x32_bf16 v[120:123], v[150:153], v[194:197], v[120:123]
	v_mfma_f32_16x16x32_bf16 v[108:111], v[138:141], v[202:205], v[108:111]
	v_mfma_f32_16x16x32_bf16 v[104:107], v[150:153], v[202:205], v[104:107]
	v_mfma_f32_16x16x32_bf16 v[92:95], v[138:141], v[210:213], v[92:95]
	v_mfma_f32_16x16x32_bf16 v[88:91], v[150:153], v[210:213], v[88:91]
	v_mfma_f32_16x16x32_bf16 v[76:79], v[138:141], v[218:221], v[76:79]
	v_mfma_f32_16x16x32_bf16 v[72:75], v[150:153], v[218:221], v[72:75]
	v_mfma_f32_16x16x32_bf16 v[124:127], v[142:145], v[198:201], v[124:127]
	v_mfma_f32_16x16x32_bf16 v[120:123], v[154:157], v[198:201], v[120:123]
	v_mfma_f32_16x16x32_bf16 v[108:111], v[142:145], v[206:209], v[108:111]
	v_mfma_f32_16x16x32_bf16 v[104:107], v[154:157], v[206:209], v[104:107]
	v_mfma_f32_16x16x32_bf16 v[92:95], v[142:145], v[214:217], v[92:95]
	v_mfma_f32_16x16x32_bf16 v[88:91], v[154:157], v[214:217], v[88:91]
	v_mfma_f32_16x16x32_bf16 v[76:79], v[142:145], v[242:245], v[76:79]
	v_mfma_f32_16x16x32_bf16 v[72:75], v[154:157], v[242:245], v[72:75]
	v_mfma_f32_16x16x32_bf16 v[116:119], v[158:161], v[194:197], v[116:119]
	v_mfma_f32_16x16x32_bf16 v[112:115], v[186:189], v[194:197], v[112:115]
	v_mfma_f32_16x16x32_bf16 v[100:103], v[158:161], v[202:205], v[100:103]
	v_mfma_f32_16x16x32_bf16 v[96:99], v[186:189], v[202:205], v[96:99]
	v_mfma_f32_16x16x32_bf16 v[84:87], v[158:161], v[210:213], v[84:87]
	v_mfma_f32_16x16x32_bf16 v[80:83], v[186:189], v[210:213], v[80:83]
	v_mfma_f32_16x16x32_bf16 v[68:71], v[158:161], v[218:221], v[68:71]
	v_mfma_f32_16x16x32_bf16 v[64:67], v[186:189], v[218:221], v[64:67]
	v_mfma_f32_16x16x32_bf16 v[116:119], v[162:165], v[198:201], v[116:119]
	v_mfma_f32_16x16x32_bf16 v[112:115], v[190:193], v[198:201], v[112:115]
	v_mfma_f32_16x16x32_bf16 v[100:103], v[162:165], v[206:209], v[100:103]
	v_mfma_f32_16x16x32_bf16 v[96:99], v[190:193], v[206:209], v[96:99]
	v_mfma_f32_16x16x32_bf16 v[84:87], v[162:165], v[214:217], v[84:87]
	v_mfma_f32_16x16x32_bf16 v[80:83], v[190:193], v[214:217], v[80:83]
	v_mfma_f32_16x16x32_bf16 v[68:71], v[162:165], v[242:245], v[68:71]
	v_mfma_f32_16x16x32_bf16 v[64:67], v[190:193], v[242:245], v[64:67]
	s_setprio 0
	s_barrier
	s_add_i32 s49, s76, s58
	v_lshl_add_u64 v[166:167], s[52:53], 0, v[168:169]
	s_mov_b32 m0, s49
	ds_read_b128 v[194:197], v149 offset:16384
	ds_read_b128 v[198:201], v149 offset:17408
	ds_read_b128 v[202:205], v149 offset:18432
	ds_read_b128 v[206:209], v149 offset:19456
	ds_read_b128 v[210:213], v149 offset:20480
	ds_read_b128 v[214:217], v149 offset:21504
	ds_read_b128 v[218:221], v149 offset:22528
	ds_read_b128 v[242:245], v149 offset:23552
	global_load_lds_dwordx4 v[166:167], off
	s_add_i32 m0, s49, 0x2000
	s_add_u32 s76, s52, 0x40000
	v_lshl_add_u64 v[222:223], s[52:53], 0, v[132:133]
	s_addc_u32 s77, s53, 0
	s_add_i32 s41, s41, s58
	global_load_lds_dwordx4 v[222:223], off
	v_lshl_add_u64 v[236:237], s[76:77], 0, v[168:169]
	s_mov_b32 m0, s41
	v_lshl_add_u64 v[246:247], s[54:55], 0, v[130:131]
	global_load_lds_dwordx4 v[236:237], off
	v_lshl_add_u64 v[236:237], s[76:77], 0, v[132:133]
	s_add_i32 m0, s41, 0x2000
	s_nop 0
	global_load_lds_dwordx4 v[236:237], off
	v_lshl_add_u64 v[236:237], s[54:55], 0, v[128:129]
	s_mov_b32 m0, s59
	s_nop 0
	global_load_lds_dwordx4 v[236:237], off
	s_mov_b32 m0, s61
	s_nop 0
	global_load_lds_dwordx4 v[246:247], off
	s_waitcnt vmcnt(8)
	s_waitcnt lgkmcnt(0)
	s_barrier
	s_setprio 1
	s_waitcnt lgkmcnt(0)
	v_mfma_f32_16x16x32_bf16 v[60:63], v[138:141], v[194:197], v[60:63]
	v_mfma_f32_16x16x32_bf16 v[56:59], v[150:153], v[194:197], v[56:59]
	v_mfma_f32_16x16x32_bf16 v[44:47], v[138:141], v[202:205], v[44:47]
	v_mfma_f32_16x16x32_bf16 v[40:43], v[150:153], v[202:205], v[40:43]
	v_mfma_f32_16x16x32_bf16 v[28:31], v[138:141], v[210:213], v[28:31]
	v_mfma_f32_16x16x32_bf16 v[24:27], v[150:153], v[210:213], v[24:27]
	v_mfma_f32_16x16x32_bf16 v[12:15], v[138:141], v[218:221], v[12:15]
	v_mfma_f32_16x16x32_bf16 v[8:11], v[150:153], v[218:221], v[8:11]
	v_mfma_f32_16x16x32_bf16 v[60:63], v[142:145], v[198:201], v[60:63]
	v_mfma_f32_16x16x32_bf16 v[56:59], v[154:157], v[198:201], v[56:59]
	v_mfma_f32_16x16x32_bf16 v[44:47], v[142:145], v[206:209], v[44:47]
	v_mfma_f32_16x16x32_bf16 v[40:43], v[154:157], v[206:209], v[40:43]
	v_mfma_f32_16x16x32_bf16 v[28:31], v[142:145], v[214:217], v[28:31]
	v_mfma_f32_16x16x32_bf16 v[24:27], v[154:157], v[214:217], v[24:27]
	v_mfma_f32_16x16x32_bf16 v[12:15], v[142:145], v[242:245], v[12:15]
	v_mfma_f32_16x16x32_bf16 v[8:11], v[154:157], v[242:245], v[8:11]
	v_mfma_f32_16x16x32_bf16 v[52:55], v[158:161], v[194:197], v[52:55]
	v_mfma_f32_16x16x32_bf16 v[48:51], v[186:189], v[194:197], v[48:51]
	v_mfma_f32_16x16x32_bf16 v[36:39], v[158:161], v[202:205], v[36:39]
	v_mfma_f32_16x16x32_bf16 v[32:35], v[186:189], v[202:205], v[32:35]
	v_mfma_f32_16x16x32_bf16 v[20:23], v[158:161], v[210:213], v[20:23]
	v_mfma_f32_16x16x32_bf16 v[16:19], v[186:189], v[210:213], v[16:19]
	v_mfma_f32_16x16x32_bf16 v[4:7], v[158:161], v[218:221], v[4:7]
	v_mfma_f32_16x16x32_bf16 v[0:3], v[186:189], v[218:221], v[0:3]
	v_mfma_f32_16x16x32_bf16 v[52:55], v[162:165], v[198:201], v[52:55]
	v_mfma_f32_16x16x32_bf16 v[48:51], v[190:193], v[198:201], v[48:51]
	v_mfma_f32_16x16x32_bf16 v[36:39], v[162:165], v[206:209], v[36:39]
	v_mfma_f32_16x16x32_bf16 v[32:35], v[190:193], v[206:209], v[32:35]
	v_mfma_f32_16x16x32_bf16 v[20:23], v[162:165], v[214:217], v[20:23]
	v_mfma_f32_16x16x32_bf16 v[16:19], v[190:193], v[214:217], v[16:19]
	v_mfma_f32_16x16x32_bf16 v[4:7], v[162:165], v[242:245], v[4:7]
	v_mfma_f32_16x16x32_bf16 v[0:3], v[190:193], v[242:245], v[0:3]
	s_setprio 0
	s_barrier
	s_add_i32 s41, 0, 0x18000
	s_add_i32 s49, 0, 0x1c000
	v_add_u32_e32 v154, s41, v148
	v_add_u32_e32 v179, s49, v148
	ds_read_b128 v[138:141], v154
	ds_read_b128 v[142:145], v154 offset:1024
	ds_read_b128 v[150:153], v154 offset:2048
	ds_read_b128 v[154:157], v154 offset:3072
	ds_read_b128 v[158:161], v179
	ds_read_b128 v[162:165], v179 offset:1024
	ds_read_b128 v[186:189], v179 offset:2048
	ds_read_b128 v[190:193], v179 offset:3072
	s_add_u32 s54, s54, 0x40000
	s_addc_u32 s55, s55, 0
	s_mov_b32 m0, s62
	v_lshl_add_u64 v[248:249], s[54:55], 0, v[128:129]
	ds_read_b128 v[194:197], v149 offset:32768
	ds_read_b128 v[198:201], v149 offset:33792
	ds_read_b128 v[202:205], v149 offset:34816
	ds_read_b128 v[206:209], v149 offset:35840
	ds_read_b128 v[210:213], v149 offset:36864
	ds_read_b128 v[214:217], v149 offset:37888
	ds_read_b128 v[218:221], v149 offset:38912
	ds_read_b128 v[242:245], v149 offset:39936
	global_load_lds_dwordx4 v[248:249], off
	v_lshl_add_u64 v[248:249], s[54:55], 0, v[130:131]
	s_mov_b32 m0, s63
	s_nop 0
	global_load_lds_dwordx4 v[248:249], off
	s_waitcnt vmcnt(8)
	s_waitcnt lgkmcnt(0)
	s_barrier
	s_setprio 1
	s_waitcnt lgkmcnt(0)
	v_mfma_f32_16x16x32_bf16 v[124:127], v[138:141], v[194:197], v[124:127]
	v_mfma_f32_16x16x32_bf16 v[120:123], v[150:153], v[194:197], v[120:123]
	v_mfma_f32_16x16x32_bf16 v[108:111], v[138:141], v[202:205], v[108:111]
	v_mfma_f32_16x16x32_bf16 v[104:107], v[150:153], v[202:205], v[104:107]
	v_mfma_f32_16x16x32_bf16 v[92:95], v[138:141], v[210:213], v[92:95]
	v_mfma_f32_16x16x32_bf16 v[88:91], v[150:153], v[210:213], v[88:91]
	v_mfma_f32_16x16x32_bf16 v[76:79], v[138:141], v[218:221], v[76:79]
	v_mfma_f32_16x16x32_bf16 v[72:75], v[150:153], v[218:221], v[72:75]
	v_mfma_f32_16x16x32_bf16 v[124:127], v[142:145], v[198:201], v[124:127]
	v_mfma_f32_16x16x32_bf16 v[120:123], v[154:157], v[198:201], v[120:123]
	v_mfma_f32_16x16x32_bf16 v[108:111], v[142:145], v[206:209], v[108:111]
	v_mfma_f32_16x16x32_bf16 v[104:107], v[154:157], v[206:209], v[104:107]
	v_mfma_f32_16x16x32_bf16 v[92:95], v[142:145], v[214:217], v[92:95]
	v_mfma_f32_16x16x32_bf16 v[88:91], v[154:157], v[214:217], v[88:91]
	v_mfma_f32_16x16x32_bf16 v[76:79], v[142:145], v[242:245], v[76:79]
	v_mfma_f32_16x16x32_bf16 v[72:75], v[154:157], v[242:245], v[72:75]
	v_mfma_f32_16x16x32_bf16 v[116:119], v[158:161], v[194:197], v[116:119]
	v_mfma_f32_16x16x32_bf16 v[112:115], v[186:189], v[194:197], v[112:115]
	v_mfma_f32_16x16x32_bf16 v[100:103], v[158:161], v[202:205], v[100:103]
	v_mfma_f32_16x16x32_bf16 v[96:99], v[186:189], v[202:205], v[96:99]
	v_mfma_f32_16x16x32_bf16 v[84:87], v[158:161], v[210:213], v[84:87]
	v_mfma_f32_16x16x32_bf16 v[80:83], v[186:189], v[210:213], v[80:83]
	v_mfma_f32_16x16x32_bf16 v[68:71], v[158:161], v[218:221], v[68:71]
	v_mfma_f32_16x16x32_bf16 v[64:67], v[186:189], v[218:221], v[64:67]
	v_mfma_f32_16x16x32_bf16 v[116:119], v[162:165], v[198:201], v[116:119]
	v_mfma_f32_16x16x32_bf16 v[112:115], v[190:193], v[198:201], v[112:115]
	v_mfma_f32_16x16x32_bf16 v[100:103], v[162:165], v[206:209], v[100:103]
	v_mfma_f32_16x16x32_bf16 v[96:99], v[190:193], v[206:209], v[96:99]
	v_mfma_f32_16x16x32_bf16 v[84:87], v[162:165], v[214:217], v[84:87]
	v_mfma_f32_16x16x32_bf16 v[80:83], v[190:193], v[214:217], v[80:83]
	v_mfma_f32_16x16x32_bf16 v[68:71], v[162:165], v[242:245], v[68:71]
	v_mfma_f32_16x16x32_bf16 v[64:67], v[190:193], v[242:245], v[64:67]
	s_setprio 0
	s_barrier
	s_add_i32 s41, s41, s58
	v_lshl_add_u64 v[166:167], v[166:167], 0, s[28:29]
	s_mov_b32 m0, s41
	ds_read_b128 v[194:197], v149 offset:49152
	ds_read_b128 v[198:201], v149 offset:50176
	ds_read_b128 v[202:205], v149 offset:51200
	ds_read_b128 v[206:209], v149 offset:52224
	ds_read_b128 v[210:213], v149 offset:53248
	ds_read_b128 v[214:217], v149 offset:54272
	ds_read_b128 v[218:221], v149 offset:55296
	ds_read_b128 v[242:245], v149 offset:56320
	global_load_lds_dwordx4 v[166:167], off
	s_add_i32 m0, s41, 0x2000
	s_add_u32 s52, s52, 0x40080
	v_lshl_add_u64 v[166:167], v[222:223], 0, s[28:29]
	s_addc_u32 s53, s53, 0
	s_add_i32 s41, s49, s58
	global_load_lds_dwordx4 v[166:167], off
	v_lshl_add_u64 v[166:167], s[52:53], 0, v[168:169]
	s_mov_b32 m0, s41
	s_nop 0
	global_load_lds_dwordx4 v[166:167], off
	v_lshl_add_u64 v[166:167], s[52:53], 0, v[132:133]
	s_add_i32 m0, s41, 0x2000
	s_nop 0
	global_load_lds_dwordx4 v[166:167], off
	v_lshl_add_u64 v[166:167], v[236:237], 0, s[28:29]
	s_mov_b32 m0, s67
	s_nop 0
	global_load_lds_dwordx4 v[166:167], off
	v_lshl_add_u64 v[166:167], v[246:247], 0, s[28:29]
	s_mov_b32 m0, s68
	s_nop 0
	global_load_lds_dwordx4 v[166:167], off
	s_waitcnt vmcnt(8)
	s_waitcnt lgkmcnt(0)
	s_barrier
	s_setprio 1
	s_waitcnt lgkmcnt(0)
	v_mfma_f32_16x16x32_bf16 v[60:63], v[138:141], v[194:197], v[60:63]
	v_mfma_f32_16x16x32_bf16 v[56:59], v[150:153], v[194:197], v[56:59]
	v_mfma_f32_16x16x32_bf16 v[44:47], v[138:141], v[202:205], v[44:47]
	v_mfma_f32_16x16x32_bf16 v[40:43], v[150:153], v[202:205], v[40:43]
	v_mfma_f32_16x16x32_bf16 v[28:31], v[138:141], v[210:213], v[28:31]
	v_mfma_f32_16x16x32_bf16 v[24:27], v[150:153], v[210:213], v[24:27]
	v_mfma_f32_16x16x32_bf16 v[12:15], v[138:141], v[218:221], v[12:15]
	v_mfma_f32_16x16x32_bf16 v[8:11], v[150:153], v[218:221], v[8:11]
	v_mfma_f32_16x16x32_bf16 v[60:63], v[142:145], v[198:201], v[60:63]
	v_mfma_f32_16x16x32_bf16 v[56:59], v[154:157], v[198:201], v[56:59]
	v_mfma_f32_16x16x32_bf16 v[44:47], v[142:145], v[206:209], v[44:47]
	v_mfma_f32_16x16x32_bf16 v[40:43], v[154:157], v[206:209], v[40:43]
	v_mfma_f32_16x16x32_bf16 v[28:31], v[142:145], v[214:217], v[28:31]
	v_mfma_f32_16x16x32_bf16 v[24:27], v[154:157], v[214:217], v[24:27]
	v_mfma_f32_16x16x32_bf16 v[12:15], v[142:145], v[242:245], v[12:15]
	v_mfma_f32_16x16x32_bf16 v[8:11], v[154:157], v[242:245], v[8:11]
	v_mfma_f32_16x16x32_bf16 v[52:55], v[158:161], v[194:197], v[52:55]
	v_mfma_f32_16x16x32_bf16 v[48:51], v[186:189], v[194:197], v[48:51]
	v_mfma_f32_16x16x32_bf16 v[36:39], v[158:161], v[202:205], v[36:39]
	v_mfma_f32_16x16x32_bf16 v[32:35], v[186:189], v[202:205], v[32:35]
	v_mfma_f32_16x16x32_bf16 v[20:23], v[158:161], v[210:213], v[20:23]
	v_mfma_f32_16x16x32_bf16 v[16:19], v[186:189], v[210:213], v[16:19]
	v_mfma_f32_16x16x32_bf16 v[4:7], v[158:161], v[218:221], v[4:7]
	v_mfma_f32_16x16x32_bf16 v[0:3], v[186:189], v[218:221], v[0:3]
	v_mfma_f32_16x16x32_bf16 v[52:55], v[162:165], v[198:201], v[52:55]
	v_mfma_f32_16x16x32_bf16 v[48:51], v[190:193], v[198:201], v[48:51]
	v_mfma_f32_16x16x32_bf16 v[36:39], v[162:165], v[206:209], v[36:39]
	v_mfma_f32_16x16x32_bf16 v[32:35], v[190:193], v[206:209], v[32:35]
	v_mfma_f32_16x16x32_bf16 v[20:23], v[162:165], v[214:217], v[20:23]
	v_mfma_f32_16x16x32_bf16 v[16:19], v[190:193], v[214:217], v[16:19]
	v_mfma_f32_16x16x32_bf16 v[4:7], v[162:165], v[242:245], v[4:7]
	v_mfma_f32_16x16x32_bf16 v[0:3], v[190:193], v[242:245], v[0:3]
	s_setprio 0
	s_barrier
	s_add_u32 s50, s50, 0x100
	s_addc_u32 s51, s51, 0
	s_add_u32 s1, s1, 0x100
	s_addc_u32 s3, s3, 0
	s_cmp_ge_i32 s43, s64
	s_mov_b32 s41, s43
	s_cbranch_scc0 .LBB0_980
	v_readlane_b32 s77, v254, 56

.LBB0_1032:
	s_add_i32 s69, s50, 2
	s_add_u32 s51, s48, 0xfffc0080
	s_addc_u32 s52, s49, -1
	s_add_i32 s70, 0, 0x10000
	s_cmp_eq_u32 s63, s50
	s_cselect_b32 s53, s1, s52
	s_cselect_b32 s52, s41, s51
	v_add_u32_e32 v142, s70, v146
	s_cselect_b32 s51, s43, s68
	s_cselect_b32 s50, s47, s67
	s_add_i32 s72, 0, 0x14000
	ds_read_b128 v[138:141], v142
	ds_read_b128 v[148:151], v142 offset:1024
	ds_read_b128 v[152:155], v142 offset:2048
	ds_read_b128 v[156:159], v142 offset:3072
	v_add_u32_e32 v142, s72, v146
	ds_read_b128 v[160:163], v142
	ds_read_b128 v[164:167], v142 offset:1024
	ds_read_b128 v[186:189], v142 offset:2048
	ds_read_b128 v[190:193], v142 offset:3072
	v_lshl_add_u64 v[142:143], s[48:49], 0, v[134:135]
	s_add_i32 m0, s54, 0xc000
	ds_read_b128 v[194:197], v147
	ds_read_b128 v[198:201], v147 offset:1024
	ds_read_b128 v[202:205], v147 offset:2048
	ds_read_b128 v[206:209], v147 offset:3072
	ds_read_b128 v[210:213], v147 offset:4096
	ds_read_b128 v[214:217], v147 offset:5120
	ds_read_b128 v[218:221], v147 offset:6144
	ds_read_b128 v[242:245], v147 offset:7168
	global_load_lds_dwordx4 v[142:143], off
	v_lshl_add_u64 v[142:143], s[48:49], 0, v[136:137]
	s_add_i32 m0, s54, 0xe000
	s_nop 0
	global_load_lds_dwordx4 v[142:143], off
	s_waitcnt vmcnt(8)
	s_waitcnt lgkmcnt(0)
	s_barrier
	s_setprio 1
	s_waitcnt lgkmcnt(0)
	v_mfma_f32_16x16x32_bf16 v[124:127], v[138:141], v[194:197], v[124:127]
	v_mfma_f32_16x16x32_bf16 v[120:123], v[152:155], v[194:197], v[120:123]
	v_mfma_f32_16x16x32_bf16 v[108:111], v[138:141], v[202:205], v[108:111]
	v_mfma_f32_16x16x32_bf16 v[104:107], v[152:155], v[202:205], v[104:107]
	v_mfma_f32_16x16x32_bf16 v[92:95], v[138:141], v[210:213], v[92:95]
	v_mfma_f32_16x16x32_bf16 v[88:91], v[152:155], v[210:213], v[88:91]
	v_mfma_f32_16x16x32_bf16 v[76:79], v[138:141], v[218:221], v[76:79]
	v_mfma_f32_16x16x32_bf16 v[72:75], v[152:155], v[218:221], v[72:75]
	v_mfma_f32_16x16x32_bf16 v[124:127], v[148:151], v[198:201], v[124:127]
	v_mfma_f32_16x16x32_bf16 v[120:123], v[156:159], v[198:201], v[120:123]
	v_mfma_f32_16x16x32_bf16 v[108:111], v[148:151], v[206:209], v[108:111]
	v_mfma_f32_16x16x32_bf16 v[104:107], v[156:159], v[206:209], v[104:107]
	v_mfma_f32_16x16x32_bf16 v[92:95], v[148:151], v[214:217], v[92:95]
	v_mfma_f32_16x16x32_bf16 v[88:91], v[156:159], v[214:217], v[88:91]
	v_mfma_f32_16x16x32_bf16 v[76:79], v[148:151], v[242:245], v[76:79]
	v_mfma_f32_16x16x32_bf16 v[72:75], v[156:159], v[242:245], v[72:75]
	v_mfma_f32_16x16x32_bf16 v[116:119], v[160:163], v[194:197], v[116:119]
	v_mfma_f32_16x16x32_bf16 v[112:115], v[186:189], v[194:197], v[112:115]
	v_mfma_f32_16x16x32_bf16 v[100:103], v[160:163], v[202:205], v[100:103]
	v_mfma_f32_16x16x32_bf16 v[96:99], v[186:189], v[202:205], v[96:99]
	v_mfma_f32_16x16x32_bf16 v[84:87], v[160:163], v[210:213], v[84:87]
	v_mfma_f32_16x16x32_bf16 v[80:83], v[186:189], v[210:213], v[80:83]
	v_mfma_f32_16x16x32_bf16 v[68:71], v[160:163], v[218:221], v[68:71]
	v_mfma_f32_16x16x32_bf16 v[64:67], v[186:189], v[218:221], v[64:67]
	v_mfma_f32_16x16x32_bf16 v[116:119], v[164:167], v[198:201], v[116:119]
	v_mfma_f32_16x16x32_bf16 v[112:115], v[190:193], v[198:201], v[112:115]
	v_mfma_f32_16x16x32_bf16 v[100:103], v[164:167], v[206:209], v[100:103]
	v_mfma_f32_16x16x32_bf16 v[96:99], v[190:193], v[206:209], v[96:99]
	v_mfma_f32_16x16x32_bf16 v[84:87], v[164:167], v[214:217], v[84:87]
	v_mfma_f32_16x16x32_bf16 v[80:83], v[190:193], v[214:217], v[80:83]
	v_mfma_f32_16x16x32_bf16 v[68:71], v[164:167], v[242:245], v[68:71]
	v_mfma_f32_16x16x32_bf16 v[64:67], v[190:193], v[242:245], v[64:67]
	s_setprio 0
	s_barrier
	s_add_i32 s70, s70, s34
	v_lshl_add_u64 v[142:143], s[50:51], 0, v[168:169]
	s_mov_b32 m0, s70
	ds_read_b128 v[194:197], v147 offset:16384
	ds_read_b128 v[198:201], v147 offset:17408
	ds_read_b128 v[202:205], v147 offset:18432
	ds_read_b128 v[206:209], v147 offset:19456
	ds_read_b128 v[210:213], v147 offset:20480
	ds_read_b128 v[214:217], v147 offset:21504
	ds_read_b128 v[218:221], v147 offset:22528
	ds_read_b128 v[242:245], v147 offset:23552
	global_load_lds_dwordx4 v[142:143], off
	s_add_i32 m0, s70, 0x2000
	s_add_u32 s70, s50, 0x40000
	v_lshl_add_u64 v[222:223], s[50:51], 0, v[132:133]
	s_addc_u32 s71, s51, 0
	s_add_i32 s72, s72, s34
	global_load_lds_dwordx4 v[222:223], off
	v_lshl_add_u64 v[236:237], s[70:71], 0, v[168:169]
	s_mov_b32 m0, s72
	v_lshl_add_u64 v[246:247], s[52:53], 0, v[130:131]
	global_load_lds_dwordx4 v[236:237], off
	v_lshl_add_u64 v[236:237], s[70:71], 0, v[132:133]
	s_add_i32 m0, s72, 0x2000
	s_nop 0
	global_load_lds_dwordx4 v[236:237], off
	v_lshl_add_u64 v[236:237], s[52:53], 0, v[128:129]
	s_mov_b32 m0, s54
	s_nop 0
	global_load_lds_dwordx4 v[236:237], off
	s_mov_b32 m0, s55
	s_nop 0
	global_load_lds_dwordx4 v[246:247], off
	s_waitcnt vmcnt(8)
	s_waitcnt lgkmcnt(0)
	s_barrier
	s_setprio 1
	s_waitcnt lgkmcnt(0)
	v_mfma_f32_16x16x32_bf16 v[60:63], v[138:141], v[194:197], v[60:63]
	v_mfma_f32_16x16x32_bf16 v[56:59], v[152:155], v[194:197], v[56:59]
	v_mfma_f32_16x16x32_bf16 v[44:47], v[138:141], v[202:205], v[44:47]
	v_mfma_f32_16x16x32_bf16 v[40:43], v[152:155], v[202:205], v[40:43]
	v_mfma_f32_16x16x32_bf16 v[28:31], v[138:141], v[210:213], v[28:31]
	v_mfma_f32_16x16x32_bf16 v[24:27], v[152:155], v[210:213], v[24:27]
	v_mfma_f32_16x16x32_bf16 v[12:15], v[138:141], v[218:221], v[12:15]
	v_mfma_f32_16x16x32_bf16 v[8:11], v[152:155], v[218:221], v[8:11]
	v_mfma_f32_16x16x32_bf16 v[60:63], v[148:151], v[198:201], v[60:63]
	v_mfma_f32_16x16x32_bf16 v[56:59], v[156:159], v[198:201], v[56:59]
	v_mfma_f32_16x16x32_bf16 v[44:47], v[148:151], v[206:209], v[44:47]
	v_mfma_f32_16x16x32_bf16 v[40:43], v[156:159], v[206:209], v[40:43]
	v_mfma_f32_16x16x32_bf16 v[28:31], v[148:151], v[214:217], v[28:31]
	v_mfma_f32_16x16x32_bf16 v[24:27], v[156:159], v[214:217], v[24:27]
	v_mfma_f32_16x16x32_bf16 v[12:15], v[148:151], v[242:245], v[12:15]
	v_mfma_f32_16x16x32_bf16 v[8:11], v[156:159], v[242:245], v[8:11]
	v_mfma_f32_16x16x32_bf16 v[52:55], v[160:163], v[194:197], v[52:55]
	v_mfma_f32_16x16x32_bf16 v[48:51], v[186:189], v[194:197], v[48:51]
	v_mfma_f32_16x16x32_bf16 v[36:39], v[160:163], v[202:205], v[36:39]
	v_mfma_f32_16x16x32_bf16 v[32:35], v[186:189], v[202:205], v[32:35]
	v_mfma_f32_16x16x32_bf16 v[20:23], v[160:163], v[210:213], v[20:23]
	v_mfma_f32_16x16x32_bf16 v[16:19], v[186:189], v[210:213], v[16:19]
	v_mfma_f32_16x16x32_bf16 v[4:7], v[160:163], v[218:221], v[4:7]
	v_mfma_f32_16x16x32_bf16 v[0:3], v[186:189], v[218:221], v[0:3]
	v_mfma_f32_16x16x32_bf16 v[52:55], v[164:167], v[198:201], v[52:55]
	v_mfma_f32_16x16x32_bf16 v[48:51], v[190:193], v[198:201], v[48:51]
	v_mfma_f32_16x16x32_bf16 v[36:39], v[164:167], v[206:209], v[36:39]
	v_mfma_f32_16x16x32_bf16 v[32:35], v[190:193], v[206:209], v[32:35]
	v_mfma_f32_16x16x32_bf16 v[20:23], v[164:167], v[214:217], v[20:23]
	v_mfma_f32_16x16x32_bf16 v[16:19], v[190:193], v[214:217], v[16:19]
	v_mfma_f32_16x16x32_bf16 v[4:7], v[164:167], v[242:245], v[4:7]
	v_mfma_f32_16x16x32_bf16 v[0:3], v[190:193], v[242:245], v[0:3]
	s_setprio 0
	s_barrier
	s_add_i32 s70, 0, 0x18000
	s_add_i32 s71, 0, 0x1c000
	v_add_u32_e32 v156, s70, v146
	v_add_u32_e32 v179, s71, v146
	ds_read_b128 v[138:141], v156
	ds_read_b128 v[148:151], v156 offset:1024
	ds_read_b128 v[152:155], v156 offset:2048
	ds_read_b128 v[156:159], v156 offset:3072
	ds_read_b128 v[160:163], v179
	ds_read_b128 v[164:167], v179 offset:1024
	ds_read_b128 v[186:189], v179 offset:2048
	ds_read_b128 v[190:193], v179 offset:3072
	s_add_u32 s52, s52, 0x40000
	s_addc_u32 s53, s53, 0
	s_mov_b32 m0, s56
	v_lshl_add_u64 v[248:249], s[52:53], 0, v[128:129]
	ds_read_b128 v[194:197], v147 offset:32768
	ds_read_b128 v[198:201], v147 offset:33792
	ds_read_b128 v[202:205], v147 offset:34816
	ds_read_b128 v[206:209], v147 offset:35840
	ds_read_b128 v[210:213], v147 offset:36864
	ds_read_b128 v[214:217], v147 offset:37888
	ds_read_b128 v[218:221], v147 offset:38912
	ds_read_b128 v[242:245], v147 offset:39936
	global_load_lds_dwordx4 v[248:249], off
	v_lshl_add_u64 v[248:249], s[52:53], 0, v[130:131]
	s_mov_b32 m0, s57
	s_nop 0
	global_load_lds_dwordx4 v[248:249], off
	s_waitcnt vmcnt(8)
	s_waitcnt lgkmcnt(0)
	s_barrier
	s_setprio 1
	s_waitcnt lgkmcnt(0)
	v_mfma_f32_16x16x32_bf16 v[124:127], v[138:141], v[194:197], v[124:127]
	v_mfma_f32_16x16x32_bf16 v[120:123], v[152:155], v[194:197], v[120:123]
	v_mfma_f32_16x16x32_bf16 v[108:111], v[138:141], v[202:205], v[108:111]
	v_mfma_f32_16x16x32_bf16 v[104:107], v[152:155], v[202:205], v[104:107]
	v_mfma_f32_16x16x32_bf16 v[92:95], v[138:141], v[210:213], v[92:95]
	v_mfma_f32_16x16x32_bf16 v[88:91], v[152:155], v[210:213], v[88:91]
	v_mfma_f32_16x16x32_bf16 v[76:79], v[138:141], v[218:221], v[76:79]
	v_mfma_f32_16x16x32_bf16 v[72:75], v[152:155], v[218:221], v[72:75]
	v_mfma_f32_16x16x32_bf16 v[124:127], v[148:151], v[198:201], v[124:127]
	v_mfma_f32_16x16x32_bf16 v[120:123], v[156:159], v[198:201], v[120:123]
	v_mfma_f32_16x16x32_bf16 v[108:111], v[148:151], v[206:209], v[108:111]
	v_mfma_f32_16x16x32_bf16 v[104:107], v[156:159], v[206:209], v[104:107]
	v_mfma_f32_16x16x32_bf16 v[92:95], v[148:151], v[214:217], v[92:95]
	v_mfma_f32_16x16x32_bf16 v[88:91], v[156:159], v[214:217], v[88:91]
	v_mfma_f32_16x16x32_bf16 v[76:79], v[148:151], v[242:245], v[76:79]
	v_mfma_f32_16x16x32_bf16 v[72:75], v[156:159], v[242:245], v[72:75]
	v_mfma_f32_16x16x32_bf16 v[116:119], v[160:163], v[194:197], v[116:119]
	v_mfma_f32_16x16x32_bf16 v[112:115], v[186:189], v[194:197], v[112:115]
	v_mfma_f32_16x16x32_bf16 v[100:103], v[160:163], v[202:205], v[100:103]
	v_mfma_f32_16x16x32_bf16 v[96:99], v[186:189], v[202:205], v[96:99]
	v_mfma_f32_16x16x32_bf16 v[84:87], v[160:163], v[210:213], v[84:87]
	v_mfma_f32_16x16x32_bf16 v[80:83], v[186:189], v[210:213], v[80:83]
	v_mfma_f32_16x16x32_bf16 v[68:71], v[160:163], v[218:221], v[68:71]
	v_mfma_f32_16x16x32_bf16 v[64:67], v[186:189], v[218:221], v[64:67]
	v_mfma_f32_16x16x32_bf16 v[116:119], v[164:167], v[198:201], v[116:119]
	v_mfma_f32_16x16x32_bf16 v[112:115], v[190:193], v[198:201], v[112:115]
	v_mfma_f32_16x16x32_bf16 v[100:103], v[164:167], v[206:209], v[100:103]
	v_mfma_f32_16x16x32_bf16 v[96:99], v[190:193], v[206:209], v[96:99]
	v_mfma_f32_16x16x32_bf16 v[84:87], v[164:167], v[214:217], v[84:87]
	v_mfma_f32_16x16x32_bf16 v[80:83], v[190:193], v[214:217], v[80:83]
	v_mfma_f32_16x16x32_bf16 v[68:71], v[164:167], v[242:245], v[68:71]
	v_mfma_f32_16x16x32_bf16 v[64:67], v[190:193], v[242:245], v[64:67]
	s_setprio 0
	s_barrier
	s_add_i32 s52, s70, s34
	v_lshl_add_u64 v[142:143], v[142:143], 0, s[28:29]
	s_mov_b32 m0, s52
	ds_read_b128 v[194:197], v147 offset:49152
	ds_read_b128 v[198:201], v147 offset:50176
	ds_read_b128 v[202:205], v147 offset:51200
	ds_read_b128 v[206:209], v147 offset:52224
	ds_read_b128 v[210:213], v147 offset:53248
	ds_read_b128 v[214:217], v147 offset:54272
	ds_read_b128 v[218:221], v147 offset:55296
	ds_read_b128 v[242:245], v147 offset:56320
	global_load_lds_dwordx4 v[142:143], off
	s_add_i32 m0, s52, 0x2000
	s_add_u32 s50, s50, 0x40080
	v_lshl_add_u64 v[142:143], v[222:223], 0, s[28:29]
	s_addc_u32 s51, s51, 0
	s_add_i32 s52, s71, s34
	global_load_lds_dwordx4 v[142:143], off
	v_lshl_add_u64 v[142:143], s[50:51], 0, v[168:169]
	s_mov_b32 m0, s52
	s_nop 0
	global_load_lds_dwordx4 v[142:143], off
	v_lshl_add_u64 v[142:143], s[50:51], 0, v[132:133]
	s_add_i32 m0, s52, 0x2000
	s_nop 0
	global_load_lds_dwordx4 v[142:143], off
	v_lshl_add_u64 v[142:143], v[236:237], 0, s[28:29]
	s_mov_b32 m0, s61
	s_nop 0
	global_load_lds_dwordx4 v[142:143], off
	v_lshl_add_u64 v[142:143], v[246:247], 0, s[28:29]
	s_mov_b32 m0, s62
	s_nop 0
	global_load_lds_dwordx4 v[142:143], off
	s_waitcnt vmcnt(8)
	s_waitcnt lgkmcnt(0)
	s_barrier
	s_setprio 1
	s_waitcnt lgkmcnt(0)
	v_mfma_f32_16x16x32_bf16 v[60:63], v[138:141], v[194:197], v[60:63]
	v_mfma_f32_16x16x32_bf16 v[56:59], v[152:155], v[194:197], v[56:59]
	v_mfma_f32_16x16x32_bf16 v[44:47], v[138:141], v[202:205], v[44:47]
	v_mfma_f32_16x16x32_bf16 v[40:43], v[152:155], v[202:205], v[40:43]
	v_mfma_f32_16x16x32_bf16 v[28:31], v[138:141], v[210:213], v[28:31]
	v_mfma_f32_16x16x32_bf16 v[24:27], v[152:155], v[210:213], v[24:27]
	v_mfma_f32_16x16x32_bf16 v[12:15], v[138:141], v[218:221], v[12:15]
	v_mfma_f32_16x16x32_bf16 v[8:11], v[152:155], v[218:221], v[8:11]
	v_mfma_f32_16x16x32_bf16 v[60:63], v[148:151], v[198:201], v[60:63]
	v_mfma_f32_16x16x32_bf16 v[56:59], v[156:159], v[198:201], v[56:59]
	v_mfma_f32_16x16x32_bf16 v[44:47], v[148:151], v[206:209], v[44:47]
	v_mfma_f32_16x16x32_bf16 v[40:43], v[156:159], v[206:209], v[40:43]
	v_mfma_f32_16x16x32_bf16 v[28:31], v[148:151], v[214:217], v[28:31]
	v_mfma_f32_16x16x32_bf16 v[24:27], v[156:159], v[214:217], v[24:27]
	v_mfma_f32_16x16x32_bf16 v[12:15], v[148:151], v[242:245], v[12:15]
	v_mfma_f32_16x16x32_bf16 v[8:11], v[156:159], v[242:245], v[8:11]
	v_mfma_f32_16x16x32_bf16 v[52:55], v[160:163], v[194:197], v[52:55]
	v_mfma_f32_16x16x32_bf16 v[48:51], v[186:189], v[194:197], v[48:51]
	v_mfma_f32_16x16x32_bf16 v[36:39], v[160:163], v[202:205], v[36:39]
	v_mfma_f32_16x16x32_bf16 v[32:35], v[186:189], v[202:205], v[32:35]
	v_mfma_f32_16x16x32_bf16 v[20:23], v[160:163], v[210:213], v[20:23]
	v_mfma_f32_16x16x32_bf16 v[16:19], v[186:189], v[210:213], v[16:19]
	v_mfma_f32_16x16x32_bf16 v[4:7], v[160:163], v[218:221], v[4:7]
	v_mfma_f32_16x16x32_bf16 v[0:3], v[186:189], v[218:221], v[0:3]
	v_mfma_f32_16x16x32_bf16 v[52:55], v[164:167], v[198:201], v[52:55]
	v_mfma_f32_16x16x32_bf16 v[48:51], v[190:193], v[198:201], v[48:51]
	v_mfma_f32_16x16x32_bf16 v[36:39], v[164:167], v[206:209], v[36:39]
	v_mfma_f32_16x16x32_bf16 v[32:35], v[190:193], v[206:209], v[32:35]
	v_mfma_f32_16x16x32_bf16 v[20:23], v[164:167], v[214:217], v[20:23]
	v_mfma_f32_16x16x32_bf16 v[16:19], v[190:193], v[214:217], v[16:19]
	v_mfma_f32_16x16x32_bf16 v[4:7], v[164:167], v[242:245], v[4:7]
	v_mfma_f32_16x16x32_bf16 v[0:3], v[190:193], v[242:245], v[0:3]
	s_setprio 0
	s_barrier
	s_add_u32 s48, s48, 0x100
	s_addc_u32 s49, s49, 0
	s_add_u32 s67, s67, 0x100
	s_addc_u32 s68, s68, 0
	s_cmp_ge_i32 s69, s58
	s_mov_b32 s50, s69
	s_cbranch_scc0 .LBB0_1032
